# speedup vs baseline: 1.0048x; 1.0048x over previous
; DEVINL u16 f2bf(float f) { uint32_t u = __float_as_uint(f); u += 0x7FFFu + ((u >> 16) & 1u); return (u16)(u >> 16); }
; DEVINL float bfs2f(short h) { return __uint_as_float(((uint32_t)(u16)h) << 16); }
; DEVINL void phase_conv(const Params& p, int layer, int wv) {
;     ...
; #pragma unroll 8
;       for (int i = 0; i < 32; ++i) {
;         const bf16x8 r3 = *(const bf16x8*)(src + (size_t)i * HS);
;         bf16x8 o;
; #pragma unroll
;         for (int e = 0; e < 8; ++e) {
;           float v = bias[e] + w[0][e] * bfs2f(r0[e]) + w[1][e] * bfs2f(r1[e]) + w[2][e] * bfs2f(r2[e]) + w[3][e] * bfs2f(r3[e]);
;           v = v / (1.f + __expf(-v));
;           o[e] = (short)f2bf(v);
;         }
;         *(bf16x8*)(xc + (size_t)(tokA + i) * 1536 + ch0) = o;
;         r0 = r1; r1 = r2; r2 = r3;
.LBB0_454:
	v_add_co_u32_e32 v62, vcc, 0xfffef000, v42
	s_waitcnt vmcnt(0)
	v_and_b32_e32 v75, 0xffff0000, v46
	v_addc_co_u32_e32 v63, vcc, -1, v43, vcc
	global_load_dwordx4 v[90:93], v[62:63], off offset:-2048
	v_lshlrev_b32_e32 v74, 16, v46
	v_add_co_u32_e64 v46, s[0:1], s31, v42
	v_and_b32_e32 v81, 0xffff0000, v47
	v_lshlrev_b32_e32 v80, 16, v47
	v_addc_co_u32_e64 v47, s[0:1], -1, v43, s[0:1]
	v_and_b32_e32 v69, 0xffff0000, v44
	v_lshlrev_b32_e32 v68, 16, v44
	v_and_b32_e32 v65, 0xffff0000, v52
	v_lshlrev_b32_e32 v64, 16, v52
	v_and_b32_e32 v73, 0xffff0000, v45
	v_lshlrev_b32_e32 v72, 16, v45
	v_and_b32_e32 v45, 0xffff0000, v53
	v_lshlrev_b32_e32 v44, 16, v53
	v_and_b32_e32 v53, 0xffff0000, v50
	v_lshlrev_b32_e32 v52, 16, v50
	v_add_co_u32_e64 v50, s[0:1], s33, v42
	v_and_b32_e32 v79, 0xffff0000, v51
	v_lshlrev_b32_e32 v78, 16, v51
	v_addc_co_u32_e64 v51, s[0:1], -1, v43, s[0:1]
	v_and_b32_e32 v67, 0xffff0000, v48
	v_lshlrev_b32_e32 v66, 16, v48
	v_and_b32_e32 v71, 0xffff0000, v49
	v_lshlrev_b32_e32 v70, 16, v49
	v_and_b32_e32 v49, 0xffff0000, v54
	v_lshlrev_b32_e32 v48, 16, v54
	v_add_co_u32_e64 v54, s[0:1], s34, v42
	v_and_b32_e32 v77, 0xffff0000, v55
	v_lshlrev_b32_e32 v76, 16, v55
	v_addc_co_u32_e64 v55, s[0:1], -1, v43, s[0:1]
	v_add_co_u32_e64 v82, s[0:1], s25, v42
	v_pk_fma_f32 v[68:69], v[4:5], v[68:69], v[36:37]
	s_nop 0
	v_addc_co_u32_e64 v83, s[0:1], -1, v43, s[0:1]
	v_add_co_u32_e64 v84, s[0:1], s26, v42
	v_pk_fma_f32 v[80:81], v[2:3], v[80:81], v[34:35]
	s_nop 0
	v_addc_co_u32_e64 v85, s[0:1], -1, v43, s[0:1]
	v_pk_fma_f32 v[96:97], v[4:5], v[66:67], v[36:37]
	v_pk_fma_f32 v[98:99], v[6:7], v[70:71], v[38:39]
	v_pk_fma_f32 v[100:101], v[0:1], v[52:53], v[32:33]
	v_pk_fma_f32 v[102:103], v[2:3], v[78:79], v[34:35]
	v_pk_fma_f32 v[112:113], v[8:9], v[66:67], v[68:69]
	v_pk_fma_f32 v[78:79], v[18:19], v[78:79], v[80:81]
	v_add_u32_e32 v41, s36, v89
	v_add_co_u32_e64 v86, s[0:1], s27, v42
	v_pk_fma_f32 v[72:73], v[6:7], v[72:73], v[38:39]
	v_pk_fma_f32 v[104:105], v[4:5], v[64:65], v[36:37]
	v_pk_fma_f32 v[110:111], v[2:3], v[76:77], v[34:35]
	v_pk_fma_f32 v[80:81], v[8:9], v[64:65], v[96:97]
	v_pk_fma_f32 v[96:97], v[10:11], v[44:45], v[98:99]
	v_pk_fma_f32 v[98:99], v[16:17], v[48:49], v[100:101]
	v_pk_fma_f32 v[100:101], v[18:19], v[76:77], v[102:103]
	v_pk_fma_f32 v[64:65], v[12:13], v[64:65], v[112:113]
	v_pk_fma_f32 v[76:77], v[22:23], v[76:77], v[78:79]
	v_addc_co_u32_e64 v87, s[0:1], -1, v43, s[0:1]
	v_mad_i64_i32 v[94:95], s[0:1], v41, s30, v[58:59]
	v_add_u32_e32 v118, 1, v41
	v_add_u32_e32 v119, 2, v41
	v_add_u32_e32 v120, 3, v41
	v_add_u32_e32 v121, 4, v41
	v_add_u32_e32 v122, 5, v41
	v_add_u32_e32 v123, 6, v41
	v_add_u32_e32 v41, 7, v41
	v_pk_fma_f32 v[114:115], v[10:11], v[70:71], v[72:73]
	v_pk_fma_f32 v[74:75], v[0:1], v[74:75], v[32:33]
	v_pk_fma_f32 v[106:107], v[6:7], v[44:45], v[38:39]
	v_mad_i64_i32 v[62:63], s[0:1], v41, s30, v[58:59]
	s_waitcnt vmcnt(0)
	v_and_b32_e32 v79, 0xffff0000, v90
	v_lshlrev_b32_e32 v78, 16, v90
	v_and_b32_e32 v113, 0xffff0000, v93
	v_lshlrev_b32_e32 v112, 16, v93
	v_pk_fma_f32 v[64:65], v[24:25], v[78:79], v[64:65]
	v_pk_fma_f32 v[44:45], v[14:15], v[44:45], v[114:115]
	v_and_b32_e32 v103, 0xffff0000, v91
	v_lshlrev_b32_e32 v102, 16, v91
	v_and_b32_e32 v91, 0xffff0000, v92
	v_lshlrev_b32_e32 v90, 16, v92
	v_pk_fma_f32 v[92:93], v[30:31], v[112:113], v[76:77]
	v_mul_f32_e32 v41, 0xbfb8aa3b, v64
	v_mul_f32_e32 v77, 0xbfb8aa3b, v65
	v_pk_fma_f32 v[116:117], v[16:17], v[52:53], v[74:75]
	v_pk_fma_f32 v[44:45], v[26:27], v[102:103], v[44:45]
	v_exp_f32_e32 v76, v41
	v_exp_f32_e32 v77, v77
	v_pk_fma_f32 v[108:109], v[0:1], v[48:49], v[32:33]
	v_pk_fma_f32 v[48:49], v[20:21], v[48:49], v[116:117]
	v_pk_fma_f32 v[80:81], v[12:13], v[78:79], v[80:81]
	v_pk_fma_f32 v[104:105], v[8:9], v[78:79], v[104:105]
	v_pk_fma_f32 v[114:115], v[4:5], v[78:79], v[36:37]
	v_mul_f32_e32 v78, 0xbfb8aa3b, v44
	v_mul_f32_e32 v79, 0xbfb8aa3b, v45
	v_pk_fma_f32 v[48:49], v[28:29], v[90:91], v[48:49]
	v_exp_f32_e32 v78, v78
	v_exp_f32_e32 v79, v79
	v_mul_f32_e32 v116, 0xbfb8aa3b, v48
	v_mul_f32_e32 v117, 0xbfb8aa3b, v49
	v_exp_f32_e32 v116, v116
	v_exp_f32_e32 v117, v117
	v_pk_add_f32 v[76:77], v[76:77], 1.0 op_sel_hi:[1,0]
	v_mad_i64_i32 v[74:75], s[0:1], v118, s30, v[58:59]
	v_mad_i64_i32 v[72:73], s[0:1], v119, s30, v[58:59]
	v_mul_f32_e32 v118, 0xbfb8aa3b, v92
	v_mul_f32_e32 v119, 0xbfb8aa3b, v93
	v_mad_i64_i32 v[68:69], s[0:1], v121, s30, v[58:59]
	v_exp_f32_e32 v118, v118
	v_exp_f32_e32 v119, v119
	v_pk_add_f32 v[78:79], v[78:79], 1.0 op_sel_hi:[1,0]
	v_rcp_f32_e32 v135, v76
	v_mad_i64_i32 v[52:53], s[0:1], v123, s30, v[58:59]
	v_rcp_f32_e32 v136, v77
	v_pk_add_f32 v[116:117], v[116:117], 1.0 op_sel_hi:[1,0]
	v_rcp_f32_e32 v137, v78
	v_rcp_f32_e32 v138, v79
	v_pk_add_f32 v[118:119], v[118:119], 1.0 op_sel_hi:[1,0]
	v_rcp_f32_e32 v139, v116
	v_mad_i64_i32 v[70:71], s[0:1], v120, s30, v[58:59]
	v_mad_i64_i32 v[66:67], s[0:1], v122, s30, v[58:59]
	v_rcp_f32_e32 v140, v117
	v_rcp_f32_e32 v141, v118
	v_rcp_f32_e32 v142, v119
	v_mul_f32_e32 v41, v64, v135
	s_mov_b64 vcc, s[0:1]
	v_mul_f32_e32 v64, v65, v136
	s_mov_b64 vcc, s[2:3]
	v_mul_f32_e32 v65, v44, v137
	s_mov_b64 vcc, s[4:5]
	v_mov_b32_e32 v44, v65
	v_mul_f32_e32 v65, v45, v138
	s_mov_b64 vcc, s[6:7]
	v_bfe_u32 v76, v41, 16, 1
	v_bfe_u32 v77, v64, 16, 1
	v_mov_b32_e32 v45, v65
	v_mul_f32_e32 v65, v48, v139
	s_mov_b64 vcc, s[8:9]
	v_add3_u32 v41, v41, v76, s28
	v_bfe_u32 v76, v44, 16, 1
	v_add3_u32 v64, v64, v77, s28
	v_mov_b32_e32 v48, v65
	v_mul_f32_e32 v65, v49, v140
	s_mov_b64 vcc, s[10:11]
	v_bfe_u32 v77, v45, 16, 1
	v_add3_u32 v44, v44, v76, s28
	v_perm_b32 v76, v64, v41, s29
	v_mov_b32_e32 v41, v65
	v_mul_f32_e32 v49, v92, v141
	s_mov_b64 vcc, s[12:13]
	v_add3_u32 v45, v45, v77, s28
	v_mul_f32_e32 v65, v93, v142
	v_bfe_u32 v64, v48, 16, 1
	v_bfe_u32 v78, v41, 16, 1
	v_perm_b32 v77, v45, v44, s29
	v_mov_b32_e32 v44, v65
	v_add3_u32 v48, v48, v64, s28
	v_bfe_u32 v45, v49, 16, 1
	v_add3_u32 v41, v41, v78, s28
	v_bfe_u32 v64, v44, 16, 1
	v_add3_u32 v45, v49, v45, s28
	v_perm_b32 v78, v41, v48, s29
	v_add3_u32 v41, v44, v64, s28
	v_perm_b32 v79, v41, v45, s29
	global_store_dwordx4 v[94:95], v[76:79], off
	global_load_dwordx4 v[44:47], v[46:47], off
	v_pk_fma_f32 v[98:99], v[20:21], v[90:91], v[98:99]
	v_pk_fma_f32 v[108:109], v[16:17], v[90:91], v[108:109]
	v_pk_fma_f32 v[90:91], v[0:1], v[90:91], v[32:33]
	v_pk_fma_f32 v[96:97], v[14:15], v[102:103], v[96:97]
	v_pk_fma_f32 v[100:101], v[22:23], v[112:113], v[100:101]
	v_pk_fma_f32 v[110:111], v[18:19], v[112:113], v[110:111]
	v_pk_fma_f32 v[106:107], v[10:11], v[102:103], v[106:107]
	v_pk_fma_f32 v[112:113], v[2:3], v[112:113], v[34:35]
	v_pk_fma_f32 v[102:103], v[6:7], v[102:103], v[38:39]
	s_add_i32 s36, s36, 8
	s_cmp_eq_u32 s36, 32
	s_waitcnt vmcnt(0)
; DEVINL u16 f2bf(float f) { uint32_t u = __float_as_uint(f); u += 0x7FFFu + ((u >> 16) & 1u); return (u16)(u >> 16); }
; DEVINL float bfs2f(short h) { return __uint_as_float(((uint32_t)(u16)h) << 16); }
; DEVINL void phase_conv(const Params& p, int layer, int wv) {
;     ...
; #pragma unroll 8
;       for (int i = 0; i < 32; ++i) {
;         const bf16x8 r3 = *(const bf16x8*)(src + (size_t)i * HS);
;         bf16x8 o;
; #pragma unroll
;         for (int e = 0; e < 8; ++e) {
;           float v = bias[e] + w[0][e] * bfs2f(r0[e]) + w[1][e] * bfs2f(r1[e]) + w[2][e] * bfs2f(r2[e]) + w[3][e] * bfs2f(r3[e]);
;           v = v / (1.f + __expf(-v));
;           o[e] = (short)f2bf(v);
;         }
;         *(bf16x8*)(xc + (size_t)(tokA + i) * 1536 + ch0) = o;
;         r0 = r1; r1 = r2; r2 = r3;
	v_and_b32_e32 v49, 0xffff0000, v44
	v_lshlrev_b32_e32 v48, 16, v44
	v_and_b32_e32 v65, 0xffff0000, v45
	v_lshlrev_b32_e32 v64, 16, v45
	v_and_b32_e32 v45, 0xffff0000, v46
	v_lshlrev_b32_e32 v44, 16, v46
	v_and_b32_e32 v77, 0xffff0000, v47
	v_lshlrev_b32_e32 v76, 16, v47
	v_pk_fma_f32 v[46:47], v[24:25], v[48:49], v[80:81]
	v_pk_fma_f32 v[80:81], v[28:29], v[44:45], v[98:99]
	v_pk_fma_f32 v[98:99], v[20:21], v[44:45], v[108:109]
	v_pk_fma_f32 v[90:91], v[16:17], v[44:45], v[90:91]
	v_pk_fma_f32 v[108:109], v[0:1], v[44:45], v[32:33]
	v_mul_f32_e32 v41, 0xbfb8aa3b, v46
	v_mul_f32_e32 v45, 0xbfb8aa3b, v47
	v_pk_fma_f32 v[78:79], v[26:27], v[64:65], v[96:97]
	v_exp_f32_e32 v44, v41
	v_exp_f32_e32 v45, v45
	v_pk_fma_f32 v[92:93], v[30:31], v[76:77], v[100:101]
	v_pk_fma_f32 v[100:101], v[22:23], v[76:77], v[110:111]
	v_mul_f32_e32 v110, 0xbfb8aa3b, v78
	v_mul_f32_e32 v111, 0xbfb8aa3b, v79
	v_exp_f32_e32 v110, v110
	v_exp_f32_e32 v111, v111
	v_pk_fma_f32 v[96:97], v[14:15], v[64:65], v[106:107]
	v_pk_fma_f32 v[106:107], v[18:19], v[76:77], v[112:113]
	v_mul_f32_e32 v112, 0xbfb8aa3b, v80
	v_mul_f32_e32 v113, 0xbfb8aa3b, v81
	v_exp_f32_e32 v112, v112
	v_exp_f32_e32 v113, v113
	v_pk_add_f32 v[44:45], v[44:45], 1.0 op_sel_hi:[1,0]
	v_pk_fma_f32 v[94:95], v[12:13], v[48:49], v[104:105]
	v_pk_fma_f32 v[104:105], v[8:9], v[48:49], v[114:115]
	v_mul_f32_e32 v114, 0xbfb8aa3b, v92
	v_mul_f32_e32 v115, 0xbfb8aa3b, v93
	v_exp_f32_e32 v114, v114
	v_exp_f32_e32 v115, v115
	v_pk_add_f32 v[110:111], v[110:111], 1.0 op_sel_hi:[1,0]
	v_rcp_f32_e32 v131, v44
	v_rcp_f32_e32 v132, v45
	v_pk_add_f32 v[112:113], v[112:113], 1.0 op_sel_hi:[1,0]
	v_rcp_f32_e32 v133, v110
	v_rcp_f32_e32 v134, v111
	v_pk_add_f32 v[114:115], v[114:115], 1.0 op_sel_hi:[1,0]
	v_rcp_f32_e32 v135, v112
	v_rcp_f32_e32 v136, v113
	v_rcp_f32_e32 v137, v114
	v_rcp_f32_e32 v138, v115
	v_mul_f32_e32 v41, v46, v131
	s_mov_b64 vcc, s[0:1]
	v_mul_f32_e32 v44, v47, v132
	s_mov_b64 vcc, s[2:3]
	v_mul_f32_e32 v45, v78, v133
	s_mov_b64 vcc, s[4:5]
	v_bfe_u32 v46, v41, 16, 1
	v_mul_f32_e32 v47, v79, v134
	s_mov_b64 vcc, s[6:7]
	v_bfe_u32 v78, v44, 16, 1
	v_add3_u32 v41, v41, v46, s28
	v_mov_b32_e32 v46, v47
	v_mul_f32_e32 v47, v80, v135
	s_mov_b64 vcc, s[8:9]
	v_add3_u32 v44, v44, v78, s28
	v_mul_f32_e32 v78, v81, v136
	s_mov_b64 vcc, s[10:11]
	v_bfe_u32 v79, v45, 16, 1
	v_bfe_u32 v80, v46, 16, 1
	v_perm_b32 v44, v44, v41, s29
	v_mov_b32_e32 v41, v78
	v_mul_f32_e32 v78, v92, v137
	s_mov_b64 vcc, s[12:13]
	v_add3_u32 v45, v45, v79, s28
	v_bfe_u32 v79, v47, 16, 1
	v_add3_u32 v46, v46, v80, s28
	v_mul_f32_e32 v80, v93, v138
	v_bfe_u32 v81, v41, 16, 1
	v_add3_u32 v47, v47, v79, s28
	v_mov_b32_e32 v79, v80
	v_perm_b32 v45, v46, v45, s29
	v_bfe_u32 v46, v78, 16, 1
	v_add3_u32 v41, v41, v81, s28
	v_bfe_u32 v80, v79, 16, 1
	v_add3_u32 v78, v78, v46, s28
	v_perm_b32 v46, v41, v47, s29
	v_add3_u32 v41, v79, v80, s28
	v_perm_b32 v47, v41, v78, s29
	global_store_dwordx4 v[74:75], v[44:47], off
	global_load_dwordx4 v[44:47], v[50:51], off offset:-2048
	v_pk_fma_f32 v[102:103], v[10:11], v[64:65], v[102:103]
	v_pk_fma_f32 v[48:49], v[4:5], v[48:49], v[36:37]
	v_pk_fma_f32 v[64:65], v[6:7], v[64:65], v[38:39]
	v_pk_fma_f32 v[76:77], v[2:3], v[76:77], v[34:35]
	s_waitcnt vmcnt(0)
	v_and_b32_e32 v51, 0xffff0000, v44
	v_lshlrev_b32_e32 v50, 16, v44
	v_and_b32_e32 v75, 0xffff0000, v45
	v_lshlrev_b32_e32 v74, 16, v45
	v_and_b32_e32 v45, 0xffff0000, v46
	v_lshlrev_b32_e32 v44, 16, v46
	v_and_b32_e32 v79, 0xffff0000, v47
	v_lshlrev_b32_e32 v78, 16, v47
	v_pk_fma_f32 v[46:47], v[24:25], v[50:51], v[94:95]
	v_pk_fma_f32 v[80:81], v[26:27], v[74:75], v[96:97]
	v_pk_fma_f32 v[92:93], v[28:29], v[44:45], v[98:99]
	v_pk_fma_f32 v[96:97], v[12:13], v[50:51], v[104:105]
	v_pk_fma_f32 v[98:99], v[14:15], v[74:75], v[102:103]
	v_pk_fma_f32 v[90:91], v[20:21], v[44:45], v[90:91]
	v_pk_fma_f32 v[102:103], v[16:17], v[44:45], v[108:109]
	v_pk_fma_f32 v[104:105], v[0:1], v[44:45], v[32:33]
	v_mul_f32_e32 v41, 0xbfb8aa3b, v46
	v_mul_f32_e32 v45, 0xbfb8aa3b, v47
	v_exp_f32_e32 v44, v41
	v_exp_f32_e32 v45, v45
	v_pk_fma_f32 v[94:95], v[30:31], v[78:79], v[100:101]
	v_pk_fma_f32 v[100:101], v[22:23], v[78:79], v[106:107]
	v_mul_f32_e32 v106, 0xbfb8aa3b, v80
	v_mul_f32_e32 v107, 0xbfb8aa3b, v81
	v_exp_f32_e32 v106, v106
	v_exp_f32_e32 v107, v107
	v_mul_f32_e32 v108, 0xbfb8aa3b, v92
	v_mul_f32_e32 v109, 0xbfb8aa3b, v93
	v_exp_f32_e32 v108, v108
	v_exp_f32_e32 v109, v109
	v_pk_add_f32 v[44:45], v[44:45], 1.0 op_sel_hi:[1,0]
	v_mul_f32_e32 v110, 0xbfb8aa3b, v94
	v_mul_f32_e32 v111, 0xbfb8aa3b, v95
	v_exp_f32_e32 v110, v110
	v_exp_f32_e32 v111, v111
	v_pk_add_f32 v[106:107], v[106:107], 1.0 op_sel_hi:[1,0]
	v_rcp_f32_e32 v127, v44
	v_rcp_f32_e32 v128, v45
	v_pk_add_f32 v[108:109], v[108:109], 1.0 op_sel_hi:[1,0]
	v_rcp_f32_e32 v129, v106
	v_rcp_f32_e32 v130, v107
	v_pk_add_f32 v[110:111], v[110:111], 1.0 op_sel_hi:[1,0]
	v_rcp_f32_e32 v131, v108
	v_rcp_f32_e32 v132, v109
	v_rcp_f32_e32 v133, v110
	v_rcp_f32_e32 v134, v111
	v_mul_f32_e32 v41, v46, v127
	s_mov_b64 vcc, s[0:1]
	v_mul_f32_e32 v44, v47, v128
	s_mov_b64 vcc, s[2:3]
	v_mul_f32_e32 v45, v80, v129
	s_mov_b64 vcc, s[4:5]
	v_bfe_u32 v46, v41, 16, 1
	v_mul_f32_e32 v47, v81, v130
	s_mov_b64 vcc, s[6:7]
	v_bfe_u32 v80, v44, 16, 1
	v_add3_u32 v41, v41, v46, s28
	v_mov_b32_e32 v46, v47
	v_mul_f32_e32 v47, v92, v131
	s_mov_b64 vcc, s[8:9]
	v_add3_u32 v44, v44, v80, s28
	v_mul_f32_e32 v80, v93, v132
	s_mov_b64 vcc, s[10:11]
	v_bfe_u32 v81, v45, 16, 1
	v_bfe_u32 v92, v46, 16, 1
	v_perm_b32 v44, v44, v41, s29
	v_mov_b32_e32 v41, v80
	v_mul_f32_e32 v80, v94, v133
	s_mov_b64 vcc, s[12:13]
	v_add3_u32 v45, v45, v81, s28
	v_bfe_u32 v81, v47, 16, 1
	v_add3_u32 v46, v46, v92, s28
	v_mul_f32_e32 v92, v95, v134
	v_bfe_u32 v93, v41, 16, 1
	v_add3_u32 v47, v47, v81, s28
	v_mov_b32_e32 v81, v92
	v_perm_b32 v45, v46, v45, s29
	v_bfe_u32 v46, v80, 16, 1
	v_add3_u32 v41, v41, v93, s28
	v_bfe_u32 v92, v81, 16, 1
	v_add3_u32 v80, v80, v46, s28
	v_perm_b32 v46, v41, v47, s29
	v_add3_u32 v41, v81, v92, s28
	v_perm_b32 v47, v41, v80, s29
	global_store_dwordx4 v[72:73], v[44:47], off
	global_load_dwordx4 v[44:47], v[54:55], off
	v_pk_fma_f32 v[48:49], v[8:9], v[50:51], v[48:49]
	v_pk_fma_f32 v[64:65], v[10:11], v[74:75], v[64:65]
	v_pk_fma_f32 v[76:77], v[18:19], v[78:79], v[76:77]
	v_pk_fma_f32 v[50:51], v[4:5], v[50:51], v[36:37]
	v_pk_fma_f32 v[74:75], v[6:7], v[74:75], v[38:39]
	v_pk_fma_f32 v[78:79], v[2:3], v[78:79], v[34:35]
	s_waitcnt vmcnt(0)
; DEVINL u16 f2bf(float f) { uint32_t u = __float_as_uint(f); u += 0x7FFFu + ((u >> 16) & 1u); return (u16)(u >> 16); }
; DEVINL float bfs2f(short h) { return __uint_as_float(((uint32_t)(u16)h) << 16); }
; DEVINL void phase_conv(const Params& p, int layer, int wv) {
;     ...
; #pragma unroll 8
;       for (int i = 0; i < 32; ++i) {
;         const bf16x8 r3 = *(const bf16x8*)(src + (size_t)i * HS);
;         bf16x8 o;
; #pragma unroll
;         for (int e = 0; e < 8; ++e) {
;           float v = bias[e] + w[0][e] * bfs2f(r0[e]) + w[1][e] * bfs2f(r1[e]) + w[2][e] * bfs2f(r2[e]) + w[3][e] * bfs2f(r3[e]);
;           v = v / (1.f + __expf(-v));
;           o[e] = (short)f2bf(v);
;         }
;         *(bf16x8*)(xc + (size_t)(tokA + i) * 1536 + ch0) = o;
;         r0 = r1; r1 = r2; r2 = r3;
	v_and_b32_e32 v55, 0xffff0000, v44
	v_lshlrev_b32_e32 v54, 16, v44
	v_and_b32_e32 v73, 0xffff0000, v45
	v_lshlrev_b32_e32 v72, 16, v45
	v_and_b32_e32 v45, 0xffff0000, v46
	v_lshlrev_b32_e32 v44, 16, v46
	v_and_b32_e32 v81, 0xffff0000, v47
	v_lshlrev_b32_e32 v80, 16, v47
	v_pk_fma_f32 v[46:47], v[24:25], v[54:55], v[96:97]
	v_pk_fma_f32 v[92:93], v[26:27], v[72:73], v[98:99]
	v_pk_fma_f32 v[90:91], v[28:29], v[44:45], v[90:91]
	v_pk_fma_f32 v[94:95], v[30:31], v[80:81], v[100:101]
	v_pk_fma_f32 v[96:97], v[20:21], v[44:45], v[102:103]
	v_pk_fma_f32 v[98:99], v[16:17], v[44:45], v[104:105]
	v_pk_fma_f32 v[100:101], v[0:1], v[44:45], v[32:33]
	v_mul_f32_e32 v41, 0xbfb8aa3b, v46
	v_mul_f32_e32 v45, 0xbfb8aa3b, v47
	v_exp_f32_e32 v44, v41
	v_exp_f32_e32 v45, v45
	v_mul_f32_e32 v102, 0xbfb8aa3b, v92
	v_mul_f32_e32 v103, 0xbfb8aa3b, v93
	v_exp_f32_e32 v102, v102
	v_exp_f32_e32 v103, v103
	v_mul_f32_e32 v104, 0xbfb8aa3b, v90
	v_mul_f32_e32 v105, 0xbfb8aa3b, v91
	v_exp_f32_e32 v104, v104
	v_exp_f32_e32 v105, v105
	v_pk_add_f32 v[44:45], v[44:45], 1.0 op_sel_hi:[1,0]
	v_mul_f32_e32 v106, 0xbfb8aa3b, v94
	v_mul_f32_e32 v107, 0xbfb8aa3b, v95
	v_exp_f32_e32 v106, v106
	v_exp_f32_e32 v107, v107
	v_pk_add_f32 v[102:103], v[102:103], 1.0 op_sel_hi:[1,0]
	v_rcp_f32_e32 v123, v44
	v_rcp_f32_e32 v124, v45
	v_pk_add_f32 v[104:105], v[104:105], 1.0 op_sel_hi:[1,0]
	v_rcp_f32_e32 v125, v102
	v_rcp_f32_e32 v126, v103
	v_pk_add_f32 v[106:107], v[106:107], 1.0 op_sel_hi:[1,0]
	v_rcp_f32_e32 v127, v104
	v_rcp_f32_e32 v128, v105
	v_rcp_f32_e32 v129, v106
	v_rcp_f32_e32 v130, v107
	v_mul_f32_e32 v41, v46, v123
	s_mov_b64 vcc, s[0:1]
	v_mul_f32_e32 v44, v47, v124
	s_mov_b64 vcc, s[2:3]
	v_mul_f32_e32 v45, v92, v125
	s_mov_b64 vcc, s[4:5]
	v_bfe_u32 v46, v41, 16, 1
	v_mul_f32_e32 v47, v93, v126
	s_mov_b64 vcc, s[6:7]
	v_bfe_u32 v92, v44, 16, 1
	v_add3_u32 v41, v41, v46, s28
	v_mov_b32_e32 v46, v47
	v_mul_f32_e32 v47, v90, v127
	s_mov_b64 vcc, s[8:9]
	v_add3_u32 v44, v44, v92, s28
	v_mul_f32_e32 v90, v91, v128
	s_mov_b64 vcc, s[10:11]
	v_bfe_u32 v92, v46, 16, 1
	v_perm_b32 v44, v44, v41, s29
	v_mov_b32_e32 v41, v90
	v_mul_f32_e32 v90, v94, v129
	s_mov_b64 vcc, s[12:13]
	v_bfe_u32 v93, v45, 16, 1
	v_bfe_u32 v91, v47, 16, 1
	v_add3_u32 v46, v46, v92, s28
	v_mul_f32_e32 v92, v95, v130
	v_add3_u32 v45, v45, v93, s28
	v_bfe_u32 v93, v41, 16, 1
	v_add3_u32 v47, v47, v91, s28
	v_mov_b32_e32 v91, v92
	v_perm_b32 v45, v46, v45, s29
	v_bfe_u32 v46, v90, 16, 1
	v_add3_u32 v41, v41, v93, s28
	v_bfe_u32 v92, v91, 16, 1
	v_add3_u32 v90, v90, v46, s28
	v_perm_b32 v46, v41, v47, s29
	v_add3_u32 v41, v91, v92, s28
	v_perm_b32 v47, v41, v90, s29
	global_store_dwordx4 v[70:71], v[44:47], off
	global_load_dwordx4 v[44:47], v[82:83], off offset:-2048
	v_pk_fma_f32 v[48:49], v[12:13], v[54:55], v[48:49]
	v_pk_fma_f32 v[64:65], v[14:15], v[72:73], v[64:65]
	v_pk_fma_f32 v[76:77], v[22:23], v[80:81], v[76:77]
	v_pk_fma_f32 v[50:51], v[8:9], v[54:55], v[50:51]
	v_pk_fma_f32 v[54:55], v[4:5], v[54:55], v[36:37]
	v_pk_fma_f32 v[74:75], v[10:11], v[72:73], v[74:75]
	v_pk_fma_f32 v[72:73], v[6:7], v[72:73], v[38:39]
	v_pk_fma_f32 v[78:79], v[18:19], v[80:81], v[78:79]
	v_pk_fma_f32 v[80:81], v[2:3], v[80:81], v[34:35]
	s_waitcnt vmcnt(0)
	v_and_b32_e32 v71, 0xffff0000, v44
	v_lshlrev_b32_e32 v70, 16, v44
	v_and_b32_e32 v83, 0xffff0000, v45
	v_lshlrev_b32_e32 v82, 16, v45
	v_and_b32_e32 v45, 0xffff0000, v46
	v_lshlrev_b32_e32 v44, 16, v46
	v_and_b32_e32 v91, 0xffff0000, v47
	v_lshlrev_b32_e32 v90, 16, v47
	v_pk_fma_f32 v[46:47], v[24:25], v[70:71], v[48:49]
	v_pk_fma_f32 v[48:49], v[26:27], v[82:83], v[64:65]
	v_pk_fma_f32 v[64:65], v[28:29], v[44:45], v[96:97]
	v_pk_fma_f32 v[92:93], v[20:21], v[44:45], v[98:99]
	v_pk_fma_f32 v[94:95], v[16:17], v[44:45], v[100:101]
	v_pk_fma_f32 v[96:97], v[0:1], v[44:45], v[32:33]
	v_mul_f32_e32 v41, 0xbfb8aa3b, v46
	v_mul_f32_e32 v45, 0xbfb8aa3b, v47
	v_exp_f32_e32 v44, v41
	v_exp_f32_e32 v45, v45
	v_mul_f32_e32 v98, 0xbfb8aa3b, v48
	v_mul_f32_e32 v99, 0xbfb8aa3b, v49
	v_exp_f32_e32 v98, v98
	v_exp_f32_e32 v99, v99
	v_mul_f32_e32 v100, 0xbfb8aa3b, v64
	v_mul_f32_e32 v101, 0xbfb8aa3b, v65
	v_pk_fma_f32 v[76:77], v[30:31], v[90:91], v[76:77]
	v_exp_f32_e32 v100, v100
	v_exp_f32_e32 v101, v101
	v_pk_add_f32 v[44:45], v[44:45], 1.0 op_sel_hi:[1,0]
	v_mul_f32_e32 v102, 0xbfb8aa3b, v76
	v_mul_f32_e32 v103, 0xbfb8aa3b, v77
	v_exp_f32_e32 v102, v102
	v_exp_f32_e32 v103, v103
	v_pk_add_f32 v[98:99], v[98:99], 1.0 op_sel_hi:[1,0]
	v_rcp_f32_e32 v119, v44
	v_rcp_f32_e32 v120, v45
	v_pk_add_f32 v[100:101], v[100:101], 1.0 op_sel_hi:[1,0]
	v_rcp_f32_e32 v121, v98
	v_rcp_f32_e32 v122, v99
	v_pk_add_f32 v[102:103], v[102:103], 1.0 op_sel_hi:[1,0]
	v_rcp_f32_e32 v123, v100
	v_rcp_f32_e32 v124, v101
	v_rcp_f32_e32 v125, v102
	v_rcp_f32_e32 v126, v103
	v_mul_f32_e32 v41, v46, v119
	s_mov_b64 vcc, s[0:1]
	v_mul_f32_e32 v44, v47, v120
	s_mov_b64 vcc, s[2:3]
	v_mul_f32_e32 v45, v48, v121
	s_mov_b64 vcc, s[4:5]
	v_bfe_u32 v46, v41, 16, 1
	v_mul_f32_e32 v47, v49, v122
	s_mov_b64 vcc, s[6:7]
	v_bfe_u32 v48, v44, 16, 1
	v_add3_u32 v41, v41, v46, s28
	v_mov_b32_e32 v46, v47
	v_mul_f32_e32 v47, v64, v123
	s_mov_b64 vcc, s[8:9]
	v_add3_u32 v44, v44, v48, s28
	v_mul_f32_e32 v48, v65, v124
	s_mov_b64 vcc, s[10:11]
	v_bfe_u32 v49, v45, 16, 1
	v_bfe_u32 v64, v46, 16, 1
	v_perm_b32 v44, v44, v41, s29
	v_mov_b32_e32 v41, v48
	v_mul_f32_e32 v48, v76, v125
	s_mov_b64 vcc, s[12:13]
	v_add3_u32 v45, v45, v49, s28
	v_bfe_u32 v49, v47, 16, 1
	v_add3_u32 v46, v46, v64, s28
	v_mul_f32_e32 v64, v77, v126
	v_bfe_u32 v65, v41, 16, 1
	v_add3_u32 v47, v47, v49, s28
	v_mov_b32_e32 v49, v64
	v_perm_b32 v45, v46, v45, s29
	v_bfe_u32 v46, v48, 16, 1
	v_add3_u32 v41, v41, v65, s28
	v_bfe_u32 v64, v49, 16, 1
	v_add3_u32 v48, v48, v46, s28
	v_perm_b32 v46, v41, v47, s29
	v_add3_u32 v41, v49, v64, s28
	v_perm_b32 v47, v41, v48, s29
	global_store_dwordx4 v[68:69], v[44:47], off
	global_load_dwordx4 v[44:47], v[84:85], off
	v_pk_fma_f32 v[50:51], v[12:13], v[70:71], v[50:51]
	v_pk_fma_f32 v[54:55], v[8:9], v[70:71], v[54:55]
	v_pk_fma_f32 v[70:71], v[4:5], v[70:71], v[36:37]
	v_pk_fma_f32 v[74:75], v[14:15], v[82:83], v[74:75]
	v_pk_fma_f32 v[72:73], v[10:11], v[82:83], v[72:73]
	v_pk_fma_f32 v[82:83], v[6:7], v[82:83], v[38:39]
	v_pk_fma_f32 v[78:79], v[22:23], v[90:91], v[78:79]
	v_pk_fma_f32 v[80:81], v[18:19], v[90:91], v[80:81]
	v_pk_fma_f32 v[90:91], v[2:3], v[90:91], v[34:35]
	s_waitcnt vmcnt(0)
; DEVINL u16 f2bf(float f) { uint32_t u = __float_as_uint(f); u += 0x7FFFu + ((u >> 16) & 1u); return (u16)(u >> 16); }
; DEVINL float bfs2f(short h) { return __uint_as_float(((uint32_t)(u16)h) << 16); }
; DEVINL void phase_conv(const Params& p, int layer, int wv) {
;     ...
; #pragma unroll 8
;       for (int i = 0; i < 32; ++i) {
;         const bf16x8 r3 = *(const bf16x8*)(src + (size_t)i * HS);
;         bf16x8 o;
; #pragma unroll
;         for (int e = 0; e < 8; ++e) {
;           float v = bias[e] + w[0][e] * bfs2f(r0[e]) + w[1][e] * bfs2f(r1[e]) + w[2][e] * bfs2f(r2[e]) + w[3][e] * bfs2f(r3[e]);
;           v = v / (1.f + __expf(-v));
;           o[e] = (short)f2bf(v);
;         }
;         *(bf16x8*)(xc + (size_t)(tokA + i) * 1536 + ch0) = o;
;         r0 = r1; r1 = r2; r2 = r3;
	v_and_b32_e32 v49, 0xffff0000, v44
	v_lshlrev_b32_e32 v48, 16, v44
	v_pk_fma_f32 v[50:51], v[24:25], v[48:49], v[50:51]
	v_and_b32_e32 v65, 0xffff0000, v45
	v_lshlrev_b32_e32 v64, 16, v45
	v_pk_fma_f32 v[54:55], v[12:13], v[48:49], v[54:55]
	v_pk_fma_f32 v[70:71], v[8:9], v[48:49], v[70:71]
	v_mul_f32_e32 v41, 0xbfb8aa3b, v50
	v_mul_f32_e32 v49, 0xbfb8aa3b, v51
	v_pk_fma_f32 v[74:75], v[26:27], v[64:65], v[74:75]
	v_exp_f32_e32 v48, v41
	v_exp_f32_e32 v49, v49
	v_and_b32_e32 v69, 0xffff0000, v46
	v_lshlrev_b32_e32 v68, 16, v46
	v_pk_fma_f32 v[72:73], v[14:15], v[64:65], v[72:73]
	v_pk_fma_f32 v[64:65], v[10:11], v[64:65], v[82:83]
	v_mul_f32_e32 v82, 0xbfb8aa3b, v74
	v_mul_f32_e32 v83, 0xbfb8aa3b, v75
	v_and_b32_e32 v77, 0xffff0000, v47
	v_lshlrev_b32_e32 v76, 16, v47
	v_pk_fma_f32 v[84:85], v[28:29], v[68:69], v[92:93]
	v_exp_f32_e32 v82, v82
	v_exp_f32_e32 v83, v83
	v_pk_fma_f32 v[78:79], v[30:31], v[76:77], v[78:79]
	v_pk_fma_f32 v[80:81], v[22:23], v[76:77], v[80:81]
	v_pk_fma_f32 v[76:77], v[18:19], v[76:77], v[90:91]
	v_mul_f32_e32 v90, 0xbfb8aa3b, v84
	v_mul_f32_e32 v91, 0xbfb8aa3b, v85
	v_exp_f32_e32 v90, v90
	v_exp_f32_e32 v91, v91
	v_pk_add_f32 v[48:49], v[48:49], 1.0 op_sel_hi:[1,0]
	v_pk_fma_f32 v[92:93], v[20:21], v[68:69], v[94:95]
	v_mul_f32_e32 v94, 0xbfb8aa3b, v78
	v_mul_f32_e32 v95, 0xbfb8aa3b, v79
	v_pk_fma_f32 v[68:69], v[16:17], v[68:69], v[96:97]
	v_exp_f32_e32 v94, v94
	v_exp_f32_e32 v95, v95
	v_pk_add_f32 v[82:83], v[82:83], 1.0 op_sel_hi:[1,0]
	v_rcp_f32_e32 v111, v48
	v_rcp_f32_e32 v112, v49
	v_pk_add_f32 v[90:91], v[90:91], 1.0 op_sel_hi:[1,0]
	v_rcp_f32_e32 v113, v82
	v_rcp_f32_e32 v114, v83
	v_pk_add_f32 v[94:95], v[94:95], 1.0 op_sel_hi:[1,0]
	v_rcp_f32_e32 v115, v90
	v_rcp_f32_e32 v116, v91
	v_rcp_f32_e32 v117, v94
	v_rcp_f32_e32 v118, v95
	v_mul_f32_e32 v41, v50, v111
	s_mov_b64 vcc, s[0:1]
	v_mul_f32_e32 v48, v51, v112
	s_mov_b64 vcc, s[2:3]
	v_mul_f32_e32 v49, v74, v113
	s_mov_b64 vcc, s[4:5]
	v_bfe_u32 v50, v41, 16, 1
	v_mul_f32_e32 v51, v75, v114
	s_mov_b64 vcc, s[6:7]
	v_bfe_u32 v74, v48, 16, 1
	v_add3_u32 v41, v41, v50, s28
	v_mov_b32_e32 v50, v51
	v_mul_f32_e32 v51, v84, v115
	s_mov_b64 vcc, s[8:9]
	v_add3_u32 v48, v48, v74, s28
	v_mul_f32_e32 v74, v85, v116
	s_mov_b64 vcc, s[10:11]
	v_bfe_u32 v75, v49, 16, 1
	v_perm_b32 v48, v48, v41, s29
	v_mov_b32_e32 v41, v74
	v_mul_f32_e32 v74, v78, v117
	s_mov_b64 vcc, s[12:13]
	v_bfe_u32 v82, v50, 16, 1
	v_add3_u32 v49, v49, v75, s28
	v_bfe_u32 v75, v51, 16, 1
	v_mul_f32_e32 v78, v79, v118
	v_add3_u32 v50, v50, v82, s28
	v_bfe_u32 v82, v41, 16, 1
	v_add3_u32 v51, v51, v75, s28
	v_mov_b32_e32 v75, v78
	v_perm_b32 v49, v50, v49, s29
	v_bfe_u32 v50, v74, 16, 1
	v_add3_u32 v41, v41, v82, s28
	v_bfe_u32 v78, v75, 16, 1
	v_add3_u32 v74, v74, v50, s28
	v_perm_b32 v50, v41, v51, s29
	v_add3_u32 v41, v75, v78, s28
	v_perm_b32 v51, v41, v74, s29
	global_store_dwordx4 v[66:67], v[48:51], off
	global_load_dwordx4 v[48:51], v[86:87], off offset:-2048
	s_waitcnt vmcnt(0)
; DEVINL u16 f2bf(float f) { uint32_t u = __float_as_uint(f); u += 0x7FFFu + ((u >> 16) & 1u); return (u16)(u >> 16); }
; DEVINL float bfs2f(short h) { return __uint_as_float(((uint32_t)(u16)h) << 16); }
; DEVINL void phase_conv(const Params& p, int layer, int wv) {
;     ...
;     for (int run = blockIdx.x * 2 + half; run < T_TOK / 32; run += gridDim.x * 2) {
;       const int tokA = run * 32;
;       const int l0 = tokA & 4095;
;       const u16* src = hb + (size_t)tokA * HS + 1024 + ch0;
;       bf16x8 r0, r1, r2;
;       const bf16x8 zero8 = {0, 0, 0, 0, 0, 0, 0, 0};
;       r0 = (l0 >= 3) ? *(const bf16x8*)(src - 3 * (long)HS) : zero8;
;       r1 = (l0 >= 2) ? *(const bf16x8*)(src - 2 * (long)HS) : zero8;
;       r2 = (l0 >= 1) ? *(const bf16x8*)(src - 1 * (long)HS) : zero8;
; #pragma unroll 8
;       for (int i = 0; i < 32; ++i) {
;         const bf16x8 r3 = *(const bf16x8*)(src + (size_t)i * HS);
;         bf16x8 o;
; #pragma unroll
;         for (int e = 0; e < 8; ++e) {
;           float v = bias[e] + w[0][e] * bfs2f(r0[e]) + w[1][e] * bfs2f(r1[e]) + w[2][e] * bfs2f(r2[e]) + w[3][e] * bfs2f(r3[e]);
;           v = v / (1.f + __expf(-v));
;           o[e] = (short)f2bf(v);
;         }
;         *(bf16x8*)(xc + (size_t)(tokA + i) * 1536 + ch0) = o;
;         r0 = r1; r1 = r2; r2 = r3;
;       }
	v_and_b32_e32 v67, 0xffff0000, v48
	v_lshlrev_b32_e32 v66, 16, v48
	v_and_b32_e32 v75, 0xffff0000, v49
	v_lshlrev_b32_e32 v74, 16, v49
	v_pk_fma_f32 v[54:55], v[24:25], v[66:67], v[54:55]
	v_pk_fma_f32 v[72:73], v[26:27], v[74:75], v[72:73]
	v_pk_fma_f32 v[74:75], v[14:15], v[74:75], v[64:65]
	v_mul_f32_e32 v41, 0xbfb8aa3b, v54
	v_mul_f32_e32 v65, 0xbfb8aa3b, v55
	v_exp_f32_e32 v64, v41
	v_exp_f32_e32 v65, v65
	v_and_b32_e32 v79, 0xffff0000, v50
	v_lshlrev_b32_e32 v78, 16, v50
	v_pk_fma_f32 v[70:71], v[12:13], v[66:67], v[70:71]
	v_mul_f32_e32 v66, 0xbfb8aa3b, v72
	v_mul_f32_e32 v67, 0xbfb8aa3b, v73
	v_pk_fma_f32 v[84:85], v[28:29], v[78:79], v[92:93]
	v_exp_f32_e32 v66, v66
	v_exp_f32_e32 v67, v67
	v_and_b32_e32 v83, 0xffff0000, v51
	v_lshlrev_b32_e32 v82, 16, v51
	v_pk_fma_f32 v[68:69], v[20:21], v[78:79], v[68:69]
	v_mul_f32_e32 v78, 0xbfb8aa3b, v84
	v_mul_f32_e32 v79, 0xbfb8aa3b, v85
	v_pk_fma_f32 v[80:81], v[30:31], v[82:83], v[80:81]
	v_exp_f32_e32 v78, v78
	v_exp_f32_e32 v79, v79
	v_pk_add_f32 v[64:65], v[64:65], 1.0 op_sel_hi:[1,0]
	v_pk_fma_f32 v[76:77], v[22:23], v[82:83], v[76:77]
	v_mul_f32_e32 v82, 0xbfb8aa3b, v80
	v_mul_f32_e32 v83, 0xbfb8aa3b, v81
	v_exp_f32_e32 v82, v82
	v_exp_f32_e32 v83, v83
	v_pk_add_f32 v[66:67], v[66:67], 1.0 op_sel_hi:[1,0]
	v_rcp_f32_e32 v103, v64
	v_rcp_f32_e32 v104, v65
	v_pk_add_f32 v[78:79], v[78:79], 1.0 op_sel_hi:[1,0]
	v_rcp_f32_e32 v105, v66
	v_rcp_f32_e32 v106, v67
	v_pk_add_f32 v[82:83], v[82:83], 1.0 op_sel_hi:[1,0]
	v_rcp_f32_e32 v107, v78
	v_rcp_f32_e32 v108, v79
	v_rcp_f32_e32 v109, v82
	v_rcp_f32_e32 v110, v83
	v_mul_f32_e32 v41, v54, v103
	s_mov_b64 vcc, s[0:1]
	v_mul_f32_e32 v54, v55, v104
	s_mov_b64 vcc, s[2:3]
	v_mul_f32_e32 v55, v72, v105
	s_mov_b64 vcc, s[4:5]
	v_bfe_u32 v64, v41, 16, 1
	v_mul_f32_e32 v65, v73, v106
	s_mov_b64 vcc, s[6:7]
	v_bfe_u32 v66, v54, 16, 1
	v_add3_u32 v41, v41, v64, s28
	v_mul_f32_e32 v64, v84, v107
	s_mov_b64 vcc, s[8:9]
	v_add3_u32 v54, v54, v66, s28
	v_mul_f32_e32 v72, v85, v108
	s_mov_b64 vcc, s[10:11]
	v_bfe_u32 v67, v55, 16, 1
	v_mov_b32_e32 v66, v64
	v_bfe_u32 v73, v65, 16, 1
	v_perm_b32 v64, v54, v41, s29
	v_mul_f32_e32 v54, v80, v109
	s_mov_b64 vcc, s[12:13]
	v_add3_u32 v55, v55, v67, s28
	v_mov_b32_e32 v41, v72
	v_add3_u32 v65, v65, v73, s28
	v_mul_f32_e32 v72, v81, v110
	v_bfe_u32 v67, v66, 16, 1
	v_bfe_u32 v73, v41, 16, 1
	v_perm_b32 v65, v65, v55, s29
	v_mov_b32_e32 v55, v72
	v_add3_u32 v66, v66, v67, s28
	v_bfe_u32 v67, v54, 16, 1
	v_add3_u32 v41, v41, v73, s28
	v_bfe_u32 v72, v55, 16, 1
	v_add3_u32 v54, v54, v67, s28
	v_perm_b32 v66, v41, v66, s29
	v_add3_u32 v41, v55, v72, s28
	v_perm_b32 v67, v41, v54, s29
	global_store_dwordx4 v[52:53], v[64:67], off
	global_load_dwordx4 v[52:55], v[42:43], off
	v_lshl_add_u64 v[42:43], v[42:43], 0, s[20:21]
	s_waitcnt vmcnt(0)
	v_and_b32_e32 v65, 0xffff0000, v52
	v_lshlrev_b32_e32 v64, 16, v52
	v_and_b32_e32 v73, 0xffff0000, v54
	v_lshlrev_b32_e32 v72, 16, v54
	v_pk_fma_f32 v[64:65], v[24:25], v[64:65], v[70:71]
	v_and_b32_e32 v67, 0xffff0000, v53
	v_lshlrev_b32_e32 v66, 16, v53
	v_pk_fma_f32 v[68:69], v[28:29], v[72:73], v[68:69]
	v_mul_f32_e32 v41, 0xbfb8aa3b, v64
	v_mul_f32_e32 v73, 0xbfb8aa3b, v65
	v_pk_fma_f32 v[66:67], v[26:27], v[66:67], v[74:75]
	v_exp_f32_e32 v72, v41
	v_exp_f32_e32 v73, v73
	v_mul_f32_e32 v74, 0xbfb8aa3b, v66
	v_mul_f32_e32 v75, 0xbfb8aa3b, v67
	v_and_b32_e32 v79, 0xffff0000, v55
	v_lshlrev_b32_e32 v78, 16, v55
	v_exp_f32_e32 v74, v74
	v_exp_f32_e32 v75, v75
	v_pk_fma_f32 v[70:71], v[30:31], v[78:79], v[76:77]
	v_mul_f32_e32 v76, 0xbfb8aa3b, v68
	v_mul_f32_e32 v77, 0xbfb8aa3b, v69
	v_exp_f32_e32 v76, v76
	v_exp_f32_e32 v77, v77
	v_pk_add_f32 v[72:73], v[72:73], 1.0 op_sel_hi:[1,0]
	v_mul_f32_e32 v78, 0xbfb8aa3b, v70
	v_mul_f32_e32 v79, 0xbfb8aa3b, v71
	v_exp_f32_e32 v78, v78
	v_exp_f32_e32 v79, v79
	v_pk_add_f32 v[74:75], v[74:75], 1.0 op_sel_hi:[1,0]
	v_rcp_f32_e32 v97, v72
	v_rcp_f32_e32 v98, v73
	v_pk_add_f32 v[76:77], v[76:77], 1.0 op_sel_hi:[1,0]
	v_rcp_f32_e32 v99, v74
	v_rcp_f32_e32 v100, v75
	v_pk_add_f32 v[78:79], v[78:79], 1.0 op_sel_hi:[1,0]
	v_rcp_f32_e32 v101, v76
	v_rcp_f32_e32 v102, v77
	v_rcp_f32_e32 v103, v78
	v_rcp_f32_e32 v104, v79
	v_mul_f32_e32 v41, v64, v97
	s_mov_b64 vcc, s[0:1]
	v_mul_f32_e32 v64, v65, v98
	s_mov_b64 vcc, s[2:3]
	v_mul_f32_e32 v65, v66, v99
	s_mov_b64 vcc, s[4:5]
	v_mul_f32_e32 v66, v67, v100
	s_mov_b64 vcc, s[6:7]
	v_bfe_u32 v72, v41, 16, 1
	v_bfe_u32 v73, v64, 16, 1
	v_mul_f32_e32 v67, v68, v101
	s_mov_b64 vcc, s[8:9]
	v_add3_u32 v41, v41, v72, s28
	v_add3_u32 v64, v64, v73, s28
	v_mul_f32_e32 v68, v69, v102
	s_mov_b64 vcc, s[10:11]
	v_perm_b32 v64, v64, v41, s29
	v_mov_b32_e32 v41, v68
	v_mul_f32_e32 v68, v70, v103
	s_mov_b64 vcc, s[12:13]
	v_bfe_u32 v72, v65, 16, 1
	v_bfe_u32 v73, v66, 16, 1
	v_bfe_u32 v69, v67, 16, 1
	v_mul_f32_e32 v70, v71, v104
	v_add3_u32 v65, v65, v72, s28
	v_add3_u32 v66, v66, v73, s28
	v_bfe_u32 v72, v41, 16, 1
	v_add3_u32 v67, v67, v69, s28
	v_mov_b32_e32 v69, v70
	v_perm_b32 v65, v66, v65, s29
	v_bfe_u32 v66, v68, 16, 1
	v_add3_u32 v41, v41, v72, s28
	v_bfe_u32 v70, v69, 16, 1
	v_add3_u32 v68, v68, v66, s28
	v_perm_b32 v66, v41, v67, s29
	v_add3_u32 v41, v69, v70, s28
	v_perm_b32 v67, v41, v68, s29
	global_store_dwordx4 v[62:63], v[64:67], off
	s_cbranch_scc0 .LBB0_454
	v_add_u32_e32 v88, s22, v88
	v_cmp_lt_i32_e32 vcc, s35, v88
	s_or_b64 s[16:17], vcc, s[16:17]
	v_add_u32_e32 v89, s23, v89
	s_andn2_b64 exec, exec, s[16:17]
	s_cbranch_execnz .LBB0_447

; DEVINL u16 f2bf(float f) { uint32_t u = __float_as_uint(f); u += 0x7FFFu + ((u >> 16) & 1u); return (u16)(u >> 16); }
; DEVINL float shx(float v, int m, int lane) { return __int_as_float(__builtin_amdgcn_ds_bpermute((lane ^ m) << 2, __float_as_int(v))); }
; DEVINL void attn_item(const Params& p, int item, char* smem, int wv) {
;     ...
; #pragma unroll
;   for (int hh = 0; hh < 2; ++hh) {
;     float lt = lsum[hh];
;     lt += shx(lt, 16, lane); lt += shx(lt, 32, lane);
;     float inv = 1.f / lt;
; #pragma unroll
;     for (int dt = 0; dt < 8; ++dt) {
;       bf16x4 ov;
; #pragma unroll
;       for (int j = 0; j < 4; ++j) ov[j] = (short)f2bf(o[hh][dt][j] * inv);
;       *(bf16x4*)(ycat + qtok * DM + 1024 + (kvh * 2 + hh) * 128 + dt * 16 + fq * 4) = ov;
;     }
;   }
.LBB0_695:
	s_setprio 0
	v_lshlrev_b32_e32 v0, 2, v0
	v_xor_b32_e32 v10, 64, v0
	ds_bpermute_b32 v4, v10, v160
	v_xor_b32_e32 v11, 0x80, v0
	v_lshlrev_b64 v[2:3], 12, v[156:157]
	v_lshlrev_b32_e32 v0, 1, v174
	v_lshl_add_u64 v[2:3], s[94:95], 0, v[2:3]
	s_waitcnt lgkmcnt(0)
	v_add_f32_e32 v4, v160, v4
	ds_bpermute_b32 v5, v11, v4
	v_lshl_add_u64 v[2:3], v[2:3], 0, v[0:1]
	s_lshl_b32 s8, s16, 1
	s_waitcnt lgkmcnt(0)
	v_add_f32_e32 v0, v4, v5
	v_div_scale_f32 v6, s[0:1], v0, v0, 1.0
	v_rcp_f32_e32 v7, v6
	v_lshl_add_u64 v[4:5], v[2:3], 0, s[8:9]
	v_div_scale_f32 v2, vcc, 1.0, v0, 1.0
	v_fma_f32 v3, -v6, v7, 1.0
	v_fmac_f32_e32 v7, v3, v7
	v_mul_f32_e32 v3, v2, v7
	v_fma_f32 v8, -v6, v3, v2
	v_fmac_f32_e32 v3, v8, v7
	v_fma_f32 v2, -v6, v3, v2
	v_div_fmas_f32 v2, v2, v7, v3
	v_div_fixup_f32 v0, v2, v0, 1.0
	v_pk_mul_f32 v[6:7], v[88:89], v[0:1] op_sel_hi:[1,0]
	v_pk_mul_f32 v[8:9], v[90:91], v[0:1] op_sel_hi:[1,0]
	v_bfe_u32 v14, v7, 16, 1
	v_bfe_u32 v12, v9, 16, 1
	v_bfe_u32 v13, v8, 16, 1
	v_bfe_u32 v15, v6, 16, 1
	v_lshl_add_u64 v[2:3], v[4:5], 0, s[14:15]
	v_add3_u32 v6, v6, v15, s26
	v_add3_u32 v14, v7, v14, s26
	v_add3_u32 v7, v8, v13, s26
	v_add3_u32 v8, v9, v12, s26
	v_add_co_u32_e32 v4, vcc, s28, v4
	v_perm_b32 v7, v8, v7, s27
	v_perm_b32 v6, v14, v6, s27
	v_addc_co_u32_e32 v5, vcc, 0, v5, vcc
	global_store_dwordx2 v[4:5], v[6:7], off offset:2048
	v_pk_mul_f32 v[4:5], v[84:85], v[0:1] op_sel_hi:[1,0]
	v_pk_mul_f32 v[6:7], v[86:87], v[0:1] op_sel_hi:[1,0]
	v_bfe_u32 v12, v5, 16, 1
	v_bfe_u32 v8, v7, 16, 1
	v_bfe_u32 v9, v6, 16, 1
	v_bfe_u32 v13, v4, 16, 1
	v_add3_u32 v4, v4, v13, s26
	v_add3_u32 v12, v5, v12, s26
	v_add3_u32 v5, v6, v9, s26
	v_add3_u32 v6, v7, v8, s26
	v_perm_b32 v5, v6, v5, s27
	v_perm_b32 v4, v12, v4, s27
	global_store_dwordx2 v[2:3], v[4:5], off offset:32
	v_pk_mul_f32 v[4:5], v[92:93], v[0:1] op_sel_hi:[1,0]
	v_pk_mul_f32 v[6:7], v[94:95], v[0:1] op_sel_hi:[1,0]
	v_bfe_u32 v12, v5, 16, 1
	v_bfe_u32 v8, v7, 16, 1
	v_bfe_u32 v9, v6, 16, 1
	v_bfe_u32 v13, v4, 16, 1
	v_add3_u32 v4, v4, v13, s26
	v_add3_u32 v12, v5, v12, s26
	v_add3_u32 v5, v6, v9, s26
	v_add3_u32 v6, v7, v8, s26
	v_perm_b32 v5, v6, v5, s27
	v_perm_b32 v4, v12, v4, s27
	global_store_dwordx2 v[2:3], v[4:5], off offset:64
	v_pk_mul_f32 v[4:5], v[96:97], v[0:1] op_sel_hi:[1,0]
	v_pk_mul_f32 v[6:7], v[98:99], v[0:1] op_sel_hi:[1,0]
	v_bfe_u32 v12, v5, 16, 1
	v_bfe_u32 v8, v7, 16, 1
	v_bfe_u32 v9, v6, 16, 1
	v_bfe_u32 v13, v4, 16, 1
	v_add3_u32 v4, v4, v13, s26
	v_add3_u32 v12, v5, v12, s26
	v_add3_u32 v5, v6, v9, s26
	v_add3_u32 v6, v7, v8, s26
	v_perm_b32 v5, v6, v5, s27
	v_perm_b32 v4, v12, v4, s27
	global_store_dwordx2 v[2:3], v[4:5], off offset:96
	v_pk_mul_f32 v[4:5], v[104:105], v[0:1] op_sel_hi:[1,0]
	v_pk_mul_f32 v[6:7], v[106:107], v[0:1] op_sel_hi:[1,0]
	v_bfe_u32 v12, v5, 16, 1
	v_bfe_u32 v8, v7, 16, 1
	v_bfe_u32 v9, v6, 16, 1
	v_bfe_u32 v13, v4, 16, 1
	v_add3_u32 v4, v4, v13, s26
	v_add3_u32 v12, v5, v12, s26
	v_add3_u32 v5, v6, v9, s26
	v_add3_u32 v6, v7, v8, s26
	v_perm_b32 v5, v6, v5, s27
	v_perm_b32 v4, v12, v4, s27
	global_store_dwordx2 v[2:3], v[4:5], off offset:128
	v_pk_mul_f32 v[4:5], v[108:109], v[0:1] op_sel_hi:[1,0]
	v_pk_mul_f32 v[6:7], v[110:111], v[0:1] op_sel_hi:[1,0]
	v_bfe_u32 v12, v5, 16, 1
	v_bfe_u32 v8, v7, 16, 1
	v_bfe_u32 v9, v6, 16, 1
	v_bfe_u32 v13, v4, 16, 1
	v_add3_u32 v4, v4, v13, s26
	v_add3_u32 v12, v5, v12, s26
	v_add3_u32 v5, v6, v9, s26
	v_add3_u32 v6, v7, v8, s26
	v_perm_b32 v5, v6, v5, s27
	v_perm_b32 v4, v12, v4, s27
	global_store_dwordx2 v[2:3], v[4:5], off offset:160
	v_pk_mul_f32 v[4:5], v[112:113], v[0:1] op_sel_hi:[1,0]
	v_pk_mul_f32 v[6:7], v[114:115], v[0:1] op_sel_hi:[1,0]
	v_bfe_u32 v12, v5, 16, 1
	v_bfe_u32 v8, v7, 16, 1
	v_bfe_u32 v9, v6, 16, 1
	v_bfe_u32 v13, v4, 16, 1
	v_add3_u32 v4, v4, v13, s26
	v_add3_u32 v12, v5, v12, s26
	v_add3_u32 v5, v6, v9, s26
	v_add3_u32 v6, v7, v8, s26
	v_perm_b32 v5, v6, v5, s27
	v_perm_b32 v4, v12, v4, s27
	global_store_dwordx2 v[2:3], v[4:5], off offset:192
	v_pk_mul_f32 v[4:5], v[100:101], v[0:1] op_sel_hi:[1,0]
	v_pk_mul_f32 v[6:7], v[102:103], v[0:1] op_sel_hi:[1,0]
	ds_bpermute_b32 v0, v10, v161
	v_bfe_u32 v8, v7, 16, 1
	v_bfe_u32 v9, v6, 16, 1
	v_bfe_u32 v10, v5, 16, 1
	v_add3_u32 v10, v5, v10, s26
	s_waitcnt lgkmcnt(0)
; DEVINL u16 f2bf(float f) { uint32_t u = __float_as_uint(f); u += 0x7FFFu + ((u >> 16) & 1u); return (u16)(u >> 16); }
; DEVINL float shx(float v, int m, int lane) { return __int_as_float(__builtin_amdgcn_ds_bpermute((lane ^ m) << 2, __float_as_int(v))); }
; DEVINL void attn_item(const Params& p, int item, char* smem, int wv) {
;     ...
; #pragma unroll
;   for (int hh = 0; hh < 2; ++hh) {
;     float lt = lsum[hh];
;     lt += shx(lt, 16, lane); lt += shx(lt, 32, lane);
;     float inv = 1.f / lt;
; #pragma unroll
;     for (int dt = 0; dt < 8; ++dt) {
;       bf16x4 ov;
; #pragma unroll
;       for (int j = 0; j < 4; ++j) ov[j] = (short)f2bf(o[hh][dt][j] * inv);
;       *(bf16x4*)(ycat + qtok * DM + 1024 + (kvh * 2 + hh) * 128 + dt * 16 + fq * 4) = ov;
;     }
;   }
	v_add_f32_e32 v0, v161, v0
	ds_bpermute_b32 v11, v11, v0
	v_add3_u32 v5, v6, v9, s26
	v_add3_u32 v6, v7, v8, s26
	v_bfe_u32 v12, v4, 16, 1
	v_add3_u32 v4, v4, v12, s26
	s_waitcnt lgkmcnt(0)
	v_add_f32_e32 v0, v0, v11
	v_div_scale_f32 v7, s[0:1], v0, v0, 1.0
	v_rcp_f32_e32 v8, v7
	v_perm_b32 v5, v6, v5, s27
	v_perm_b32 v4, v10, v4, s27
	global_store_dwordx2 v[2:3], v[4:5], off offset:224
	v_fma_f32 v4, -v7, v8, 1.0
	v_fmac_f32_e32 v8, v4, v8
	v_div_scale_f32 v4, vcc, 1.0, v0, 1.0
	v_mul_f32_e32 v5, v4, v8
	v_fma_f32 v6, -v7, v5, v4
	v_fmac_f32_e32 v5, v6, v8
	v_fma_f32 v4, -v7, v5, v4
	v_div_fmas_f32 v4, v4, v8, v5
	v_div_fixup_f32 v0, v4, v0, 1.0
	v_pk_mul_f32 v[4:5], v[52:53], v[0:1] op_sel_hi:[1,0]
	v_pk_mul_f32 v[6:7], v[54:55], v[0:1] op_sel_hi:[1,0]
	v_bfe_u32 v10, v5, 16, 1
	v_bfe_u32 v8, v7, 16, 1
	v_bfe_u32 v9, v6, 16, 1
	v_bfe_u32 v11, v4, 16, 1
	v_add3_u32 v4, v4, v11, s26
	v_add3_u32 v10, v5, v10, s26
	v_add3_u32 v5, v6, v9, s26
	v_add3_u32 v6, v7, v8, s26
	v_perm_b32 v5, v6, v5, s27
	v_perm_b32 v4, v10, v4, s27
	global_store_dwordx2 v[2:3], v[4:5], off offset:256
	v_pk_mul_f32 v[4:5], v[56:57], v[0:1] op_sel_hi:[1,0]
	v_pk_mul_f32 v[6:7], v[58:59], v[0:1] op_sel_hi:[1,0]
	v_bfe_u32 v10, v5, 16, 1
	v_bfe_u32 v8, v7, 16, 1
	v_bfe_u32 v9, v6, 16, 1
	v_bfe_u32 v11, v4, 16, 1
	v_add3_u32 v4, v4, v11, s26
	v_add3_u32 v10, v5, v10, s26
	v_add3_u32 v5, v6, v9, s26
	v_add3_u32 v6, v7, v8, s26
	v_perm_b32 v5, v6, v5, s27
	v_perm_b32 v4, v10, v4, s27
	global_store_dwordx2 v[2:3], v[4:5], off offset:288
	v_pk_mul_f32 v[4:5], v[60:61], v[0:1] op_sel_hi:[1,0]
	v_pk_mul_f32 v[6:7], v[62:63], v[0:1] op_sel_hi:[1,0]
	v_bfe_u32 v10, v5, 16, 1
	v_bfe_u32 v8, v7, 16, 1
	v_bfe_u32 v9, v6, 16, 1
	v_bfe_u32 v11, v4, 16, 1
	v_add3_u32 v4, v4, v11, s26
	v_add3_u32 v10, v5, v10, s26
	v_add3_u32 v5, v6, v9, s26
	v_add3_u32 v6, v7, v8, s26
	v_perm_b32 v5, v6, v5, s27
	v_perm_b32 v4, v10, v4, s27
	global_store_dwordx2 v[2:3], v[4:5], off offset:320
	v_pk_mul_f32 v[4:5], v[64:65], v[0:1] op_sel_hi:[1,0]
	v_pk_mul_f32 v[6:7], v[66:67], v[0:1] op_sel_hi:[1,0]
	v_bfe_u32 v10, v5, 16, 1
	v_bfe_u32 v8, v7, 16, 1
	v_bfe_u32 v9, v6, 16, 1
	v_bfe_u32 v11, v4, 16, 1
	v_add3_u32 v4, v4, v11, s26
	v_add3_u32 v10, v5, v10, s26
	v_add3_u32 v5, v6, v9, s26
	v_add3_u32 v6, v7, v8, s26
	v_perm_b32 v5, v6, v5, s27
	v_perm_b32 v4, v10, v4, s27
	global_store_dwordx2 v[2:3], v[4:5], off offset:352
	v_pk_mul_f32 v[4:5], v[72:73], v[0:1] op_sel_hi:[1,0]
	v_pk_mul_f32 v[6:7], v[74:75], v[0:1] op_sel_hi:[1,0]
	v_bfe_u32 v10, v5, 16, 1
	v_bfe_u32 v8, v7, 16, 1
	v_bfe_u32 v9, v6, 16, 1
	v_bfe_u32 v11, v4, 16, 1
	v_add3_u32 v4, v4, v11, s26
	v_add3_u32 v10, v5, v10, s26
	v_add3_u32 v5, v6, v9, s26
	v_add3_u32 v6, v7, v8, s26
	v_perm_b32 v5, v6, v5, s27
	v_perm_b32 v4, v10, v4, s27
	global_store_dwordx2 v[2:3], v[4:5], off offset:384
	v_pk_mul_f32 v[4:5], v[76:77], v[0:1] op_sel_hi:[1,0]
	v_pk_mul_f32 v[6:7], v[78:79], v[0:1] op_sel_hi:[1,0]
	v_bfe_u32 v10, v5, 16, 1
	v_bfe_u32 v8, v7, 16, 1
	v_bfe_u32 v9, v6, 16, 1
	v_bfe_u32 v11, v4, 16, 1
	v_add3_u32 v4, v4, v11, s26
	v_add3_u32 v10, v5, v10, s26
	v_add3_u32 v5, v6, v9, s26
	v_add3_u32 v6, v7, v8, s26
	v_perm_b32 v5, v6, v5, s27
	v_perm_b32 v4, v10, v4, s27
	global_store_dwordx2 v[2:3], v[4:5], off offset:416
	v_pk_mul_f32 v[4:5], v[80:81], v[0:1] op_sel_hi:[1,0]
	v_pk_mul_f32 v[6:7], v[82:83], v[0:1] op_sel_hi:[1,0]
	v_bfe_u32 v10, v5, 16, 1
	v_bfe_u32 v8, v7, 16, 1
	v_bfe_u32 v9, v6, 16, 1
	v_bfe_u32 v11, v4, 16, 1
	v_add3_u32 v4, v4, v11, s26
	v_add3_u32 v10, v5, v10, s26
	v_add3_u32 v5, v6, v9, s26
	v_add3_u32 v6, v7, v8, s26
	v_perm_b32 v5, v6, v5, s27
	v_perm_b32 v4, v10, v4, s27
	global_store_dwordx2 v[2:3], v[4:5], off offset:448
	v_pk_mul_f32 v[4:5], v[68:69], v[0:1] op_sel_hi:[1,0]
	v_pk_mul_f32 v[6:7], v[70:71], v[0:1] op_sel_hi:[1,0]
	v_bfe_u32 v9, v5, 16, 1
	v_bfe_u32 v0, v7, 16, 1
	v_bfe_u32 v8, v6, 16, 1
	v_bfe_u32 v10, v4, 16, 1
	v_add3_u32 v4, v4, v10, s26
	v_add3_u32 v9, v5, v9, s26
	v_add3_u32 v5, v6, v8, s26
	v_add3_u32 v0, v7, v0, s26
	v_perm_b32 v5, v0, v5, s27
	v_perm_b32 v4, v9, v4, s27
	s_mov_b64 s[0:1], 0
	global_store_dwordx2 v[2:3], v[4:5], off offset:480

; DEVINL int next_item(int* ctr, char* smem, int wv) {
;   int* slot = (int*)(smem + SMEM_MAIN);
;   __syncthreads();
;   if (opaque_tid(wv) == 0) *slot = atomicAdd(ctr, 1);
;   __syncthreads();
;   return *slot;
; DEVINL void attn_item(const Params& p, int item, char* smem, int wv) {
;     ...
;   const int tid = opaque_tid(wv), lane = tid & 63, wid = __builtin_amdgcn_readfirstlane(tid >> 6), fr = lane & 15, fq = lane >> 4;
;   const int qblk = 31 - (item >> 4), b = (item >> 2) & 3, kvh = item & 3;
;   const int q0 = qblk * 128, ntile = 2 * qblk + 2;
;   const int qlast = q0 + wid * 16 + 15;
;   u16* Ks = (u16*)smem;
;   u16* Vs = Ks + 64 * 136;
;   const size_t qtok = (size_t)b * SEQ + q0 + wid * 16 + fr;
;   bf16x8 qf[2][4];
; #pragma unroll
;   for (int hh = 0; hh < 2; ++hh)
; #pragma unroll
;     for (int kc = 0; kc < 4; ++kc)
;       qf[hh][kc] = *(const bf16x8*)(hb + qtok * HS + 2560 + (kvh * 2 + hh) * 128 + kc * 32 + fq * 8);
;   f32x4 o[2][8];
; #pragma unroll
;   for (int hh = 0; hh < 2; ++hh)
; #pragma unroll
;     for (int dt = 0; dt < 8; ++dt) o[hh][dt] = f32x4{0.f, 0.f, 0.f, 0.f};
;   float mrun[2] = {0.f, 0.f}, lsum[2] = {0.f, 0.f};
;   unsigned long long mw_next = bits[qtok * 64];
;   u32x4 rk[2], rv[2];
;   const u16* kg = hb + ((size_t)b * SEQ + (tid >> 4)) * HS + 3584 + kvh * 128 + (tid & 15) * 8;
;   const u16* vg = vT + ((size_t)(b * 4 + kvh) * 128 + (tid >> 3)) * SEQ + (tid & 7) * 8;
; #pragma unroll
;   for (int i = 0; i < 2; ++i) {
;     rk[i] = *(const u32x4*)(kg + (size_t)(32 * i) * HS);
;     rv[i] = *(const u32x4*)(vg + (size_t)(64 * i) * SEQ);
;   }
;   for (int kt = 0; kt < ntile; ++kt) {
; #pragma unroll
;     for (int i = 0; i < 2; ++i) {
;       *(u32x4*)(Ks + ((tid >> 4) + 32 * i) * 136 + (tid & 15) * 8) = rk[i];
;       *(u32x4*)(Vs + ((tid >> 3) + 64 * i) * 72 + (tid & 7) * 8) = rv[i];
;     }
;     __syncthreads();
;     if (kt + 1 < ntile) {
; #pragma unroll
;       for (int i = 0; i < 2; ++i) {
;         rk[i] = *(const u32x4*)(kg + (size_t)((kt + 1) * 64 + 32 * i) * HS);
;         rv[i] = *(const u32x4*)(vg + (size_t)(64 * i) * SEQ + (kt + 1) * 64);
;       }
;     }
;     const unsigned long long mw = mw_next;
;     if (kt + 1 < ntile) mw_next = bits[qtok * 64 + kt + 1];
.LBB0_701:
	s_or_b64 exec, exec, s[0:1]
	s_waitcnt lgkmcnt(0)
	s_barrier
	ds_read_b32 v0, v170
	s_movk_i32 s0, 0x1ff
	s_waitcnt lgkmcnt(0)
	v_cmp_lt_i32_e32 vcc, s0, v0
	v_readfirstlane_b32 s5, v0
	s_mov_b64 s[0:1], -1
	s_cbranch_vccnz .LBB0_696
	v_mov_b32_e32 v120, v176
	s_ashr_i32 s29, s5, 4
	s_sub_i32 s30, 31, s29
	v_readfirstlane_b32 s0, v120
	s_lshl_b32 s1, s5, 10
	s_lshl_b32 s7, s30, 7
	s_ashr_i32 s31, s0, 2
	s_cmp_lt_i32 s31, 64
	s_cbranch_scc1 .Lprio_skip_a0
	s_setprio 2
.Lprio_skip_a0:
	s_and_b32 s33, s1, 0x3000
	v_and_b32_e32 v60, 15, v120
	s_and_b32 s0, s31, -16
	s_add_i32 s8, s7, s33
	s_ashr_i32 s1, s0, 31
	v_or_b32_e32 v0, s8, v60
	s_waitcnt vmcnt(1)
	v_lshl_add_u64 v[156:157], v[0:1], 0, s[0:1]
	v_mov_b64_e32 v[2:3], s[62:63]
	v_mad_u64_u32 v[4:5], s[0:1], v156, s19, v[2:3]
	s_and_b32 s6, s5, 3
	v_mad_i32_i24 v5, v157, s19, v5
	v_and_b32_e32 v0, 48, v120
	v_lshl_add_u64 v[4:5], v[4:5], 0, v[0:1]
	s_lshl_b32 s8, s6, 9
	v_ashrrev_i32_e32 v14, 4, v120
	v_lshl_add_u64 v[8:9], v[4:5], 0, s[8:9]
	v_add_u32_e32 v4, s33, v14
	s_lshl_b32 s16, s6, 8
	s_mov_b32 s17, s9
	v_mad_i64_i32 v[2:3], s[0:1], v4, s19, v[2:3]
	v_lshlrev_b32_e32 v6, 4, v120
	v_lshl_add_u64 v[2:3], v[2:3], 0, s[16:17]
	v_and_b32_e32 v10, 0xf0, v6
	v_mov_b32_e32 v11, v1
	v_lshl_add_u64 v[116:117], v[2:3], 0, v[10:11]
	s_lshl_b32 s0, s5, 7
	v_ashrrev_i32_e32 v2, 3, v120
	s_and_b32 s8, s0, 0x780
	v_ashrrev_i32_e32 v3, 31, v2
	v_lshl_add_u64 v[4:5], v[2:3], 0, s[8:9]
	v_lshlrev_b64 v[4:5], 13, v[4:5]
	v_lshl_add_u64 v[4:5], s[82:83], 0, v[4:5]
	v_and_b32_e32 v12, 0x70, v6
	v_mov_b32_e32 v13, v1
	v_lshl_add_u64 v[158:159], v[4:5], 0, v[12:13]
	v_add_co_u32_e32 v4, vcc, s20, v116
	global_load_dwordx4 v[36:39], v[158:159], off
	s_nop 0
	v_addc_co_u32_e32 v5, vcc, 0, v117, vcc
	v_add_co_u32_e32 v6, vcc, s21, v116
	v_mul_lo_u32 v2, v2, s24
	s_nop 0
	v_addc_co_u32_e32 v7, vcc, 0, v117, vcc
	global_load_dwordx4 v[40:43], v[4:5], off offset:3072
	global_load_dwordx4 v[44:47], v[6:7], off offset:3072
	v_add_co_u32_e32 v52, vcc, s22, v158
	v_add_u32_e32 v11, 0, v12
	s_nop 0
	v_addc_co_u32_e32 v53, vcc, 0, v159, vcc
	global_load_dwordx4 v[48:51], v[52:53], off
	v_mul_lo_u32 v3, v14, s23
	v_add_u32_e32 v10, 0, v10
	v_and_b32_e32 v173, 64, v12
	v_bfe_u32 v11, v12, 4, 1
	v_lshl_or_b32 v173, v11, 5, v173
	v_bfe_u32 v11, v12, 5, 1
	v_lshl_or_b32 v173, v11, 3, v173
	v_add_u32_e32 v173, v173, v2
	v_add_co_u32_e64 v2, s[0:1], s20, v8
	v_lshl_add_u64 v[28:29], v[8:9], 0, s[10:11]
	v_add_u32_e32 v172, v10, v3
	v_lshlrev_b64 v[118:119], 9, v[156:157]
	v_add_co_u32_e32 v54, vcc, 0xa1000, v116
	v_addc_co_u32_e64 v3, s[0:1], 0, v9, s[0:1]
	global_load_dwordx4 v[4:7], v[28:29], off offset:64
	v_lshl_add_u64 v[56:57], s[80:81], 0, v[118:119]
	v_addc_co_u32_e32 v55, vcc, 0, v117, vcc
	global_load_dwordx4 v[8:11], v[28:29], off offset:128
	global_load_dwordx4 v[12:15], v[28:29], off offset:192
	global_load_dwordx4 v[16:19], v[28:29], off offset:256
	global_load_dwordx4 v[20:23], v[28:29], off offset:320
	global_load_dwordx4 v[24:27], v[28:29], off offset:384
	s_nop 0
	global_load_dwordx4 v[28:31], v[28:29], off offset:448
	s_nop 0
	global_load_dwordx4 v[32:35], v[2:3], off offset:1024
	s_nop 0
	global_load_dwordx2 v[2:3], v[56:57], off
	v_add_co_u32_e32 v58, vcc, 0xf1000, v116
	s_add_i32 s8, s31, s7
	s_nop 0
	v_addc_co_u32_e32 v59, vcc, 0, v117, vcc
	s_cmp_gt_i32 s8, -1
	s_mov_b64 s[0:1], -1
	s_waitcnt vmcnt(11)
	ds_write_b128 v172, v[40:43]
	ds_write_b64 v173, v[36:37] offset:17408
	ds_write_b64 v173, v[38:39] offset:17424
	s_waitcnt vmcnt(10)
	ds_write_b128 v172, v[44:47] offset:8704
	s_waitcnt vmcnt(9)
	ds_write_b64 v173, v[48:49] offset:26624
	ds_write_b64 v173, v[50:51] offset:26640
	s_waitcnt lgkmcnt(0)
	s_barrier
	global_load_dwordx4 v[44:47], v[58:59], off offset:3072
	global_load_dwordx4 v[36:39], v[54:55], off offset:3072
	global_load_dwordx4 v[48:51], v[52:53], off offset:128
	global_load_dwordx4 v[40:43], v[158:159], off offset:128
	global_load_dwordx2 v[162:163], v[56:57], off offset:8
	v_mad_u32_u24 v52, v60, s23, 0
	v_lshlrev_b32_e32 v53, 7, v60
	v_lshrrev_b32_e32 v54, 2, v120
	v_sub_u32_e32 v53, v52, v53
	v_and_b32_e32 v174, 12, v54
	v_add_u32_e32 v175, v52, v0
	v_lshl_add_u32 v177, v174, 2, v53
	s_cbranch_scc0 .LBB0_704
; DEVINL float fexp2(float x) { return __builtin_amdgcn_exp2f(x); }
; #define LDK(DST, KQ) _Pragma("unroll") for (int kc = 0; kc < 4; ++kc) DST[kc] = *(const bf16x8*)(Ks + ((KQ) * 16 + fr) * 136 + kc * 32 + fq * 8)
; #define MMS(SRC, KQ) do { s[0][KQ] = f32x4{-mrun[0], -mrun[0], -mrun[0], -mrun[0]}; s[1][KQ] = f32x4{-mrun[1], -mrun[1], -mrun[1], -mrun[1]}; __builtin_amdgcn_s_setprio(1); \
;       _Pragma("unroll") for (int kc = 0; kc < 4; ++kc) { s[0][KQ] = mfma16(SRC[kc], qf[0][kc], s[0][KQ]); s[1][KQ] = mfma16(SRC[kc], qf[1][kc], s[1][KQ]); } __builtin_amdgcn_s_setprio(0); } while (0)
; DEVINL void attn_item(const Params& p, int item, char* smem, int wv) {
;     ...
;     LDK(kfa, 0);
;     LDK(kfb, 1); MMS(kfa, 0);
;     LDK(kfa, 2); MMS(kfb, 1);
;     LDK(kfb, 3); MMS(kfa, 2);
;     LDV(vfa, 0); MMS(kfb, 3);
;     bf16x8 pf[2][2];
;     {
;       const unsigned long long msh = mw >> (fq * 4);
;       const int mlo = (int)(unsigned)msh, mhi = (int)(unsigned)(msh >> 32);
;       int mk[4][4];
; #pragma unroll
;       for (int j = 0; j < 4; ++j) {
;         mk[0][j] = __builtin_amdgcn_sbfe(mlo, j, 1); mk[1][j] = __builtin_amdgcn_sbfe(mlo, 16 + j, 1);
;         mk[2][j] = __builtin_amdgcn_sbfe(mhi, j, 1); mk[3][j] = __builtin_amdgcn_sbfe(mhi, 16 + j, 1);
;       }
; #pragma unroll
;       for (int hh = 0; hh < 2; ++hh) {
;         float mx = s[hh][0][0];
; #pragma unroll
;         for (int kq = 0; kq < 4; ++kq)
; #pragma unroll
;           for (int j = 0; j < 4; ++j) mx = fmaxf(mx, s[hh][kq][j]);
;         {
;           auto r1 = __builtin_amdgcn_permlane16_swap(__float_as_uint(mx), __float_as_uint(mx), false, false);
;           mx = fmaxf(__uint_as_float(r1[0]), __uint_as_float(r1[1]));
;           auto r2 = __builtin_amdgcn_permlane32_swap(__float_as_uint(mx), __float_as_uint(mx), false, false);
;           mx = fmaxf(__uint_as_float(r2[0]), __uint_as_float(r2[1]));
;         }
;         if (kt == 0 || __ballot(mx > 8.f)) {
;           const float delta = (kt == 0) ? mx : fmaxf(mx, 0.f);
;           const float alpha = fexp2(-delta);
;           mrun[hh] += delta;
;           lsum[hh] *= alpha;
; #pragma unroll
;           for (int dt = 0; dt < 8; ++dt) o[hh][dt] *= alpha;
; #pragma unroll
;           for (int kq = 0; kq < 4; ++kq)
; #pragma unroll
;             for (int j = 0; j < 4; ++j) s[hh][kq][j] -= delta;
	ds_read_b128 v[52:55], v175
	ds_read_b128 v[56:59], v175 offset:64
	ds_read_b128 v[60:63], v175 offset:128
	ds_read_b128 v[64:67], v175 offset:192
	ds_read_b128 v[68:71], v175 offset:4352
	ds_read_b128 v[72:75], v175 offset:4416
	ds_read_b128 v[76:79], v175 offset:4480
	ds_read_b128 v[80:83], v175 offset:4544
	s_mov_b32 s6, s4
	s_mov_b32 s7, s4
	s_mov_b32 s5, s4
	v_mov_b64_e32 v[86:87], s[6:7]
	v_mov_b64_e32 v[84:85], s[4:5]
	s_waitcnt vmcnt(6) lgkmcnt(7)
	s_nop 0
	v_mfma_f32_16x16x32_bf16 v[88:91], v[52:55], v[32:35], v[84:87]
	v_mfma_f32_16x16x32_bf16 v[52:55], v[52:55], v[16:19], v[84:87]
	s_waitcnt lgkmcnt(6)
	v_mfma_f32_16x16x32_bf16 v[88:91], v[56:59], v[4:7], v[88:91]
	v_mfma_f32_16x16x32_bf16 v[52:55], v[56:59], v[20:23], v[52:55]
	s_waitcnt lgkmcnt(5)
	v_mfma_f32_16x16x32_bf16 v[56:59], v[60:63], v[8:11], v[88:91]
	v_mfma_f32_16x16x32_bf16 v[52:55], v[60:63], v[24:27], v[52:55]
	s_waitcnt lgkmcnt(4)
	v_mfma_f32_16x16x32_bf16 v[60:63], v[64:67], v[12:15], v[56:59]
	v_mfma_f32_16x16x32_bf16 v[64:67], v[64:67], v[28:31], v[52:55]
	s_nop 3
	ds_read_b128 v[52:55], v175 offset:8704
	ds_read_b128 v[56:59], v175 offset:8768
	ds_read_b128 v[88:91], v175 offset:8832
	ds_read_b128 v[92:95], v175 offset:8896
	s_waitcnt lgkmcnt(7)
	v_mfma_f32_16x16x32_bf16 v[96:99], v[68:71], v[32:35], v[84:87]
	v_mfma_f32_16x16x32_bf16 v[68:71], v[68:71], v[16:19], v[84:87]
	s_waitcnt lgkmcnt(6)
	v_mfma_f32_16x16x32_bf16 v[96:99], v[72:75], v[4:7], v[96:99]
	v_mfma_f32_16x16x32_bf16 v[68:71], v[72:75], v[20:23], v[68:71]
	s_waitcnt lgkmcnt(5)
	v_mfma_f32_16x16x32_bf16 v[72:75], v[76:79], v[8:11], v[96:99]
	v_mfma_f32_16x16x32_bf16 v[68:71], v[76:79], v[24:27], v[68:71]
	s_waitcnt lgkmcnt(4)
	v_mfma_f32_16x16x32_bf16 v[72:75], v[80:83], v[12:15], v[72:75]
	v_mfma_f32_16x16x32_bf16 v[68:71], v[80:83], v[28:31], v[68:71]
	ds_read_b128 v[76:79], v175 offset:13056
	ds_read_b128 v[80:83], v175 offset:13120
	ds_read_b128 v[96:99], v175 offset:13184
	ds_read_b128 v[100:103], v175 offset:13248
	s_waitcnt lgkmcnt(7)
	v_mfma_f32_16x16x32_bf16 v[104:107], v[52:55], v[32:35], v[84:87]
	v_mfma_f32_16x16x32_bf16 v[52:55], v[52:55], v[16:19], v[84:87]
	s_waitcnt lgkmcnt(6)
	v_mfma_f32_16x16x32_bf16 v[104:107], v[56:59], v[4:7], v[104:107]
	v_mfma_f32_16x16x32_bf16 v[52:55], v[56:59], v[20:23], v[52:55]
	s_waitcnt lgkmcnt(5)
	v_mfma_f32_16x16x32_bf16 v[56:59], v[88:91], v[8:11], v[104:107]
	v_mfma_f32_16x16x32_bf16 v[52:55], v[88:91], v[24:27], v[52:55]
	s_waitcnt lgkmcnt(4)
	v_mfma_f32_16x16x32_bf16 v[88:91], v[92:95], v[12:15], v[56:59]
	v_mfma_f32_16x16x32_bf16 v[92:95], v[92:95], v[28:31], v[52:55]
	s_nop 0
	s_nop 2
	ds_read_b128 v[52:55], v177 offset:17408
	ds_read_b128 v[56:59], v177 offset:17472
	s_waitcnt lgkmcnt(5)
	v_mfma_f32_16x16x32_bf16 v[104:107], v[76:79], v[32:35], v[84:87]
	v_mfma_f32_16x16x32_bf16 v[76:79], v[76:79], v[16:19], v[84:87]
	s_waitcnt lgkmcnt(4)
	v_mfma_f32_16x16x32_bf16 v[84:87], v[80:83], v[4:7], v[104:107]
	v_mfma_f32_16x16x32_bf16 v[76:79], v[80:83], v[20:23], v[76:79]
	s_waitcnt lgkmcnt(3)
	v_mfma_f32_16x16x32_bf16 v[80:83], v[96:99], v[8:11], v[84:87]
	v_mfma_f32_16x16x32_bf16 v[76:79], v[96:99], v[24:27], v[76:79]
	s_waitcnt lgkmcnt(2)
	v_mfma_f32_16x16x32_bf16 v[80:83], v[100:103], v[12:15], v[80:83]
	v_mfma_f32_16x16x32_bf16 v[76:79], v[100:103], v[28:31], v[76:79]
	s_waitcnt vmcnt(5)
	v_lshrrev_b64 v[2:3], v174, v[2:3]
	v_bfe_i32 v0, v2, 0, 1
	v_bfe_i32 v86, v2, 16, 1
	v_bfe_i32 v87, v3, 0, 1
	v_bfe_i32 v96, v3, 16, 1
	v_bfe_i32 v97, v2, 1, 1
	v_bfe_i32 v98, v2, 17, 1
	v_bfe_i32 v99, v3, 1, 1
	v_bfe_i32 v104, v3, 17, 1
	v_bfe_i32 v100, v2, 2, 1
	v_bfe_i32 v101, v2, 18, 1
	v_bfe_i32 v105, v3, 2, 1
	v_bfe_i32 v106, v3, 18, 1
	v_bfe_i32 v102, v2, 3, 1
	v_bfe_i32 v103, v2, 19, 1
	v_bfe_i32 v107, v3, 3, 1
	v_bfe_i32 v108, v3, 19, 1
	v_max_f32_e32 v2, v61, v61
	v_max_f32_e32 v3, v60, v60
	v_max_f32_e32 v2, v3, v2
	v_max3_f32 v2, v2, v62, v63
	v_max3_f32 v2, v2, v72, v73
	v_max3_f32 v2, v2, v74, v75
	v_max3_f32 v2, v2, v88, v89
	v_max3_f32 v2, v2, v90, v91
	v_max3_f32 v2, v2, v80, v81
	v_max3_f32 v2, v2, v82, v83
	v_mov_b32_e32 v3, v2
	s_nop 1
	v_permlane16_swap_b32_e32 v2, v3
	v_max_f32_e32 v3, v3, v3
	v_max_f32_e32 v2, v2, v2
	v_max_f32_e32 v2, v2, v3
	v_mov_b32_e32 v3, v2
	s_nop 1
	v_permlane32_swap_b32_e32 v2, v3
	v_max_f32_e32 v3, v3, v3
	v_max_f32_e32 v2, v2, v2
	v_max_f32_e32 v3, v2, v3
	v_sub_f32_e32 v2, v80, v3
	v_sub_f32_e32 v61, v61, v3
	v_sub_f32_e32 v80, v81, v3
	v_sub_f32_e32 v81, v82, v3
	v_sub_f32_e32 v82, v83, v3
	v_sub_f32_e32 v83, v88, v3
	v_sub_f32_e32 v88, v90, v3
	v_exp_f32_e32 v90, v61
	v_exp_f32_e32 v115, v2
	v_max_f32_e32 v2, v65, v65
	v_max_f32_e32 v61, v64, v64
	v_max_f32_e32 v2, v61, v2
	v_max3_f32 v2, v2, v66, v67
	v_max3_f32 v2, v2, v68, v69
	v_max3_f32 v2, v2, v70, v71
	v_max3_f32 v2, v2, v92, v93
	v_max3_f32 v2, v2, v94, v95
	v_max3_f32 v2, v2, v76, v77
	v_max3_f32 v2, v2, v78, v79
	v_mov_b32_e32 v61, v2
	s_nop 1
	v_permlane16_swap_b32_e32 v2, v61
	v_max_f32_e32 v61, v61, v61
	v_max_f32_e32 v2, v2, v2
	v_max_f32_e32 v2, v2, v61
	v_mov_b32_e32 v61, v2
	s_nop 1
	v_permlane32_swap_b32_e32 v2, v61
	v_max_f32_e32 v61, v61, v61
	v_max_f32_e32 v2, v2, v2
	v_max_f32_e32 v2, v2, v61
	v_sub_f32_e32 v60, v60, v3
	v_sub_f32_e32 v64, v64, v2
	v_exp_f32_e32 v60, v60
	v_sub_f32_e32 v65, v65, v2
	v_exp_f32_e32 v64, v64
	v_sub_f32_e32 v62, v62, v3
	v_sub_f32_e32 v66, v66, v2
	v_exp_f32_e32 v65, v65
	v_sub_f32_e32 v85, v89, v3
	v_sub_f32_e32 v89, v91, v3
	v_sub_f32_e32 v63, v63, v3
	v_exp_f32_e32 v91, v62
	v_sub_f32_e32 v67, v67, v2
	v_exp_f32_e32 v66, v66
	v_sub_f32_e32 v72, v72, v3
	v_exp_f32_e32 v109, v63
	v_sub_f32_e32 v61, v68, v2
; DEVINL float fexp2(float x) { return __builtin_amdgcn_exp2f(x); }
; DEVINL uint32_t pk2(float a, float b) { hwf2 v = {a, b}; hwbf2 r = __builtin_convertvector(v, hwbf2); return *(uint32_t*)&r; }
; #define MMV(SRC, DT) do { __builtin_amdgcn_s_setprio(1); _Pragma("unroll") for (int c2 = 0; c2 < 2; ++c2) { o[0][DT] = mfma16(SRC[c2], pf[0][c2], o[0][DT]); o[1][DT] = mfma16(SRC[c2], pf[1][c2], o[1][DT]); } __builtin_amdgcn_s_setprio(0); } while (0)
; DEVINL void attn_item(const Params& p, int item, char* smem, int wv) {
;     ...
;         float ps = 0.f;
;         float pv[4][4];
; #pragma unroll
;         for (int kq = 0; kq < 4; ++kq)
; #pragma unroll
;           for (int j = 0; j < 4; ++j) {
;             pv[kq][j] = __uint_as_float(__float_as_uint(fexp2(s[hh][kq][j])) & (unsigned)mk[kq][j]);
;             ps += pv[kq][j];
;           }
; #pragma unroll
;         for (int c2 = 0; c2 < 2; ++c2) {
;           u32x4 pw;
;           pw[0] = pk2(pv[2 * c2][0], pv[2 * c2][1]); pw[1] = pk2(pv[2 * c2][2], pv[2 * c2][3]);
;           pw[2] = pk2(pv[2 * c2 + 1][0], pv[2 * c2 + 1][1]); pw[3] = pk2(pv[2 * c2 + 1][2], pv[2 * c2 + 1][3]);
;           pf[hh][c2] = *(bf16x8*)&pw;
;         }
;         lsum[hh] += ps;
;       }
;     }
;     LDV(vfb, 1); MMV(vfa, 0);
;     LDV(vfa, 2); MMV(vfb, 1);
;     LDV(vfb, 3); MMV(vfa, 2);
;     LDV(vfa, 4); MMV(vfb, 3);
;     LDV(vfb, 5); MMV(vfa, 4);
;     LDV(vfa, 6); MMV(vfb, 5);
;     LDV(vfb, 7); MMV(vfa, 6);
;     MMV(vfb, 7);
	v_sub_f32_e32 v62, v69, v2
	v_exp_f32_e32 v67, v67
	v_sub_f32_e32 v73, v73, v3
	v_exp_f32_e32 v72, v72
	v_exp_f32_e32 v113, v83
	v_exp_f32_e32 v125, v82
	v_sub_f32_e32 v82, v92, v2
	v_sub_f32_e32 v83, v93, v2
	v_sub_f32_e32 v63, v70, v2
	v_sub_f32_e32 v68, v71, v2
	v_exp_f32_e32 v70, v61
	v_exp_f32_e32 v71, v62
	v_and_b32_e32 v61, v0, v64
	v_and_b32_e32 v60, v0, v60
	v_and_b32_e32 v62, v97, v90
	v_sub_f32_e32 v74, v74, v3
	v_exp_f32_e32 v110, v73
	v_exp_f32_e32 v121, v80
	v_exp_f32_e32 v124, v81
	v_sub_f32_e32 v122, v76, v2
	v_sub_f32_e32 v126, v78, v2
	v_exp_f32_e32 v76, v63
	v_exp_f32_e32 v78, v68
	v_and_b32_e32 v63, v97, v65
	v_cvt_pk_bf16_f32 v68, v60, v62
	v_pk_add_f32 v[80:81], v[60:61], 0 op_sel_hi:[1,0]
	v_exp_f32_e32 v0, v82
	v_exp_f32_e32 v60, v83
	v_sub_f32_e32 v75, v75, v3
	v_exp_f32_e32 v111, v74
	v_and_b32_e32 v65, v100, v66
	v_and_b32_e32 v64, v100, v91
	v_pk_add_f32 v[80:81], v[80:81], v[62:63]
	v_exp_f32_e32 v112, v75
	v_and_b32_e32 v67, v102, v67
	v_and_b32_e32 v66, v102, v109
	v_pk_add_f32 v[80:81], v[80:81], v[64:65]
	v_sub_f32_e32 v93, v95, v2
	v_and_b32_e32 v73, v86, v70
	v_and_b32_e32 v72, v86, v72
	v_pk_add_f32 v[80:81], v[80:81], v[66:67]
	v_exp_f32_e32 v114, v85
	v_sub_f32_e32 v92, v94, v2
	v_and_b32_e32 v75, v98, v71
	v_and_b32_e32 v74, v98, v110
	v_pk_add_f32 v[80:81], v[80:81], v[72:73]
	v_and_b32_e32 v83, v87, v0
	v_and_b32_e32 v82, v87, v113
	v_and_b32_e32 v87, v99, v60
	v_exp_f32_e32 v60, v93
	v_exp_f32_e32 v88, v88
	v_sub_f32_e32 v123, v77, v2
	v_and_b32_e32 v77, v101, v76
	v_and_b32_e32 v76, v101, v111
	v_pk_add_f32 v[80:81], v[80:81], v[74:75]
	v_exp_f32_e32 v0, v92
	v_exp_f32_e32 v89, v89
	v_sub_f32_e32 v127, v79, v2
	v_and_b32_e32 v79, v103, v78
	v_and_b32_e32 v78, v103, v112
	v_pk_add_f32 v[80:81], v[80:81], v[76:77]
	v_exp_f32_e32 v62, v122
	v_pk_add_f32 v[80:81], v[80:81], v[78:79]
	v_cvt_pk_bf16_f32 v69, v64, v66
	v_and_b32_e32 v86, v99, v114
	v_exp_f32_e32 v64, v123
	v_cvt_pk_bf16_f32 v100, v61, v63
	v_cvt_pk_bf16_f32 v102, v73, v75
	v_and_b32_e32 v75, v107, v60
	v_pk_add_f32 v[60:61], v[80:81], v[82:83]
	v_cvt_pk_bf16_f32 v70, v72, v74
	v_exp_f32_e32 v66, v126
	v_and_b32_e32 v73, v105, v0
	v_and_b32_e32 v72, v105, v88
	v_pk_add_f32 v[60:61], v[60:61], v[86:87]
	v_exp_f32_e32 v90, v127
	v_and_b32_e32 v74, v107, v89
	v_pk_add_f32 v[60:61], v[60:61], v[72:73]
	v_cvt_pk_bf16_f32 v71, v76, v78
	v_cvt_pk_bf16_f32 v103, v77, v79
	v_and_b32_e32 v77, v96, v62
	v_and_b32_e32 v76, v96, v115
	v_pk_add_f32 v[60:61], v[60:61], v[74:75]
	v_and_b32_e32 v79, v104, v64
	v_and_b32_e32 v78, v104, v121
	v_pk_add_f32 v[60:61], v[60:61], v[76:77]
	v_and_b32_e32 v89, v106, v66
	v_and_b32_e32 v88, v106, v124
	v_pk_add_f32 v[60:61], v[60:61], v[78:79]
	v_and_b32_e32 v91, v108, v90
	v_and_b32_e32 v90, v108, v125
	v_pk_add_f32 v[60:61], v[60:61], v[88:89]
	s_nop 0
	v_exp_f32_e64 v84, -v3
	v_exp_f32_e64 v85, -v2
	v_cvt_pk_bf16_f32 v101, v65, v67
	v_pk_add_f32 v[80:81], v[60:61], v[90:91]
	ds_read_b128 v[60:63], v177 offset:19712
	ds_read_b128 v[64:67], v177 offset:19776
	v_pk_add_f32 v[2:3], v[2:3], 0 op_sel_hi:[1,0]
	v_pk_mul_f32 v[122:123], v[84:85], 0 op_sel_hi:[1,0]
	v_pk_fma_f32 v[160:161], v[84:85], 0, v[80:81] op_sel_hi:[1,0,1]
	v_mov_b32_e32 v126, v122
	v_mov_b32_e32 v127, v122
	v_mov_b32_e32 v128, v122
	v_mov_b32_e32 v129, v122
	v_cvt_pk_bf16_f32 v130, v82, v86
	v_cvt_pk_bf16_f32 v131, v72, v74
	v_cvt_pk_bf16_f32 v132, v76, v78
	v_cvt_pk_bf16_f32 v133, v88, v90
	v_mov_b32_e32 v122, v123
	v_mov_b32_e32 v124, v123
	v_mov_b32_e32 v125, v123
	v_cvt_pk_bf16_f32 v134, v83, v87
	v_cvt_pk_bf16_f32 v135, v73, v75
	v_cvt_pk_bf16_f32 v136, v77, v79
	v_cvt_pk_bf16_f32 v137, v89, v91
	s_waitcnt lgkmcnt(3)
	v_mfma_f32_16x16x32_bf16 v[72:75], v[52:55], v[68:71], v[126:129]
	v_mfma_f32_16x16x32_bf16 v[52:55], v[52:55], v[100:103], v[122:125]
	s_waitcnt lgkmcnt(2)
	v_mfma_f32_16x16x32_bf16 v[88:91], v[56:59], v[130:133], v[72:75]
	v_mfma_f32_16x16x32_bf16 v[52:55], v[56:59], v[134:137], v[52:55]
	s_nop 0
	s_nop 1
	ds_read_b128 v[72:75], v177 offset:22016
	ds_read_b128 v[76:79], v177 offset:22080
	s_waitcnt lgkmcnt(3)
	v_mfma_f32_16x16x32_bf16 v[56:59], v[60:63], v[68:71], v[126:129]
	v_mfma_f32_16x16x32_bf16 v[60:63], v[60:63], v[100:103], v[122:125]
	s_waitcnt lgkmcnt(2)
	v_mfma_f32_16x16x32_bf16 v[84:87], v[64:67], v[130:133], v[56:59]
	v_mfma_f32_16x16x32_bf16 v[56:59], v[64:67], v[134:137], v[60:63]
	s_nop 0
	ds_read_b128 v[64:67], v177 offset:24320
	ds_read_b128 v[80:83], v177 offset:24384
	s_waitcnt lgkmcnt(3)
	v_mfma_f32_16x16x32_bf16 v[60:63], v[72:75], v[68:71], v[126:129]
	v_mfma_f32_16x16x32_bf16 v[72:75], v[72:75], v[100:103], v[122:125]
	s_waitcnt lgkmcnt(2)
	v_mfma_f32_16x16x32_bf16 v[92:95], v[76:79], v[130:133], v[60:63]
	v_mfma_f32_16x16x32_bf16 v[60:63], v[76:79], v[134:137], v[72:75]
	s_nop 0
	s_nop 2
	ds_read_b128 v[72:75], v177 offset:26624
	ds_read_b128 v[76:79], v177 offset:26688
	s_waitcnt lgkmcnt(3)
	v_mfma_f32_16x16x32_bf16 v[96:99], v[64:67], v[68:71], v[126:129]
	v_mfma_f32_16x16x32_bf16 v[64:67], v[64:67], v[100:103], v[122:125]
	s_waitcnt lgkmcnt(2)
	v_mfma_f32_16x16x32_bf16 v[96:99], v[80:83], v[130:133], v[96:99]
	v_mfma_f32_16x16x32_bf16 v[64:67], v[80:83], v[134:137], v[64:67]
	s_nop 0
	ds_read_b128 v[80:83], v177 offset:28928
	ds_read_b128 v[112:115], v177 offset:28992
	s_waitcnt lgkmcnt(3)
	v_mfma_f32_16x16x32_bf16 v[104:107], v[72:75], v[68:71], v[126:129]
	v_mfma_f32_16x16x32_bf16 v[72:75], v[72:75], v[100:103], v[122:125]
	s_waitcnt lgkmcnt(2)
	v_mfma_f32_16x16x32_bf16 v[104:107], v[76:79], v[130:133], v[104:107]
	v_mfma_f32_16x16x32_bf16 v[72:75], v[76:79], v[134:137], v[72:75]
	s_nop 0
	ds_read_b128 v[138:141], v177 offset:31232
	ds_read_b128 v[142:145], v177 offset:31296
	s_waitcnt lgkmcnt(3)
	v_mfma_f32_16x16x32_bf16 v[76:79], v[80:83], v[68:71], v[126:129]
	v_mfma_f32_16x16x32_bf16 v[80:83], v[80:83], v[100:103], v[122:125]
	s_waitcnt lgkmcnt(2)
	v_mfma_f32_16x16x32_bf16 v[108:111], v[112:115], v[130:133], v[76:79]
	v_mfma_f32_16x16x32_bf16 v[76:79], v[112:115], v[134:137], v[80:83]
	s_nop 0
	ds_read_b128 v[146:149], v177 offset:33536
	ds_read_b128 v[150:153], v177 offset:33600
	s_waitcnt lgkmcnt(3)
	v_mfma_f32_16x16x32_bf16 v[80:83], v[138:141], v[68:71], v[126:129]
	v_mfma_f32_16x16x32_bf16 v[138:141], v[138:141], v[100:103], v[122:125]
	s_waitcnt lgkmcnt(2)
	v_mfma_f32_16x16x32_bf16 v[112:115], v[142:145], v[130:133], v[80:83]
	v_mfma_f32_16x16x32_bf16 v[80:83], v[142:145], v[134:137], v[138:141]
	s_waitcnt lgkmcnt(1)
	v_mfma_f32_16x16x32_bf16 v[68:71], v[146:149], v[68:71], v[126:129]
	v_mfma_f32_16x16x32_bf16 v[122:125], v[146:149], v[100:103], v[122:125]
	s_waitcnt lgkmcnt(0)
	v_mfma_f32_16x16x32_bf16 v[100:103], v[150:153], v[130:133], v[68:71]
	v_mfma_f32_16x16x32_bf16 v[68:71], v[150:153], v[134:137], v[122:125]
	s_cbranch_execz .LBB0_705
	s_branch .LBB0_706

; DEVINL void attn_item(const Params& p, int item, char* smem, int wv) {
;     ...
;   for (int kt = 0; kt < ntile; ++kt) {
; #pragma unroll
;     for (int i = 0; i < 2; ++i) {
;       *(u32x4*)(Ks + ((tid >> 4) + 32 * i) * 136 + (tid & 15) * 8) = rk[i];
;       *(u32x4*)(Vs + ((tid >> 3) + 64 * i) * 72 + (tid & 7) * 8) = rv[i];
;     }
;     __syncthreads();
;     if (kt + 1 < ntile) {
; #pragma unroll
;       for (int i = 0; i < 2; ++i) {
;         rk[i] = *(const u32x4*)(kg + (size_t)((kt + 1) * 64 + 32 * i) * HS);
;         rv[i] = *(const u32x4*)(vg + (size_t)(64 * i) * SEQ + (kt + 1) * 64);
;       }
;     }
;     const unsigned long long mw = mw_next;
;     if (kt + 1 < ntile) mw_next = bits[qtok * 64 + kt + 1];
.LBB0_707:
	s_add_i32 s8, s7, 0x41
	s_cmp_ge_u32 s8, s0
	ds_write_b128 v172, v[36:39]
	ds_write_b64 v173, v[40:41] offset:17408
	ds_write_b64 v173, v[42:43] offset:17424
	ds_write_b128 v172, v[44:47] offset:8704
	ds_write_b64 v173, v[48:49] offset:26624
	ds_write_b64 v173, v[50:51] offset:26640
	s_waitcnt lgkmcnt(0)
	s_barrier
	s_cbranch_scc1 .LBB0_709
	s_sub_i32 s8, s6, 32
	v_lshl_add_u64 v[44:45], s[8:9], 1, v[158:159]
	v_add_co_u32_e32 v48, vcc, 0x80000, v44
	v_mad_u64_u32 v[36:37], s[30:31], s8, v171, v[164:165]
	v_mad_u64_u32 v[46:47], s[30:31], s6, v171, v[164:165]
	v_addc_co_u32_e32 v49, vcc, 0, v45, vcc
	global_load_dwordx4 v[36:39], v[36:37], off
	s_nop 0
	global_load_dwordx4 v[40:43], v[44:45], off
	s_nop 0
	global_load_dwordx4 v[44:47], v[46:47], off
	s_nop 0
	global_load_dwordx4 v[48:51], v[48:49], off
	s_nop 0
	global_load_dwordx2 v[168:169], v[166:167], off
; DEVINL float fexp2(float x) { return __builtin_amdgcn_exp2f(x); }
; #define LDK(DST, KQ) _Pragma("unroll") for (int kc = 0; kc < 4; ++kc) DST[kc] = *(const bf16x8*)(Ks + ((KQ) * 16 + fr) * 136 + kc * 32 + fq * 8)
; DEVINL void attn_item(const Params& p, int item, char* smem, int wv) {
;     ...
;     if (kt * 64 <= qlast) {
;     f32x4 s[2][4];
;     bf16x8 kfa[4], kfb[4];
;     bf16x8 vfa[2], vfb[2];
;     ...
;     LDK(kfa, 0);
;     LDK(kfb, 1); MMS(kfa, 0);
;     LDK(kfa, 2); MMS(kfb, 1);
;     LDK(kfb, 3); MMS(kfa, 2);
;     LDV(vfa, 0); MMS(kfb, 3);
;     bf16x8 pf[2][2];
;     {
;       const unsigned long long msh = mw >> (fq * 4);
;       const int mlo = (int)(unsigned)msh, mhi = (int)(unsigned)(msh >> 32);
;       int mk[4][4];
; #pragma unroll
;       for (int j = 0; j < 4; ++j) {
;         mk[0][j] = __builtin_amdgcn_sbfe(mlo, j, 1); mk[1][j] = __builtin_amdgcn_sbfe(mlo, 16 + j, 1);
;         mk[2][j] = __builtin_amdgcn_sbfe(mhi, j, 1); mk[3][j] = __builtin_amdgcn_sbfe(mhi, 16 + j, 1);
;       }
; #pragma unroll
;       for (int hh = 0; hh < 2; ++hh) {
;         float mx = s[hh][0][0];
; #pragma unroll
;         for (int kq = 0; kq < 4; ++kq)
; #pragma unroll
;           for (int j = 0; j < 4; ++j) mx = fmaxf(mx, s[hh][kq][j]);
;         {
;           auto r1 = __builtin_amdgcn_permlane16_swap(__float_as_uint(mx), __float_as_uint(mx), false, false);
;           mx = fmaxf(__uint_as_float(r1[0]), __uint_as_float(r1[1]));
;           auto r2 = __builtin_amdgcn_permlane32_swap(__float_as_uint(mx), __float_as_uint(mx), false, false);
;           mx = fmaxf(__uint_as_float(r2[0]), __uint_as_float(r2[1]));
;         }
;         if (kt == 0 || __ballot(mx > 8.f)) {
;           const float delta = (kt == 0) ? mx : fmaxf(mx, 0.f);
;           const float alpha = fexp2(-delta);
;           mrun[hh] += delta;
;           lsum[hh] *= alpha;
; #pragma unroll
;           for (int dt = 0; dt < 8; ++dt) o[hh][dt] *= alpha;
; #pragma unroll
;           for (int kq = 0; kq < 4; ++kq)
; #pragma unroll
;             for (int j = 0; j < 4; ++j) s[hh][kq][j] -= delta;
.LBB0_709:
	s_add_i32 s8, s6, 0xffffffa0
	s_cmp_gt_i32 s8, s1
	s_cbranch_scc1 .LBB0_715
	ds_read_b128 v[116:119], v175
	ds_read_b128 v[120:123], v175 offset:64
	ds_read_b128 v[124:127], v175 offset:128
	ds_read_b128 v[128:131], v175 offset:192
	ds_read_b128 v[132:135], v175 offset:4352
	ds_read_b128 v[140:143], v175 offset:4416
	ds_read_b128 v[144:147], v175 offset:4480
	ds_read_b128 v[178:181], v175 offset:4544
	v_xor_b32_e32 v182, 0x80000000, v3
	v_xor_b32_e32 v186, 0x80000000, v2
	v_mov_b32_e32 v183, v182
	v_mov_b32_e32 v184, v182
	v_mov_b32_e32 v185, v182
	v_mov_b32_e32 v187, v186
	v_mov_b32_e32 v188, v186
	v_mov_b32_e32 v189, v186
	s_waitcnt lgkmcnt(7)
	v_mfma_f32_16x16x32_bf16 v[136:139], v[116:119], v[32:35], v[182:185]
	v_mfma_f32_16x16x32_bf16 v[116:119], v[116:119], v[16:19], v[186:189]
	s_waitcnt lgkmcnt(6)
	v_mfma_f32_16x16x32_bf16 v[136:139], v[120:123], v[4:7], v[136:139]
	v_mfma_f32_16x16x32_bf16 v[116:119], v[120:123], v[20:23], v[116:119]
	s_waitcnt lgkmcnt(5)
	v_mfma_f32_16x16x32_bf16 v[120:123], v[124:127], v[8:11], v[136:139]
	v_mfma_f32_16x16x32_bf16 v[116:119], v[124:127], v[24:27], v[116:119]
	s_waitcnt lgkmcnt(4)
	v_mfma_f32_16x16x32_bf16 v[152:155], v[128:131], v[12:15], v[120:123]
	v_mfma_f32_16x16x32_bf16 v[136:139], v[128:131], v[28:31], v[116:119]
	s_nop 3
	ds_read_b128 v[116:119], v175 offset:8704
	ds_read_b128 v[120:123], v175 offset:8768
	ds_read_b128 v[124:127], v175 offset:8832
	ds_read_b128 v[128:131], v175 offset:8896
	s_waitcnt lgkmcnt(7)
	v_mfma_f32_16x16x32_bf16 v[148:151], v[132:135], v[32:35], v[182:185]
	v_mfma_f32_16x16x32_bf16 v[132:135], v[132:135], v[16:19], v[186:189]
	s_waitcnt lgkmcnt(6)
	v_mfma_f32_16x16x32_bf16 v[148:151], v[140:143], v[4:7], v[148:151]
	v_mfma_f32_16x16x32_bf16 v[132:135], v[140:143], v[20:23], v[132:135]
	s_waitcnt lgkmcnt(5)
	v_mfma_f32_16x16x32_bf16 v[140:143], v[144:147], v[8:11], v[148:151]
	v_mfma_f32_16x16x32_bf16 v[132:135], v[144:147], v[24:27], v[132:135]
	s_waitcnt lgkmcnt(4)
	v_mfma_f32_16x16x32_bf16 v[148:151], v[178:181], v[12:15], v[140:143]
	v_mfma_f32_16x16x32_bf16 v[132:135], v[178:181], v[28:31], v[132:135]
	ds_read_b128 v[144:147], v175 offset:13056
	ds_read_b128 v[178:181], v175 offset:13120
	ds_read_b128 v[190:193], v175 offset:13184
	ds_read_b128 v[194:197], v175 offset:13248
	s_waitcnt lgkmcnt(7)
	v_mfma_f32_16x16x32_bf16 v[140:143], v[116:119], v[32:35], v[182:185]
	v_mfma_f32_16x16x32_bf16 v[116:119], v[116:119], v[16:19], v[186:189]
	s_waitcnt lgkmcnt(6)
	v_mfma_f32_16x16x32_bf16 v[140:143], v[120:123], v[4:7], v[140:143]
	v_mfma_f32_16x16x32_bf16 v[116:119], v[120:123], v[20:23], v[116:119]
	s_waitcnt lgkmcnt(5)
	v_mfma_f32_16x16x32_bf16 v[120:123], v[124:127], v[8:11], v[140:143]
	v_mfma_f32_16x16x32_bf16 v[116:119], v[124:127], v[24:27], v[116:119]
	s_waitcnt lgkmcnt(4)
	v_mfma_f32_16x16x32_bf16 v[140:143], v[128:131], v[12:15], v[120:123]
	v_mfma_f32_16x16x32_bf16 v[124:127], v[128:131], v[28:31], v[116:119]
	s_nop 2
	s_nop 0
	ds_read_b128 v[116:119], v177 offset:17408
	ds_read_b128 v[120:123], v177 offset:17472
	s_waitcnt lgkmcnt(5)
	v_mfma_f32_16x16x32_bf16 v[128:131], v[144:147], v[32:35], v[182:185]
	v_mfma_f32_16x16x32_bf16 v[144:147], v[144:147], v[16:19], v[186:189]
	s_waitcnt lgkmcnt(4)
	v_mfma_f32_16x16x32_bf16 v[128:131], v[178:181], v[4:7], v[128:131]
	v_mfma_f32_16x16x32_bf16 v[144:147], v[178:181], v[20:23], v[144:147]
	s_waitcnt lgkmcnt(3)
	v_mfma_f32_16x16x32_bf16 v[128:131], v[190:193], v[8:11], v[128:131]
	v_mfma_f32_16x16x32_bf16 v[178:181], v[190:193], v[24:27], v[144:147]
	s_waitcnt lgkmcnt(2)
	v_mfma_f32_16x16x32_bf16 v[144:147], v[194:197], v[12:15], v[128:131]
	v_mfma_f32_16x16x32_bf16 v[128:131], v[194:197], v[28:31], v[178:181]
	s_nop 3
	v_max_f32_e32 v178, v153, v153
	v_max_f32_e32 v179, v152, v152
	v_max_f32_e32 v178, v179, v178
	v_max3_f32 v178, v178, v154, v155
	v_max3_f32 v178, v178, v148, v149
	v_max3_f32 v178, v178, v150, v151
	v_max3_f32 v178, v178, v140, v141
	v_max3_f32 v178, v178, v142, v143
	v_max3_f32 v178, v178, v144, v145
	v_max3_f32 v178, v178, v146, v147
	v_mov_b32_e32 v179, v178
	s_nop 1
	v_permlane16_swap_b32_e32 v178, v179
	v_max_f32_e32 v179, v179, v179
	v_max_f32_e32 v178, v178, v178
	v_max_f32_e32 v178, v178, v179
	v_mov_b32_e32 v179, v178
	s_nop 1
	v_permlane32_swap_b32_e32 v178, v179
	v_max_f32_e32 v179, v179, v179
	v_max_f32_e32 v178, v178, v178
	v_max_f32_e32 v178, v178, v179
	v_cmp_lt_f32_e32 vcc, s25, v178
	s_cbranch_vccz .LBB0_712
	v_max_f32_e32 v178, v178, v178
	v_max_f32_e32 v178, 0, v178
	v_exp_f32_e64 v180, -v178
	v_add_f32_e32 v3, v3, v178
	v_pk_add_f32 v[152:153], v[152:153], v[178:179] op_sel_hi:[1,0] neg_lo:[0,1] neg_hi:[0,1]
	v_pk_add_f32 v[154:155], v[154:155], v[178:179] op_sel_hi:[1,0] neg_lo:[0,1] neg_hi:[0,1]
	v_mul_f32_e32 v160, v160, v180
	v_pk_mul_f32 v[90:91], v[90:91], v[180:181] op_sel_hi:[1,0]
	v_pk_mul_f32 v[88:89], v[88:89], v[180:181] op_sel_hi:[1,0]
	v_pk_mul_f32 v[86:87], v[86:87], v[180:181] op_sel_hi:[1,0]
	v_pk_mul_f32 v[84:85], v[84:85], v[180:181] op_sel_hi:[1,0]
	v_pk_mul_f32 v[94:95], v[94:95], v[180:181] op_sel_hi:[1,0]
	v_pk_mul_f32 v[92:93], v[92:93], v[180:181] op_sel_hi:[1,0]
	v_pk_mul_f32 v[98:99], v[98:99], v[180:181] op_sel_hi:[1,0]
	v_pk_mul_f32 v[96:97], v[96:97], v[180:181] op_sel_hi:[1,0]
	v_pk_mul_f32 v[106:107], v[106:107], v[180:181] op_sel_hi:[1,0]
	v_pk_mul_f32 v[104:105], v[104:105], v[180:181] op_sel_hi:[1,0]
	v_pk_mul_f32 v[110:111], v[110:111], v[180:181] op_sel_hi:[1,0]
	v_pk_mul_f32 v[108:109], v[108:109], v[180:181] op_sel_hi:[1,0]
	v_pk_mul_f32 v[114:115], v[114:115], v[180:181] op_sel_hi:[1,0]
	v_pk_mul_f32 v[112:113], v[112:113], v[180:181] op_sel_hi:[1,0]
	v_pk_mul_f32 v[102:103], v[102:103], v[180:181] op_sel_hi:[1,0]
	v_pk_mul_f32 v[100:101], v[100:101], v[180:181] op_sel_hi:[1,0]
	v_pk_add_f32 v[148:149], v[148:149], v[178:179] op_sel_hi:[1,0] neg_lo:[0,1] neg_hi:[0,1]
	v_pk_add_f32 v[150:151], v[150:151], v[178:179] op_sel_hi:[1,0] neg_lo:[0,1] neg_hi:[0,1]
	v_pk_add_f32 v[140:141], v[140:141], v[178:179] op_sel_hi:[1,0] neg_lo:[0,1] neg_hi:[0,1]
	v_pk_add_f32 v[142:143], v[142:143], v[178:179] op_sel_hi:[1,0] neg_lo:[0,1] neg_hi:[0,1]
	v_pk_add_f32 v[144:145], v[144:145], v[178:179] op_sel_hi:[1,0] neg_lo:[0,1] neg_hi:[0,1]
	v_pk_add_f32 v[146:147], v[146:147], v[178:179] op_sel_hi:[1,0] neg_lo:[0,1] neg_hi:[0,1]

; DEVINL float fexp2(float x) { return __builtin_amdgcn_exp2f(x); }
; DEVINL uint32_t pk2(float a, float b) { hwf2 v = {a, b}; hwbf2 r = __builtin_convertvector(v, hwbf2); return *(uint32_t*)&r; }
; #define MMV(SRC, DT) do { __builtin_amdgcn_s_setprio(1); _Pragma("unroll") for (int c2 = 0; c2 < 2; ++c2) { o[0][DT] = mfma16(SRC[c2], pf[0][c2], o[0][DT]); o[1][DT] = mfma16(SRC[c2], pf[1][c2], o[1][DT]); } __builtin_amdgcn_s_setprio(0); } while (0)
; DEVINL void attn_item(const Params& p, int item, char* smem, int wv) {
;     ...
;         float ps = 0.f;
;         float pv[4][4];
; #pragma unroll
;         for (int kq = 0; kq < 4; ++kq)
; #pragma unroll
;           for (int j = 0; j < 4; ++j) {
;             pv[kq][j] = __uint_as_float(__float_as_uint(fexp2(s[hh][kq][j])) & (unsigned)mk[kq][j]);
;             ps += pv[kq][j];
;           }
; #pragma unroll
;         for (int c2 = 0; c2 < 2; ++c2) {
;           u32x4 pw;
;           pw[0] = pk2(pv[2 * c2][0], pv[2 * c2][1]); pw[1] = pk2(pv[2 * c2][2], pv[2 * c2][3]);
;           pw[2] = pk2(pv[2 * c2 + 1][0], pv[2 * c2 + 1][1]); pw[3] = pk2(pv[2 * c2 + 1][2], pv[2 * c2 + 1][3]);
;           pf[hh][c2] = *(bf16x8*)&pw;
;         }
;         lsum[hh] += ps;
;       }
;     }
;     LDV(vfb, 1); MMV(vfa, 0);
.LBB0_714:
	v_exp_f32_e32 v152, v152
	v_exp_f32_e32 v153, v153
	v_lshrrev_b64 v[162:163], v174, v[162:163]
	v_exp_f32_e32 v154, v154
	v_bfe_i32 v178, v162, 0, 1
	v_exp_f32_e32 v155, v155
	v_bfe_i32 v180, v162, 1, 1
	v_and_b32_e32 v152, v178, v152
	v_exp_f32_e32 v148, v148
	v_bfe_i32 v187, v162, 2, 1
	v_and_b32_e32 v153, v180, v153
	v_add_f32_e32 v192, 0, v152
	v_exp_f32_e32 v149, v149
	v_bfe_i32 v186, v162, 3, 1
	v_add_f32_e32 v192, v192, v153
	v_and_b32_e32 v154, v187, v154
	v_exp_f32_e32 v150, v150
	v_exp_f32_e32 v141, v141
	v_bfe_i32 v182, v162, 16, 1
	v_and_b32_e32 v155, v186, v155
	v_add_f32_e32 v192, v192, v154
	v_exp_f32_e32 v151, v151
	v_exp_f32_e32 v140, v140
	v_bfe_i32 v181, v162, 17, 1
	v_add_f32_e32 v192, v192, v155
	v_and_b32_e32 v148, v182, v148
	v_bfe_i32 v183, v163, 1, 1
	v_bfe_i32 v188, v162, 19, 1
	v_bfe_i32 v162, v162, 18, 1
	v_and_b32_e32 v149, v181, v149
	v_add_f32_e32 v192, v192, v148
	v_bfe_i32 v179, v163, 0, 1
	v_add_f32_e32 v192, v192, v149
	v_and_b32_e32 v150, v162, v150
	v_and_b32_e32 v193, v183, v141
	v_exp_f32_e32 v141, v142
	v_and_b32_e32 v151, v188, v151
	v_add_f32_e32 v192, v192, v150
	v_and_b32_e32 v194, v179, v140
	v_exp_f32_e32 v140, v143
	v_add_f32_e32 v192, v192, v151
	v_bfe_i32 v190, v163, 2, 1
	v_add_f32_e32 v142, v192, v194
	v_bfe_i32 v189, v163, 3, 1
	v_add_f32_e32 v142, v142, v193
	v_and_b32_e32 v195, v190, v141
	v_and_b32_e32 v192, v189, v140
	v_add_f32_e32 v140, v142, v195
	v_exp_f32_e32 v141, v144
	v_add_f32_e32 v196, v140, v192
	v_exp_f32_e32 v140, v145
	v_exp_f32_e32 v142, v147
	v_exp_f32_e32 v143, v146
	v_bfe_i32 v185, v163, 16, 1
	v_bfe_i32 v184, v163, 17, 1
	v_bfe_i32 v191, v163, 19, 1
	v_and_b32_e32 v198, v185, v141
	v_exp_f32_e32 v136, v136
	v_bfe_i32 v163, v163, 18, 1
	v_and_b32_e32 v197, v184, v140
	v_and_b32_e32 v199, v191, v142
	v_cvt_pk_bf16_f32 v142, v148, v149
	v_add_f32_e32 v148, v196, v198
	v_exp_f32_e32 v137, v137
	v_and_b32_e32 v200, v163, v143
	v_add_f32_e32 v148, v148, v197
	v_exp_f32_e32 v138, v138
	v_add_f32_e32 v148, v148, v200
	v_exp_f32_e32 v139, v139
	v_add_f32_e32 v148, v148, v199
	v_and_b32_e32 v136, v178, v136
	v_exp_f32_e32 v132, v132
	v_add_f32_e32 v160, v160, v148
	v_and_b32_e32 v137, v180, v137
	v_add_f32_e32 v148, 0, v136
	v_exp_f32_e32 v133, v133
	v_add_f32_e32 v148, v148, v137
	v_and_b32_e32 v138, v187, v138
	v_exp_f32_e32 v134, v134
	v_exp_f32_e32 v125, v125
	v_and_b32_e32 v139, v186, v139
	v_add_f32_e32 v148, v148, v138
	v_exp_f32_e32 v135, v135
	v_exp_f32_e32 v124, v124
	v_add_f32_e32 v148, v148, v139
	v_and_b32_e32 v132, v182, v132
	v_and_b32_e32 v133, v181, v133
	v_add_f32_e32 v148, v148, v132
	v_add_f32_e32 v148, v148, v133
	v_and_b32_e32 v134, v162, v134
	v_and_b32_e32 v149, v183, v125
	v_exp_f32_e32 v125, v126
	v_cvt_pk_bf16_f32 v143, v150, v151
	v_and_b32_e32 v135, v188, v135
	v_add_f32_e32 v148, v148, v134
	v_and_b32_e32 v150, v179, v124
	v_exp_f32_e32 v124, v127
	v_add_f32_e32 v148, v148, v135
	v_add_f32_e32 v126, v148, v150
	v_add_f32_e32 v126, v126, v149
	v_and_b32_e32 v151, v190, v125
	v_and_b32_e32 v148, v189, v124
	v_add_f32_e32 v124, v126, v151
	v_cvt_pk_bf16_f32 v140, v152, v153
	v_add_f32_e32 v152, v124, v148
	v_exp_f32_e32 v124, v129
	v_exp_f32_e32 v125, v128
	v_exp_f32_e32 v126, v131
	v_exp_f32_e32 v127, v130
	v_cvt_pk_bf16_f32 v141, v154, v155
	v_and_b32_e32 v153, v184, v124
	v_and_b32_e32 v154, v185, v125
	v_cvt_pk_bf16_f32 v124, v136, v137
	s_nop 0
	v_and_b32_e32 v155, v191, v126
	v_and_b32_e32 v162, v163, v127
	v_cvt_pk_bf16_f32 v125, v138, v139
	v_cvt_pk_bf16_f32 v126, v132, v133
	v_cvt_pk_bf16_f32 v127, v134, v135
	v_cvt_pk_bf16_f32 v129, v151, v148
	v_add_f32_e32 v148, v152, v154
	ds_read_b128 v[132:135], v177 offset:19712
	ds_read_b128 v[136:139], v177 offset:19776
	v_add_f32_e32 v148, v148, v153
	v_add_f32_e32 v148, v148, v162
	v_add_f32_e32 v148, v148, v155
	v_add_f32_e32 v161, v161, v148
	v_cvt_pk_bf16_f32 v144, v194, v193
	v_cvt_pk_bf16_f32 v145, v195, v192
	v_cvt_pk_bf16_f32 v146, v198, v197
	v_cvt_pk_bf16_f32 v147, v200, v199
	v_cvt_pk_bf16_f32 v128, v150, v149
	v_cvt_pk_bf16_f32 v130, v154, v153
	v_cvt_pk_bf16_f32 v131, v162, v155
	s_waitcnt lgkmcnt(3)
; #define MMV(SRC, DT) do { __builtin_amdgcn_s_setprio(1); _Pragma("unroll") for (int c2 = 0; c2 < 2; ++c2) { o[0][DT] = mfma16(SRC[c2], pf[0][c2], o[0][DT]); o[1][DT] = mfma16(SRC[c2], pf[1][c2], o[1][DT]); } __builtin_amdgcn_s_setprio(0); } while (0)
; DEVINL void attn_item(const Params& p, int item, char* smem, int wv) {
;     ...
;     LDV(vfb, 1); MMV(vfa, 0);
;     LDV(vfa, 2); MMV(vfb, 1);
;     LDV(vfb, 3); MMV(vfa, 2);
;     LDV(vfa, 4); MMV(vfb, 3);
;     LDV(vfb, 5); MMV(vfa, 4);
;     LDV(vfa, 6); MMV(vfb, 5);
;     LDV(vfb, 7); MMV(vfa, 6);
;     MMV(vfb, 7);
	v_mfma_f32_16x16x32_bf16 v[88:91], v[116:119], v[140:143], v[88:91]
	v_mfma_f32_16x16x32_bf16 v[52:55], v[116:119], v[124:127], v[52:55]
	s_waitcnt lgkmcnt(2)
	v_mfma_f32_16x16x32_bf16 v[88:91], v[120:123], v[144:147], v[88:91]
	v_mfma_f32_16x16x32_bf16 v[52:55], v[120:123], v[128:131], v[52:55]
	s_nop 0
	ds_read_b128 v[116:119], v177 offset:22016
	ds_read_b128 v[120:123], v177 offset:22080
	s_waitcnt lgkmcnt(3)
	v_mfma_f32_16x16x32_bf16 v[84:87], v[132:135], v[140:143], v[84:87]
	v_mfma_f32_16x16x32_bf16 v[56:59], v[132:135], v[124:127], v[56:59]
	s_waitcnt lgkmcnt(2)
	v_mfma_f32_16x16x32_bf16 v[84:87], v[136:139], v[144:147], v[84:87]
	v_mfma_f32_16x16x32_bf16 v[56:59], v[136:139], v[128:131], v[56:59]
	s_nop 0
	ds_read_b128 v[132:135], v177 offset:24320
	ds_read_b128 v[136:139], v177 offset:24384
	s_waitcnt lgkmcnt(3)
	v_mfma_f32_16x16x32_bf16 v[92:95], v[116:119], v[140:143], v[92:95]
	v_mfma_f32_16x16x32_bf16 v[60:63], v[116:119], v[124:127], v[60:63]
	s_waitcnt lgkmcnt(2)
	v_mfma_f32_16x16x32_bf16 v[92:95], v[120:123], v[144:147], v[92:95]
	v_mfma_f32_16x16x32_bf16 v[60:63], v[120:123], v[128:131], v[60:63]
	s_nop 0
	ds_read_b128 v[116:119], v177 offset:26624
	ds_read_b128 v[120:123], v177 offset:26688
	s_waitcnt lgkmcnt(3)
	v_mfma_f32_16x16x32_bf16 v[96:99], v[132:135], v[140:143], v[96:99]
	v_mfma_f32_16x16x32_bf16 v[64:67], v[132:135], v[124:127], v[64:67]
	s_waitcnt lgkmcnt(2)
	v_mfma_f32_16x16x32_bf16 v[96:99], v[136:139], v[144:147], v[96:99]
	v_mfma_f32_16x16x32_bf16 v[64:67], v[136:139], v[128:131], v[64:67]
	s_nop 0
	ds_read_b128 v[132:135], v177 offset:28928
	ds_read_b128 v[136:139], v177 offset:28992
	s_waitcnt lgkmcnt(3)
	v_mfma_f32_16x16x32_bf16 v[104:107], v[116:119], v[140:143], v[104:107]
	v_mfma_f32_16x16x32_bf16 v[72:75], v[116:119], v[124:127], v[72:75]
	s_waitcnt lgkmcnt(2)
	v_mfma_f32_16x16x32_bf16 v[104:107], v[120:123], v[144:147], v[104:107]
	v_mfma_f32_16x16x32_bf16 v[72:75], v[120:123], v[128:131], v[72:75]
	s_nop 0
	ds_read_b128 v[116:119], v177 offset:31232
	ds_read_b128 v[120:123], v177 offset:31296
	s_waitcnt lgkmcnt(3)
	v_mfma_f32_16x16x32_bf16 v[108:111], v[132:135], v[140:143], v[108:111]
	v_mfma_f32_16x16x32_bf16 v[76:79], v[132:135], v[124:127], v[76:79]
	s_waitcnt lgkmcnt(2)
	v_mfma_f32_16x16x32_bf16 v[108:111], v[136:139], v[144:147], v[108:111]
	v_mfma_f32_16x16x32_bf16 v[76:79], v[136:139], v[128:131], v[76:79]
	s_nop 0
	ds_read_b128 v[132:135], v177 offset:33536
	ds_read_b128 v[136:139], v177 offset:33600
	s_waitcnt lgkmcnt(3)
	v_mfma_f32_16x16x32_bf16 v[112:115], v[116:119], v[140:143], v[112:115]
	v_mfma_f32_16x16x32_bf16 v[80:83], v[116:119], v[124:127], v[80:83]
	s_waitcnt lgkmcnt(2)
	v_mfma_f32_16x16x32_bf16 v[112:115], v[120:123], v[144:147], v[112:115]
	v_mfma_f32_16x16x32_bf16 v[80:83], v[120:123], v[128:131], v[80:83]
	s_waitcnt lgkmcnt(1)
	v_mfma_f32_16x16x32_bf16 v[100:103], v[132:135], v[140:143], v[100:103]
	v_mfma_f32_16x16x32_bf16 v[68:71], v[132:135], v[124:127], v[68:71]
	s_waitcnt lgkmcnt(0)
	v_mfma_f32_16x16x32_bf16 v[100:103], v[136:139], v[144:147], v[100:103]
	v_mfma_f32_16x16x32_bf16 v[68:71], v[136:139], v[128:131], v[68:71]

; DEVINL u16 f2bf(float f) { uint32_t u = __float_as_uint(f); u += 0x7FFFu + ((u >> 16) & 1u); return (u16)(u >> 16); }
; DEVINL float bfs2f(short h) { return __uint_as_float(((uint32_t)(u16)h) << 16); }
; DEVINL void phase_conv(const Params& p, int layer, int wv) {
;     ...
; #pragma unroll 8
;       for (int i = 0; i < 32; ++i) {
;         const bf16x8 r3 = *(const bf16x8*)(src + (size_t)i * HS);
;         bf16x8 o;
; #pragma unroll
;         for (int e = 0; e < 8; ++e) {
;           float v = bias[e] + w[0][e] * bfs2f(r0[e]) + w[1][e] * bfs2f(r1[e]) + w[2][e] * bfs2f(r2[e]) + w[3][e] * bfs2f(r3[e]);
;           v = v / (1.f + __expf(-v));
;           o[e] = (short)f2bf(v);
;         }
;         *(bf16x8*)(xc + (size_t)(tokA + i) * 1536 + ch0) = o;
;         r0 = r1; r1 = r2; r2 = r3;
.LBB0_1477:
	v_add_co_u32_e32 v62, vcc, 0xfffef000, v42
	s_waitcnt vmcnt(0)
	v_and_b32_e32 v69, 0xffff0000, v44
	v_addc_co_u32_e32 v63, vcc, -1, v43, vcc
	global_load_dwordx4 v[90:93], v[62:63], off offset:-2048
	v_lshlrev_b32_e32 v68, 16, v44
	v_and_b32_e32 v81, 0xffff0000, v47
	v_lshlrev_b32_e32 v80, 16, v47
	v_and_b32_e32 v67, 0xffff0000, v48
	v_lshlrev_b32_e32 v66, 16, v48
	v_and_b32_e32 v65, 0xffff0000, v52
	v_lshlrev_b32_e32 v64, 16, v52
	v_and_b32_e32 v73, 0xffff0000, v45
	v_lshlrev_b32_e32 v72, 16, v45
	v_and_b32_e32 v71, 0xffff0000, v49
	v_lshlrev_b32_e32 v70, 16, v49
	v_and_b32_e32 v45, 0xffff0000, v53
	v_lshlrev_b32_e32 v44, 16, v53
	v_and_b32_e32 v53, 0xffff0000, v50
	v_lshlrev_b32_e32 v52, 16, v50
	v_and_b32_e32 v79, 0xffff0000, v51
	v_lshlrev_b32_e32 v78, 16, v51
	v_pk_fma_f32 v[68:69], v[0:1], v[68:69], v[32:33]
	v_pk_fma_f32 v[80:81], v[10:11], v[80:81], v[38:39]
	v_and_b32_e32 v49, 0xffff0000, v54
	v_lshlrev_b32_e32 v48, 16, v54
	v_and_b32_e32 v77, 0xffff0000, v55
	v_lshlrev_b32_e32 v76, 16, v55
	v_pk_fma_f32 v[96:97], v[0:1], v[66:67], v[32:33]
	v_pk_fma_f32 v[98:99], v[2:3], v[70:71], v[34:35]
	v_pk_fma_f32 v[100:101], v[8:9], v[52:53], v[36:37]
	v_pk_fma_f32 v[102:103], v[10:11], v[78:79], v[38:39]
	v_pk_fma_f32 v[112:113], v[4:5], v[66:67], v[68:69]
	v_pk_fma_f32 v[78:79], v[14:15], v[78:79], v[80:81]
	v_add_u32_e32 v41, s38, v89
	v_pk_fma_f32 v[72:73], v[2:3], v[72:73], v[34:35]
	v_pk_fma_f32 v[104:105], v[0:1], v[64:65], v[32:33]
	v_pk_fma_f32 v[110:111], v[10:11], v[76:77], v[38:39]
	v_pk_fma_f32 v[80:81], v[4:5], v[64:65], v[96:97]
	v_pk_fma_f32 v[96:97], v[6:7], v[44:45], v[98:99]
	v_pk_fma_f32 v[98:99], v[12:13], v[48:49], v[100:101]
	v_pk_fma_f32 v[100:101], v[14:15], v[76:77], v[102:103]
	v_pk_fma_f32 v[64:65], v[16:17], v[64:65], v[112:113]
	v_pk_fma_f32 v[76:77], v[26:27], v[76:77], v[78:79]
	v_and_b32_e32 v75, 0xffff0000, v46
	v_lshlrev_b32_e32 v74, 16, v46
	v_mad_i64_i32 v[94:95], s[0:1], v41, s33, v[58:59]
	v_add_u32_e32 v118, 1, v41
	v_add_u32_e32 v119, 2, v41
	v_add_u32_e32 v120, 3, v41
	v_add_u32_e32 v121, 4, v41
	v_add_u32_e32 v122, 5, v41
	v_add_u32_e32 v123, 6, v41
	v_add_u32_e32 v41, 7, v41
	v_pk_fma_f32 v[114:115], v[6:7], v[70:71], v[72:73]
	v_pk_fma_f32 v[74:75], v[8:9], v[74:75], v[36:37]
	v_pk_fma_f32 v[106:107], v[2:3], v[44:45], v[34:35]
	v_mad_i64_i32 v[62:63], s[0:1], v41, s33, v[58:59]
	v_pk_fma_f32 v[44:45], v[18:19], v[44:45], v[114:115]
	v_add_co_u32_e64 v46, s[2:3], s34, v42
	v_pk_fma_f32 v[116:117], v[12:13], v[52:53], v[74:75]
	s_nop 0
	v_addc_co_u32_e64 v47, s[2:3], -1, v43, s[2:3]
	v_pk_fma_f32 v[108:109], v[8:9], v[48:49], v[36:37]
	v_pk_fma_f32 v[48:49], v[24:25], v[48:49], v[116:117]
	v_add_co_u32_e64 v50, s[2:3], s35, v42
	v_mad_i64_i32 v[74:75], s[0:1], v118, s33, v[58:59]
	s_nop 0
	v_addc_co_u32_e64 v51, s[2:3], -1, v43, s[2:3]
	v_add_co_u32_e64 v54, s[2:3], s36, v42
	v_mad_i64_i32 v[72:73], s[0:1], v119, s33, v[58:59]
	s_nop 0
	v_addc_co_u32_e64 v55, s[2:3], -1, v43, s[2:3]
	v_add_co_u32_e64 v82, s[2:3], s27, v42
	v_mad_i64_i32 v[68:69], s[0:1], v121, s33, v[58:59]
	s_waitcnt vmcnt(0)
	v_and_b32_e32 v79, 0xffff0000, v90
	v_lshlrev_b32_e32 v78, 16, v90
	v_and_b32_e32 v113, 0xffff0000, v93
	v_lshlrev_b32_e32 v112, 16, v93
	v_pk_fma_f32 v[64:65], v[20:21], v[78:79], v[64:65]
	v_and_b32_e32 v103, 0xffff0000, v91
	v_lshlrev_b32_e32 v102, 16, v91
	v_and_b32_e32 v91, 0xffff0000, v92
	v_lshlrev_b32_e32 v90, 16, v92
	v_pk_fma_f32 v[92:93], v[30:31], v[112:113], v[76:77]
	v_mul_f32_e32 v41, 0xbfb8aa3b, v64
	v_mul_f32_e32 v77, 0xbfb8aa3b, v65
	v_pk_fma_f32 v[44:45], v[22:23], v[102:103], v[44:45]
	v_exp_f32_e32 v76, v41
	v_exp_f32_e32 v77, v77
	v_pk_fma_f32 v[80:81], v[16:17], v[78:79], v[80:81]
	v_pk_fma_f32 v[104:105], v[4:5], v[78:79], v[104:105]
	v_pk_fma_f32 v[114:115], v[0:1], v[78:79], v[32:33]
	v_mul_f32_e32 v78, 0xbfb8aa3b, v44
	v_mul_f32_e32 v79, 0xbfb8aa3b, v45
	v_pk_fma_f32 v[48:49], v[28:29], v[90:91], v[48:49]
	v_exp_f32_e32 v78, v78
	v_exp_f32_e32 v79, v79
	v_mul_f32_e32 v116, 0xbfb8aa3b, v48
	v_mul_f32_e32 v117, 0xbfb8aa3b, v49
	v_exp_f32_e32 v116, v116
	v_exp_f32_e32 v117, v117
	v_pk_add_f32 v[76:77], v[76:77], 1.0 op_sel_hi:[1,0]
	v_mul_f32_e32 v118, 0xbfb8aa3b, v92
	v_mul_f32_e32 v119, 0xbfb8aa3b, v93
	v_exp_f32_e32 v118, v118
	v_exp_f32_e32 v119, v119
	v_pk_add_f32 v[78:79], v[78:79], 1.0 op_sel_hi:[1,0]
	v_rcp_f32_e32 v135, v76
	v_addc_co_u32_e64 v83, s[2:3], -1, v43, s[2:3]
	v_mad_i64_i32 v[52:53], s[0:1], v123, s33, v[58:59]
	v_rcp_f32_e32 v136, v77
	v_add_co_u32_e64 v84, s[2:3], s28, v42
	v_pk_add_f32 v[116:117], v[116:117], 1.0 op_sel_hi:[1,0]
	v_rcp_f32_e32 v137, v78
	v_addc_co_u32_e64 v85, s[2:3], -1, v43, s[2:3]
	v_rcp_f32_e32 v138, v79
	v_add_co_u32_e64 v86, s[2:3], s29, v42
	v_pk_add_f32 v[118:119], v[118:119], 1.0 op_sel_hi:[1,0]
	v_rcp_f32_e32 v139, v116
	v_addc_co_u32_e64 v87, s[2:3], -1, v43, s[2:3]
	v_mad_i64_i32 v[70:71], s[0:1], v120, s33, v[58:59]
	v_rcp_f32_e32 v140, v117
	v_mad_i64_i32 v[66:67], s[0:1], v122, s33, v[58:59]
	v_rcp_f32_e32 v141, v118
	v_rcp_f32_e32 v142, v119
	v_mul_f32_e32 v41, v64, v135
	s_mov_b64 vcc, s[2:3]
	v_mul_f32_e32 v64, v65, v136
	s_mov_b64 vcc, s[4:5]
	v_mul_f32_e32 v65, v44, v137
	s_mov_b64 vcc, s[6:7]
	v_mov_b32_e32 v44, v65
	v_mul_f32_e32 v65, v45, v138
	s_mov_b64 vcc, s[8:9]
	v_bfe_u32 v76, v41, 16, 1
	v_bfe_u32 v77, v64, 16, 1
	v_mov_b32_e32 v45, v65
	v_mul_f32_e32 v65, v48, v139
	s_mov_b64 vcc, s[10:11]
	v_add3_u32 v41, v41, v76, s30
	v_bfe_u32 v76, v44, 16, 1
	v_add3_u32 v64, v64, v77, s30
	v_mov_b32_e32 v48, v65
	v_mul_f32_e32 v65, v49, v140
	s_mov_b64 vcc, s[12:13]
	v_bfe_u32 v77, v45, 16, 1
	v_add3_u32 v44, v44, v76, s30
	v_perm_b32 v76, v64, v41, s31
	v_mov_b32_e32 v41, v65
	v_mul_f32_e32 v49, v92, v141
	s_mov_b64 vcc, s[14:15]
	v_add3_u32 v45, v45, v77, s30
	v_mul_f32_e32 v65, v93, v142
	v_bfe_u32 v64, v48, 16, 1
	v_bfe_u32 v78, v41, 16, 1
	v_perm_b32 v77, v45, v44, s31
	v_mov_b32_e32 v44, v65
	v_add3_u32 v48, v48, v64, s30
	v_bfe_u32 v45, v49, 16, 1
	v_add3_u32 v41, v41, v78, s30
	v_bfe_u32 v64, v44, 16, 1
	v_add3_u32 v45, v49, v45, s30
	v_perm_b32 v78, v41, v48, s31
	v_add3_u32 v41, v44, v64, s30
	v_perm_b32 v79, v41, v45, s31
	global_store_dwordx4 v[94:95], v[76:79], off
	global_load_dwordx4 v[44:47], v[46:47], off
	v_pk_fma_f32 v[98:99], v[24:25], v[90:91], v[98:99]
	v_pk_fma_f32 v[108:109], v[12:13], v[90:91], v[108:109]
	v_pk_fma_f32 v[90:91], v[8:9], v[90:91], v[36:37]
	v_pk_fma_f32 v[96:97], v[18:19], v[102:103], v[96:97]
	v_pk_fma_f32 v[100:101], v[26:27], v[112:113], v[100:101]
	v_pk_fma_f32 v[110:111], v[14:15], v[112:113], v[110:111]
	v_pk_fma_f32 v[106:107], v[6:7], v[102:103], v[106:107]
	v_pk_fma_f32 v[112:113], v[10:11], v[112:113], v[38:39]
	v_pk_fma_f32 v[102:103], v[2:3], v[102:103], v[34:35]
	s_add_i32 s38, s38, 8
	s_cmp_eq_u32 s38, 32
	s_waitcnt vmcnt(0)
; DEVINL u16 f2bf(float f) { uint32_t u = __float_as_uint(f); u += 0x7FFFu + ((u >> 16) & 1u); return (u16)(u >> 16); }
; DEVINL float bfs2f(short h) { return __uint_as_float(((uint32_t)(u16)h) << 16); }
; DEVINL void phase_conv(const Params& p, int layer, int wv) {
;     ...
; #pragma unroll 8
;       for (int i = 0; i < 32; ++i) {
;         const bf16x8 r3 = *(const bf16x8*)(src + (size_t)i * HS);
;         bf16x8 o;
; #pragma unroll
;         for (int e = 0; e < 8; ++e) {
;           float v = bias[e] + w[0][e] * bfs2f(r0[e]) + w[1][e] * bfs2f(r1[e]) + w[2][e] * bfs2f(r2[e]) + w[3][e] * bfs2f(r3[e]);
;           v = v / (1.f + __expf(-v));
;           o[e] = (short)f2bf(v);
;         }
;         *(bf16x8*)(xc + (size_t)(tokA + i) * 1536 + ch0) = o;
;         r0 = r1; r1 = r2; r2 = r3;
	v_and_b32_e32 v49, 0xffff0000, v44
	v_lshlrev_b32_e32 v48, 16, v44
	v_and_b32_e32 v65, 0xffff0000, v45
	v_lshlrev_b32_e32 v64, 16, v45
	v_and_b32_e32 v45, 0xffff0000, v46
	v_lshlrev_b32_e32 v44, 16, v46
	v_and_b32_e32 v77, 0xffff0000, v47
	v_lshlrev_b32_e32 v76, 16, v47
	v_pk_fma_f32 v[46:47], v[20:21], v[48:49], v[80:81]
	v_pk_fma_f32 v[80:81], v[28:29], v[44:45], v[98:99]
	v_pk_fma_f32 v[98:99], v[24:25], v[44:45], v[108:109]
	v_pk_fma_f32 v[90:91], v[12:13], v[44:45], v[90:91]
	v_pk_fma_f32 v[108:109], v[8:9], v[44:45], v[36:37]
	v_mul_f32_e32 v41, 0xbfb8aa3b, v46
	v_mul_f32_e32 v45, 0xbfb8aa3b, v47
	v_pk_fma_f32 v[78:79], v[22:23], v[64:65], v[96:97]
	v_exp_f32_e32 v44, v41
	v_exp_f32_e32 v45, v45
	v_pk_fma_f32 v[92:93], v[30:31], v[76:77], v[100:101]
	v_pk_fma_f32 v[100:101], v[26:27], v[76:77], v[110:111]
	v_mul_f32_e32 v110, 0xbfb8aa3b, v78
	v_mul_f32_e32 v111, 0xbfb8aa3b, v79
	v_exp_f32_e32 v110, v110
	v_exp_f32_e32 v111, v111
	v_pk_fma_f32 v[96:97], v[18:19], v[64:65], v[106:107]
	v_pk_fma_f32 v[106:107], v[14:15], v[76:77], v[112:113]
	v_mul_f32_e32 v112, 0xbfb8aa3b, v80
	v_mul_f32_e32 v113, 0xbfb8aa3b, v81
	v_exp_f32_e32 v112, v112
	v_exp_f32_e32 v113, v113
	v_pk_add_f32 v[44:45], v[44:45], 1.0 op_sel_hi:[1,0]
	v_pk_fma_f32 v[94:95], v[16:17], v[48:49], v[104:105]
	v_pk_fma_f32 v[104:105], v[4:5], v[48:49], v[114:115]
	v_mul_f32_e32 v114, 0xbfb8aa3b, v92
	v_mul_f32_e32 v115, 0xbfb8aa3b, v93
	v_exp_f32_e32 v114, v114
	v_exp_f32_e32 v115, v115
	v_pk_add_f32 v[110:111], v[110:111], 1.0 op_sel_hi:[1,0]
	v_rcp_f32_e32 v131, v44
	v_rcp_f32_e32 v132, v45
	v_pk_add_f32 v[112:113], v[112:113], 1.0 op_sel_hi:[1,0]
	v_rcp_f32_e32 v133, v110
	v_rcp_f32_e32 v134, v111
	v_pk_add_f32 v[114:115], v[114:115], 1.0 op_sel_hi:[1,0]
	v_rcp_f32_e32 v135, v112
	v_rcp_f32_e32 v136, v113
	v_rcp_f32_e32 v137, v114
	v_rcp_f32_e32 v138, v115
	v_mul_f32_e32 v41, v46, v131
	s_mov_b64 vcc, s[2:3]
	v_mul_f32_e32 v44, v47, v132
	s_mov_b64 vcc, s[4:5]
	v_mul_f32_e32 v45, v78, v133
	s_mov_b64 vcc, s[6:7]
	v_bfe_u32 v46, v41, 16, 1
	v_mul_f32_e32 v47, v79, v134
	s_mov_b64 vcc, s[8:9]
	v_bfe_u32 v78, v44, 16, 1
	v_add3_u32 v41, v41, v46, s30
	v_mov_b32_e32 v46, v47
	v_mul_f32_e32 v47, v80, v135
	s_mov_b64 vcc, s[10:11]
	v_add3_u32 v44, v44, v78, s30
	v_mul_f32_e32 v78, v81, v136
	s_mov_b64 vcc, s[12:13]
	v_bfe_u32 v79, v45, 16, 1
	v_bfe_u32 v80, v46, 16, 1
	v_perm_b32 v44, v44, v41, s31
	v_mov_b32_e32 v41, v78
	v_mul_f32_e32 v78, v92, v137
	s_mov_b64 vcc, s[14:15]
	v_add3_u32 v45, v45, v79, s30
	v_bfe_u32 v79, v47, 16, 1
	v_add3_u32 v46, v46, v80, s30
	v_mul_f32_e32 v80, v93, v138
	v_bfe_u32 v81, v41, 16, 1
	v_add3_u32 v47, v47, v79, s30
	v_mov_b32_e32 v79, v80
	v_perm_b32 v45, v46, v45, s31
	v_bfe_u32 v46, v78, 16, 1
	v_add3_u32 v41, v41, v81, s30
	v_bfe_u32 v80, v79, 16, 1
	v_add3_u32 v78, v78, v46, s30
	v_perm_b32 v46, v41, v47, s31
	v_add3_u32 v41, v79, v80, s30
	v_perm_b32 v47, v41, v78, s31
	global_store_dwordx4 v[74:75], v[44:47], off
	global_load_dwordx4 v[44:47], v[50:51], off offset:-2048
	v_pk_fma_f32 v[102:103], v[6:7], v[64:65], v[102:103]
	v_pk_fma_f32 v[48:49], v[0:1], v[48:49], v[32:33]
	v_pk_fma_f32 v[64:65], v[2:3], v[64:65], v[34:35]
	v_pk_fma_f32 v[76:77], v[10:11], v[76:77], v[38:39]
	s_waitcnt vmcnt(0)
	v_and_b32_e32 v51, 0xffff0000, v44
	v_lshlrev_b32_e32 v50, 16, v44
	v_and_b32_e32 v75, 0xffff0000, v45
	v_lshlrev_b32_e32 v74, 16, v45
	v_and_b32_e32 v45, 0xffff0000, v46
	v_lshlrev_b32_e32 v44, 16, v46
	v_and_b32_e32 v79, 0xffff0000, v47
	v_lshlrev_b32_e32 v78, 16, v47
	v_pk_fma_f32 v[46:47], v[20:21], v[50:51], v[94:95]
	v_pk_fma_f32 v[80:81], v[22:23], v[74:75], v[96:97]
	v_pk_fma_f32 v[92:93], v[28:29], v[44:45], v[98:99]
	v_pk_fma_f32 v[96:97], v[16:17], v[50:51], v[104:105]
	v_pk_fma_f32 v[98:99], v[18:19], v[74:75], v[102:103]
	v_pk_fma_f32 v[90:91], v[24:25], v[44:45], v[90:91]
	v_pk_fma_f32 v[102:103], v[12:13], v[44:45], v[108:109]
	v_pk_fma_f32 v[104:105], v[8:9], v[44:45], v[36:37]
	v_mul_f32_e32 v41, 0xbfb8aa3b, v46
	v_mul_f32_e32 v45, 0xbfb8aa3b, v47
	v_exp_f32_e32 v44, v41
	v_exp_f32_e32 v45, v45
	v_pk_fma_f32 v[94:95], v[30:31], v[78:79], v[100:101]
	v_pk_fma_f32 v[100:101], v[26:27], v[78:79], v[106:107]
	v_mul_f32_e32 v106, 0xbfb8aa3b, v80
	v_mul_f32_e32 v107, 0xbfb8aa3b, v81
	v_exp_f32_e32 v106, v106
	v_exp_f32_e32 v107, v107
	v_mul_f32_e32 v108, 0xbfb8aa3b, v92
	v_mul_f32_e32 v109, 0xbfb8aa3b, v93
	v_exp_f32_e32 v108, v108
	v_exp_f32_e32 v109, v109
	v_pk_add_f32 v[44:45], v[44:45], 1.0 op_sel_hi:[1,0]
	v_mul_f32_e32 v110, 0xbfb8aa3b, v94
	v_mul_f32_e32 v111, 0xbfb8aa3b, v95
	v_exp_f32_e32 v110, v110
	v_exp_f32_e32 v111, v111
	v_pk_add_f32 v[106:107], v[106:107], 1.0 op_sel_hi:[1,0]
	v_rcp_f32_e32 v127, v44
	v_rcp_f32_e32 v128, v45
	v_pk_add_f32 v[108:109], v[108:109], 1.0 op_sel_hi:[1,0]
	v_rcp_f32_e32 v129, v106
	v_rcp_f32_e32 v130, v107
	v_pk_add_f32 v[110:111], v[110:111], 1.0 op_sel_hi:[1,0]
	v_rcp_f32_e32 v131, v108
	v_rcp_f32_e32 v132, v109
	v_rcp_f32_e32 v133, v110
	v_rcp_f32_e32 v134, v111
	v_mul_f32_e32 v41, v46, v127
	s_mov_b64 vcc, s[2:3]
	v_mul_f32_e32 v44, v47, v128
	s_mov_b64 vcc, s[4:5]
	v_mul_f32_e32 v45, v80, v129
	s_mov_b64 vcc, s[6:7]
	v_bfe_u32 v46, v41, 16, 1
	v_mul_f32_e32 v47, v81, v130
	s_mov_b64 vcc, s[8:9]
	v_bfe_u32 v80, v44, 16, 1
	v_add3_u32 v41, v41, v46, s30
	v_mov_b32_e32 v46, v47
	v_mul_f32_e32 v47, v92, v131
	s_mov_b64 vcc, s[10:11]
	v_add3_u32 v44, v44, v80, s30
	v_mul_f32_e32 v80, v93, v132
	s_mov_b64 vcc, s[12:13]
	v_bfe_u32 v81, v45, 16, 1
	v_bfe_u32 v92, v46, 16, 1
	v_perm_b32 v44, v44, v41, s31
	v_mov_b32_e32 v41, v80
	v_mul_f32_e32 v80, v94, v133
	s_mov_b64 vcc, s[14:15]
	v_add3_u32 v45, v45, v81, s30
	v_bfe_u32 v81, v47, 16, 1
	v_add3_u32 v46, v46, v92, s30
	v_mul_f32_e32 v92, v95, v134
	v_bfe_u32 v93, v41, 16, 1
	v_add3_u32 v47, v47, v81, s30
	v_mov_b32_e32 v81, v92
	v_perm_b32 v45, v46, v45, s31
	v_bfe_u32 v46, v80, 16, 1
	v_add3_u32 v41, v41, v93, s30
	v_bfe_u32 v92, v81, 16, 1
	v_add3_u32 v80, v80, v46, s30
	v_perm_b32 v46, v41, v47, s31
	v_add3_u32 v41, v81, v92, s30
	v_perm_b32 v47, v41, v80, s31
	global_store_dwordx4 v[72:73], v[44:47], off
	global_load_dwordx4 v[44:47], v[54:55], off
	v_pk_fma_f32 v[48:49], v[4:5], v[50:51], v[48:49]
	v_pk_fma_f32 v[64:65], v[6:7], v[74:75], v[64:65]
	v_pk_fma_f32 v[76:77], v[14:15], v[78:79], v[76:77]
	v_pk_fma_f32 v[50:51], v[0:1], v[50:51], v[32:33]
	v_pk_fma_f32 v[74:75], v[2:3], v[74:75], v[34:35]
	v_pk_fma_f32 v[78:79], v[10:11], v[78:79], v[38:39]
	s_waitcnt vmcnt(0)
; DEVINL u16 f2bf(float f) { uint32_t u = __float_as_uint(f); u += 0x7FFFu + ((u >> 16) & 1u); return (u16)(u >> 16); }
; DEVINL float bfs2f(short h) { return __uint_as_float(((uint32_t)(u16)h) << 16); }
; DEVINL void phase_conv(const Params& p, int layer, int wv) {
;     ...
;     for (int run = blockIdx.x * 2 + half; run < T_TOK / 32; run += gridDim.x * 2) {
;       const int tokA = run * 32;
;       const int l0 = tokA & 4095;
;       const u16* src = hb + (size_t)tokA * HS + 1024 + ch0;
;       bf16x8 r0, r1, r2;
;       const bf16x8 zero8 = {0, 0, 0, 0, 0, 0, 0, 0};
;       r0 = (l0 >= 3) ? *(const bf16x8*)(src - 3 * (long)HS) : zero8;
;       r1 = (l0 >= 2) ? *(const bf16x8*)(src - 2 * (long)HS) : zero8;
;       r2 = (l0 >= 1) ? *(const bf16x8*)(src - 1 * (long)HS) : zero8;
; #pragma unroll 8
;       for (int i = 0; i < 32; ++i) {
;         const bf16x8 r3 = *(const bf16x8*)(src + (size_t)i * HS);
;         bf16x8 o;
; #pragma unroll
;         for (int e = 0; e < 8; ++e) {
;           float v = bias[e] + w[0][e] * bfs2f(r0[e]) + w[1][e] * bfs2f(r1[e]) + w[2][e] * bfs2f(r2[e]) + w[3][e] * bfs2f(r3[e]);
;           v = v / (1.f + __expf(-v));
;           o[e] = (short)f2bf(v);
;         }
;         *(bf16x8*)(xc + (size_t)(tokA + i) * 1536 + ch0) = o;
;         r0 = r1; r1 = r2; r2 = r3;
;       }
	v_and_b32_e32 v55, 0xffff0000, v44
	v_lshlrev_b32_e32 v54, 16, v44
	v_and_b32_e32 v73, 0xffff0000, v45
	v_lshlrev_b32_e32 v72, 16, v45
	v_and_b32_e32 v45, 0xffff0000, v46
	v_lshlrev_b32_e32 v44, 16, v46
	v_and_b32_e32 v81, 0xffff0000, v47
	v_lshlrev_b32_e32 v80, 16, v47
	v_pk_fma_f32 v[46:47], v[20:21], v[54:55], v[96:97]
	v_pk_fma_f32 v[92:93], v[22:23], v[72:73], v[98:99]
	v_pk_fma_f32 v[90:91], v[28:29], v[44:45], v[90:91]
	v_pk_fma_f32 v[94:95], v[30:31], v[80:81], v[100:101]
	v_pk_fma_f32 v[96:97], v[24:25], v[44:45], v[102:103]
	v_pk_fma_f32 v[98:99], v[12:13], v[44:45], v[104:105]
	v_pk_fma_f32 v[100:101], v[8:9], v[44:45], v[36:37]
	v_mul_f32_e32 v41, 0xbfb8aa3b, v46
	v_mul_f32_e32 v45, 0xbfb8aa3b, v47
	v_exp_f32_e32 v44, v41
	v_exp_f32_e32 v45, v45
	v_mul_f32_e32 v102, 0xbfb8aa3b, v92
	v_mul_f32_e32 v103, 0xbfb8aa3b, v93
	v_exp_f32_e32 v102, v102
	v_exp_f32_e32 v103, v103
	v_mul_f32_e32 v104, 0xbfb8aa3b, v90
	v_mul_f32_e32 v105, 0xbfb8aa3b, v91
	v_exp_f32_e32 v104, v104
	v_exp_f32_e32 v105, v105
	v_pk_add_f32 v[44:45], v[44:45], 1.0 op_sel_hi:[1,0]
	v_mul_f32_e32 v106, 0xbfb8aa3b, v94
	v_mul_f32_e32 v107, 0xbfb8aa3b, v95
	v_exp_f32_e32 v106, v106
	v_exp_f32_e32 v107, v107
	v_pk_add_f32 v[102:103], v[102:103], 1.0 op_sel_hi:[1,0]
	v_rcp_f32_e32 v123, v44
	v_rcp_f32_e32 v124, v45
	v_pk_add_f32 v[104:105], v[104:105], 1.0 op_sel_hi:[1,0]
	v_rcp_f32_e32 v125, v102
	v_rcp_f32_e32 v126, v103
	v_pk_add_f32 v[106:107], v[106:107], 1.0 op_sel_hi:[1,0]
	v_rcp_f32_e32 v127, v104
	v_rcp_f32_e32 v128, v105
	v_rcp_f32_e32 v129, v106
	v_rcp_f32_e32 v130, v107
	v_mul_f32_e32 v41, v46, v123
	s_mov_b64 vcc, s[2:3]
	v_mul_f32_e32 v44, v47, v124
	s_mov_b64 vcc, s[4:5]
	v_mul_f32_e32 v45, v92, v125
	s_mov_b64 vcc, s[6:7]
	v_bfe_u32 v46, v41, 16, 1
	v_mul_f32_e32 v47, v93, v126
	s_mov_b64 vcc, s[8:9]
	v_bfe_u32 v92, v44, 16, 1
	v_add3_u32 v41, v41, v46, s30
	v_mov_b32_e32 v46, v47
	v_mul_f32_e32 v47, v90, v127
	s_mov_b64 vcc, s[10:11]
	v_add3_u32 v44, v44, v92, s30
	v_mul_f32_e32 v90, v91, v128
	s_mov_b64 vcc, s[12:13]
	v_bfe_u32 v92, v46, 16, 1
	v_perm_b32 v44, v44, v41, s31
	v_mov_b32_e32 v41, v90
	v_mul_f32_e32 v90, v94, v129
	s_mov_b64 vcc, s[14:15]
	v_bfe_u32 v93, v45, 16, 1
	v_bfe_u32 v91, v47, 16, 1
	v_add3_u32 v46, v46, v92, s30
	v_mul_f32_e32 v92, v95, v130
	v_add3_u32 v45, v45, v93, s30
	v_bfe_u32 v93, v41, 16, 1
	v_add3_u32 v47, v47, v91, s30
	v_mov_b32_e32 v91, v92
	v_perm_b32 v45, v46, v45, s31
	v_bfe_u32 v46, v90, 16, 1
	v_add3_u32 v41, v41, v93, s30
	v_bfe_u32 v92, v91, 16, 1
	v_add3_u32 v90, v90, v46, s30
	v_perm_b32 v46, v41, v47, s31
	v_add3_u32 v41, v91, v92, s30
	v_perm_b32 v47, v41, v90, s31
	global_store_dwordx4 v[70:71], v[44:47], off
	global_load_dwordx4 v[44:47], v[82:83], off offset:-2048
	v_pk_fma_f32 v[48:49], v[16:17], v[54:55], v[48:49]
	v_pk_fma_f32 v[64:65], v[18:19], v[72:73], v[64:65]
	v_pk_fma_f32 v[76:77], v[26:27], v[80:81], v[76:77]
	v_pk_fma_f32 v[50:51], v[4:5], v[54:55], v[50:51]
	v_pk_fma_f32 v[54:55], v[0:1], v[54:55], v[32:33]
	v_pk_fma_f32 v[74:75], v[6:7], v[72:73], v[74:75]
	v_pk_fma_f32 v[72:73], v[2:3], v[72:73], v[34:35]
	v_pk_fma_f32 v[78:79], v[14:15], v[80:81], v[78:79]
	v_pk_fma_f32 v[80:81], v[10:11], v[80:81], v[38:39]
	s_waitcnt vmcnt(0)
	v_and_b32_e32 v71, 0xffff0000, v44
	v_lshlrev_b32_e32 v70, 16, v44
	v_and_b32_e32 v83, 0xffff0000, v45
	v_lshlrev_b32_e32 v82, 16, v45
	v_and_b32_e32 v45, 0xffff0000, v46
	v_lshlrev_b32_e32 v44, 16, v46
	v_and_b32_e32 v91, 0xffff0000, v47
	v_lshlrev_b32_e32 v90, 16, v47
	v_pk_fma_f32 v[46:47], v[20:21], v[70:71], v[48:49]
	v_pk_fma_f32 v[48:49], v[22:23], v[82:83], v[64:65]
	v_pk_fma_f32 v[64:65], v[28:29], v[44:45], v[96:97]
	v_pk_fma_f32 v[92:93], v[24:25], v[44:45], v[98:99]
	v_pk_fma_f32 v[94:95], v[12:13], v[44:45], v[100:101]
	v_pk_fma_f32 v[96:97], v[8:9], v[44:45], v[36:37]
	v_mul_f32_e32 v41, 0xbfb8aa3b, v46
	v_mul_f32_e32 v45, 0xbfb8aa3b, v47
	v_exp_f32_e32 v44, v41
	v_exp_f32_e32 v45, v45
	v_mul_f32_e32 v98, 0xbfb8aa3b, v48
	v_mul_f32_e32 v99, 0xbfb8aa3b, v49
	v_exp_f32_e32 v98, v98
	v_exp_f32_e32 v99, v99
	v_mul_f32_e32 v100, 0xbfb8aa3b, v64
	v_mul_f32_e32 v101, 0xbfb8aa3b, v65
	v_pk_fma_f32 v[76:77], v[30:31], v[90:91], v[76:77]
	v_exp_f32_e32 v100, v100
	v_exp_f32_e32 v101, v101
	v_pk_add_f32 v[44:45], v[44:45], 1.0 op_sel_hi:[1,0]
	v_mul_f32_e32 v102, 0xbfb8aa3b, v76
	v_mul_f32_e32 v103, 0xbfb8aa3b, v77
	v_exp_f32_e32 v102, v102
	v_exp_f32_e32 v103, v103
	v_pk_add_f32 v[98:99], v[98:99], 1.0 op_sel_hi:[1,0]
	v_rcp_f32_e32 v119, v44
	v_rcp_f32_e32 v120, v45
	v_pk_add_f32 v[100:101], v[100:101], 1.0 op_sel_hi:[1,0]
	v_rcp_f32_e32 v121, v98
	v_rcp_f32_e32 v122, v99
	v_pk_add_f32 v[102:103], v[102:103], 1.0 op_sel_hi:[1,0]
	v_rcp_f32_e32 v123, v100
	v_rcp_f32_e32 v124, v101
	v_rcp_f32_e32 v125, v102
	v_rcp_f32_e32 v126, v103
	v_mul_f32_e32 v41, v46, v119
	s_mov_b64 vcc, s[2:3]
	v_mul_f32_e32 v44, v47, v120
	s_mov_b64 vcc, s[4:5]
	v_mul_f32_e32 v45, v48, v121
	s_mov_b64 vcc, s[6:7]
	v_bfe_u32 v46, v41, 16, 1
	v_mul_f32_e32 v47, v49, v122
	s_mov_b64 vcc, s[8:9]
	v_bfe_u32 v48, v44, 16, 1
	v_add3_u32 v41, v41, v46, s30
	v_mov_b32_e32 v46, v47
	v_mul_f32_e32 v47, v64, v123
	s_mov_b64 vcc, s[10:11]
	v_add3_u32 v44, v44, v48, s30
	v_mul_f32_e32 v48, v65, v124
	s_mov_b64 vcc, s[12:13]
	v_bfe_u32 v49, v45, 16, 1
	v_bfe_u32 v64, v46, 16, 1
	v_perm_b32 v44, v44, v41, s31
	v_mov_b32_e32 v41, v48
	v_mul_f32_e32 v48, v76, v125
	s_mov_b64 vcc, s[14:15]
	v_add3_u32 v45, v45, v49, s30
	v_bfe_u32 v49, v47, 16, 1
	v_add3_u32 v46, v46, v64, s30
	v_mul_f32_e32 v64, v77, v126
	v_bfe_u32 v65, v41, 16, 1
	v_add3_u32 v47, v47, v49, s30
	v_mov_b32_e32 v49, v64
	v_perm_b32 v45, v46, v45, s31
	v_bfe_u32 v46, v48, 16, 1
	v_add3_u32 v41, v41, v65, s30
	v_bfe_u32 v64, v49, 16, 1
	v_add3_u32 v48, v48, v46, s30
	v_perm_b32 v46, v41, v47, s31
	v_add3_u32 v41, v49, v64, s30
	v_perm_b32 v47, v41, v48, s31
	global_store_dwordx4 v[68:69], v[44:47], off
	global_load_dwordx4 v[44:47], v[84:85], off
	v_pk_fma_f32 v[50:51], v[16:17], v[70:71], v[50:51]
	v_pk_fma_f32 v[54:55], v[4:5], v[70:71], v[54:55]
	v_pk_fma_f32 v[70:71], v[0:1], v[70:71], v[32:33]
	v_pk_fma_f32 v[74:75], v[18:19], v[82:83], v[74:75]
	v_pk_fma_f32 v[72:73], v[6:7], v[82:83], v[72:73]
	v_pk_fma_f32 v[82:83], v[2:3], v[82:83], v[34:35]
	v_pk_fma_f32 v[78:79], v[26:27], v[90:91], v[78:79]
	v_pk_fma_f32 v[80:81], v[14:15], v[90:91], v[80:81]
	v_pk_fma_f32 v[90:91], v[10:11], v[90:91], v[38:39]
	s_waitcnt vmcnt(0)
; DEVINL u16 f2bf(float f) { uint32_t u = __float_as_uint(f); u += 0x7FFFu + ((u >> 16) & 1u); return (u16)(u >> 16); }
; DEVINL float bfs2f(short h) { return __uint_as_float(((uint32_t)(u16)h) << 16); }
; DEVINL void phase_conv(const Params& p, int layer, int wv) {
;     ...
;       for (int i = 0; i < 32; ++i) {
;         const bf16x8 r3 = *(const bf16x8*)(src + (size_t)i * HS);
;         bf16x8 o;
; #pragma unroll
;         for (int e = 0; e < 8; ++e) {
;           float v = bias[e] + w[0][e] * bfs2f(r0[e]) + w[1][e] * bfs2f(r1[e]) + w[2][e] * bfs2f(r2[e]) + w[3][e] * bfs2f(r3[e]);
;           v = v / (1.f + __expf(-v));
;           o[e] = (short)f2bf(v);
;         }
;         *(bf16x8*)(xc + (size_t)(tokA + i) * 1536 + ch0) = o;
;         r0 = r1; r1 = r2; r2 = r3;
	v_and_b32_e32 v49, 0xffff0000, v44
	v_lshlrev_b32_e32 v48, 16, v44
	v_pk_fma_f32 v[50:51], v[20:21], v[48:49], v[50:51]
	v_and_b32_e32 v65, 0xffff0000, v45
	v_lshlrev_b32_e32 v64, 16, v45
	v_pk_fma_f32 v[54:55], v[16:17], v[48:49], v[54:55]
	v_pk_fma_f32 v[70:71], v[4:5], v[48:49], v[70:71]
	v_mul_f32_e32 v41, 0xbfb8aa3b, v50
	v_mul_f32_e32 v49, 0xbfb8aa3b, v51
	v_pk_fma_f32 v[74:75], v[22:23], v[64:65], v[74:75]
	v_exp_f32_e32 v48, v41
	v_exp_f32_e32 v49, v49
	v_and_b32_e32 v69, 0xffff0000, v46
	v_lshlrev_b32_e32 v68, 16, v46
	v_pk_fma_f32 v[72:73], v[18:19], v[64:65], v[72:73]
	v_pk_fma_f32 v[64:65], v[6:7], v[64:65], v[82:83]
	v_mul_f32_e32 v82, 0xbfb8aa3b, v74
	v_mul_f32_e32 v83, 0xbfb8aa3b, v75
	v_and_b32_e32 v77, 0xffff0000, v47
	v_lshlrev_b32_e32 v76, 16, v47
	v_pk_fma_f32 v[84:85], v[28:29], v[68:69], v[92:93]
	v_exp_f32_e32 v82, v82
	v_exp_f32_e32 v83, v83
	v_pk_fma_f32 v[78:79], v[30:31], v[76:77], v[78:79]
	v_pk_fma_f32 v[80:81], v[26:27], v[76:77], v[80:81]
	v_pk_fma_f32 v[76:77], v[14:15], v[76:77], v[90:91]
	v_mul_f32_e32 v90, 0xbfb8aa3b, v84
	v_mul_f32_e32 v91, 0xbfb8aa3b, v85
	v_exp_f32_e32 v90, v90
	v_exp_f32_e32 v91, v91
	v_pk_add_f32 v[48:49], v[48:49], 1.0 op_sel_hi:[1,0]
	v_pk_fma_f32 v[92:93], v[24:25], v[68:69], v[94:95]
	v_mul_f32_e32 v94, 0xbfb8aa3b, v78
	v_mul_f32_e32 v95, 0xbfb8aa3b, v79
	v_pk_fma_f32 v[68:69], v[12:13], v[68:69], v[96:97]
	v_exp_f32_e32 v94, v94
	v_exp_f32_e32 v95, v95
	v_pk_add_f32 v[82:83], v[82:83], 1.0 op_sel_hi:[1,0]
	v_rcp_f32_e32 v111, v48
	v_rcp_f32_e32 v112, v49
	v_pk_add_f32 v[90:91], v[90:91], 1.0 op_sel_hi:[1,0]
	v_rcp_f32_e32 v113, v82
	v_rcp_f32_e32 v114, v83
	v_pk_add_f32 v[94:95], v[94:95], 1.0 op_sel_hi:[1,0]
	v_rcp_f32_e32 v115, v90
	v_rcp_f32_e32 v116, v91
	v_rcp_f32_e32 v117, v94
	v_rcp_f32_e32 v118, v95
	v_mul_f32_e32 v41, v50, v111
	s_mov_b64 vcc, s[2:3]
	v_mul_f32_e32 v48, v51, v112
	s_mov_b64 vcc, s[4:5]
	v_mul_f32_e32 v49, v74, v113
	s_mov_b64 vcc, s[6:7]
	v_bfe_u32 v50, v41, 16, 1
	v_mul_f32_e32 v51, v75, v114
	s_mov_b64 vcc, s[8:9]
	v_bfe_u32 v74, v48, 16, 1
	v_add3_u32 v41, v41, v50, s30
	v_mov_b32_e32 v50, v51
	v_mul_f32_e32 v51, v84, v115
	s_mov_b64 vcc, s[10:11]
	v_add3_u32 v48, v48, v74, s30
	v_mul_f32_e32 v74, v85, v116
	s_mov_b64 vcc, s[12:13]
	v_bfe_u32 v75, v49, 16, 1
	v_perm_b32 v48, v48, v41, s31
	v_mov_b32_e32 v41, v74
	v_mul_f32_e32 v74, v78, v117
	s_mov_b64 vcc, s[14:15]
	v_bfe_u32 v82, v50, 16, 1
	v_add3_u32 v49, v49, v75, s30
	v_bfe_u32 v75, v51, 16, 1
	v_mul_f32_e32 v78, v79, v118
	v_add3_u32 v50, v50, v82, s30
	v_bfe_u32 v82, v41, 16, 1
	v_add3_u32 v51, v51, v75, s30
	v_mov_b32_e32 v75, v78
	v_perm_b32 v49, v50, v49, s31
	v_bfe_u32 v50, v74, 16, 1
	v_add3_u32 v41, v41, v82, s30
	v_bfe_u32 v78, v75, 16, 1
	v_add3_u32 v74, v74, v50, s30
	v_perm_b32 v50, v41, v51, s31
	v_add3_u32 v41, v75, v78, s30
	v_perm_b32 v51, v41, v74, s31
	global_store_dwordx4 v[66:67], v[48:51], off
	global_load_dwordx4 v[48:51], v[86:87], off offset:-2048
	s_waitcnt vmcnt(0)
; DEVINL u16 f2bf(float f) { uint32_t u = __float_as_uint(f); u += 0x7FFFu + ((u >> 16) & 1u); return (u16)(u >> 16); }
; DEVINL float bfs2f(short h) { return __uint_as_float(((uint32_t)(u16)h) << 16); }
; DEVINL void phase_conv(const Params& p, int layer, int wv) {
;     ...
;     for (int run = blockIdx.x * 2 + half; run < T_TOK / 32; run += gridDim.x * 2) {
;       const int tokA = run * 32;
;       const int l0 = tokA & 4095;
;       const u16* src = hb + (size_t)tokA * HS + 1024 + ch0;
;       bf16x8 r0, r1, r2;
;       const bf16x8 zero8 = {0, 0, 0, 0, 0, 0, 0, 0};
;       r0 = (l0 >= 3) ? *(const bf16x8*)(src - 3 * (long)HS) : zero8;
;       r1 = (l0 >= 2) ? *(const bf16x8*)(src - 2 * (long)HS) : zero8;
;       r2 = (l0 >= 1) ? *(const bf16x8*)(src - 1 * (long)HS) : zero8;
; #pragma unroll 8
;       for (int i = 0; i < 32; ++i) {
;         const bf16x8 r3 = *(const bf16x8*)(src + (size_t)i * HS);
;         bf16x8 o;
; #pragma unroll
;         for (int e = 0; e < 8; ++e) {
;           float v = bias[e] + w[0][e] * bfs2f(r0[e]) + w[1][e] * bfs2f(r1[e]) + w[2][e] * bfs2f(r2[e]) + w[3][e] * bfs2f(r3[e]);
;           v = v / (1.f + __expf(-v));
;           o[e] = (short)f2bf(v);
;         }
;         *(bf16x8*)(xc + (size_t)(tokA + i) * 1536 + ch0) = o;
;         r0 = r1; r1 = r2; r2 = r3;
;       }
	v_and_b32_e32 v67, 0xffff0000, v48
	v_lshlrev_b32_e32 v66, 16, v48
	v_and_b32_e32 v75, 0xffff0000, v49
	v_lshlrev_b32_e32 v74, 16, v49
	v_pk_fma_f32 v[54:55], v[20:21], v[66:67], v[54:55]
	v_pk_fma_f32 v[72:73], v[22:23], v[74:75], v[72:73]
	v_pk_fma_f32 v[74:75], v[18:19], v[74:75], v[64:65]
	v_mul_f32_e32 v41, 0xbfb8aa3b, v54
	v_mul_f32_e32 v65, 0xbfb8aa3b, v55
	v_exp_f32_e32 v64, v41
	v_exp_f32_e32 v65, v65
	v_and_b32_e32 v79, 0xffff0000, v50
	v_lshlrev_b32_e32 v78, 16, v50
	v_pk_fma_f32 v[70:71], v[16:17], v[66:67], v[70:71]
	v_mul_f32_e32 v66, 0xbfb8aa3b, v72
	v_mul_f32_e32 v67, 0xbfb8aa3b, v73
	v_pk_fma_f32 v[84:85], v[28:29], v[78:79], v[92:93]
	v_exp_f32_e32 v66, v66
	v_exp_f32_e32 v67, v67
	v_and_b32_e32 v83, 0xffff0000, v51
	v_lshlrev_b32_e32 v82, 16, v51
	v_pk_fma_f32 v[68:69], v[24:25], v[78:79], v[68:69]
	v_mul_f32_e32 v78, 0xbfb8aa3b, v84
	v_mul_f32_e32 v79, 0xbfb8aa3b, v85
	v_pk_fma_f32 v[80:81], v[30:31], v[82:83], v[80:81]
	v_exp_f32_e32 v78, v78
	v_exp_f32_e32 v79, v79
	v_pk_add_f32 v[64:65], v[64:65], 1.0 op_sel_hi:[1,0]
	v_pk_fma_f32 v[76:77], v[26:27], v[82:83], v[76:77]
	v_mul_f32_e32 v82, 0xbfb8aa3b, v80
	v_mul_f32_e32 v83, 0xbfb8aa3b, v81
	v_exp_f32_e32 v82, v82
	v_exp_f32_e32 v83, v83
	v_pk_add_f32 v[66:67], v[66:67], 1.0 op_sel_hi:[1,0]
	v_rcp_f32_e32 v103, v64
	v_rcp_f32_e32 v104, v65
	v_pk_add_f32 v[78:79], v[78:79], 1.0 op_sel_hi:[1,0]
	v_rcp_f32_e32 v105, v66
	v_rcp_f32_e32 v106, v67
	v_pk_add_f32 v[82:83], v[82:83], 1.0 op_sel_hi:[1,0]
	v_rcp_f32_e32 v107, v78
	v_rcp_f32_e32 v108, v79
	v_rcp_f32_e32 v109, v82
	v_rcp_f32_e32 v110, v83
	v_mul_f32_e32 v41, v54, v103
	s_mov_b64 vcc, s[2:3]
	v_mul_f32_e32 v54, v55, v104
	s_mov_b64 vcc, s[4:5]
	v_mul_f32_e32 v55, v72, v105
	s_mov_b64 vcc, s[6:7]
	v_bfe_u32 v64, v41, 16, 1
	v_mul_f32_e32 v65, v73, v106
	s_mov_b64 vcc, s[8:9]
	v_bfe_u32 v66, v54, 16, 1
	v_add3_u32 v41, v41, v64, s30
	v_mul_f32_e32 v64, v84, v107
	s_mov_b64 vcc, s[10:11]
	v_add3_u32 v54, v54, v66, s30
	v_mul_f32_e32 v72, v85, v108
	s_mov_b64 vcc, s[12:13]
	v_bfe_u32 v67, v55, 16, 1
	v_mov_b32_e32 v66, v64
	v_bfe_u32 v73, v65, 16, 1
	v_perm_b32 v64, v54, v41, s31
	v_mul_f32_e32 v54, v80, v109
	s_mov_b64 vcc, s[14:15]
	v_add3_u32 v55, v55, v67, s30
	v_mov_b32_e32 v41, v72
	v_add3_u32 v65, v65, v73, s30
	v_mul_f32_e32 v72, v81, v110
	v_bfe_u32 v67, v66, 16, 1
	v_bfe_u32 v73, v41, 16, 1
	v_perm_b32 v65, v65, v55, s31
	v_mov_b32_e32 v55, v72
	v_add3_u32 v66, v66, v67, s30
	v_bfe_u32 v67, v54, 16, 1
	v_add3_u32 v41, v41, v73, s30
	v_bfe_u32 v72, v55, 16, 1
	v_add3_u32 v54, v54, v67, s30
	v_perm_b32 v66, v41, v66, s31
	v_add3_u32 v41, v55, v72, s30
	v_perm_b32 v67, v41, v54, s31
	global_store_dwordx4 v[52:53], v[64:67], off
	global_load_dwordx4 v[52:55], v[42:43], off
	v_lshl_add_u64 v[42:43], v[42:43], 0, s[22:23]
	s_waitcnt vmcnt(0)
	v_and_b32_e32 v65, 0xffff0000, v52
	v_lshlrev_b32_e32 v64, 16, v52
	v_and_b32_e32 v73, 0xffff0000, v54
	v_lshlrev_b32_e32 v72, 16, v54
	v_pk_fma_f32 v[64:65], v[20:21], v[64:65], v[70:71]
	v_and_b32_e32 v67, 0xffff0000, v53
	v_lshlrev_b32_e32 v66, 16, v53
	v_pk_fma_f32 v[68:69], v[28:29], v[72:73], v[68:69]
	v_mul_f32_e32 v41, 0xbfb8aa3b, v64
	v_mul_f32_e32 v73, 0xbfb8aa3b, v65
	v_pk_fma_f32 v[66:67], v[22:23], v[66:67], v[74:75]
	v_exp_f32_e32 v72, v41
	v_exp_f32_e32 v73, v73
	v_mul_f32_e32 v74, 0xbfb8aa3b, v66
	v_mul_f32_e32 v75, 0xbfb8aa3b, v67
	v_and_b32_e32 v79, 0xffff0000, v55
	v_lshlrev_b32_e32 v78, 16, v55
	v_exp_f32_e32 v74, v74
	v_exp_f32_e32 v75, v75
	v_pk_fma_f32 v[70:71], v[30:31], v[78:79], v[76:77]
	v_mul_f32_e32 v76, 0xbfb8aa3b, v68
	v_mul_f32_e32 v77, 0xbfb8aa3b, v69
	v_exp_f32_e32 v76, v76
	v_exp_f32_e32 v77, v77
	v_pk_add_f32 v[72:73], v[72:73], 1.0 op_sel_hi:[1,0]
	v_mul_f32_e32 v78, 0xbfb8aa3b, v70
	v_mul_f32_e32 v79, 0xbfb8aa3b, v71
	v_exp_f32_e32 v78, v78
	v_exp_f32_e32 v79, v79
	v_pk_add_f32 v[74:75], v[74:75], 1.0 op_sel_hi:[1,0]
	v_rcp_f32_e32 v97, v72
	v_rcp_f32_e32 v98, v73
	v_pk_add_f32 v[76:77], v[76:77], 1.0 op_sel_hi:[1,0]
	v_rcp_f32_e32 v99, v74
	v_rcp_f32_e32 v100, v75
	v_pk_add_f32 v[78:79], v[78:79], 1.0 op_sel_hi:[1,0]
	v_rcp_f32_e32 v101, v76
	v_rcp_f32_e32 v102, v77
	v_rcp_f32_e32 v103, v78
	v_rcp_f32_e32 v104, v79
	v_mul_f32_e32 v41, v64, v97
	s_mov_b64 vcc, s[2:3]
	v_mul_f32_e32 v64, v65, v98
	s_mov_b64 vcc, s[4:5]
	v_mul_f32_e32 v65, v66, v99
	s_mov_b64 vcc, s[6:7]
	v_mul_f32_e32 v66, v67, v100
	s_mov_b64 vcc, s[8:9]
	v_bfe_u32 v72, v41, 16, 1
	v_bfe_u32 v73, v64, 16, 1
	v_mul_f32_e32 v67, v68, v101
	s_mov_b64 vcc, s[10:11]
	v_add3_u32 v41, v41, v72, s30
	v_add3_u32 v64, v64, v73, s30
	v_mul_f32_e32 v68, v69, v102
	s_mov_b64 vcc, s[12:13]
	v_perm_b32 v64, v64, v41, s31
	v_mov_b32_e32 v41, v68
	v_mul_f32_e32 v68, v70, v103
	s_mov_b64 vcc, s[14:15]
	v_bfe_u32 v72, v65, 16, 1
	v_bfe_u32 v73, v66, 16, 1
	v_bfe_u32 v69, v67, 16, 1
	v_mul_f32_e32 v70, v71, v104
	v_add3_u32 v65, v65, v72, s30
	v_add3_u32 v66, v66, v73, s30
	v_bfe_u32 v72, v41, 16, 1
	v_add3_u32 v67, v67, v69, s30
	v_mov_b32_e32 v69, v70
	v_perm_b32 v65, v66, v65, s31
	v_bfe_u32 v66, v68, 16, 1
	v_add3_u32 v41, v41, v72, s30
	v_bfe_u32 v70, v69, 16, 1
	v_add3_u32 v68, v68, v66, s30
	v_perm_b32 v66, v41, v67, s31
	v_add3_u32 v41, v69, v70, s30
	v_perm_b32 v67, v41, v68, s31
	global_store_dwordx4 v[62:63], v[64:67], off
	s_cbranch_scc0 .LBB0_1477
	v_add_u32_e32 v88, s24, v88
	v_cmp_lt_i32_e32 vcc, s37, v88
	s_or_b64 s[18:19], vcc, s[18:19]
	v_add_u32_e32 v89, s25, v89
	s_andn2_b64 exec, exec, s[18:19]
	s_cbranch_execnz .LBB0_1470

; DEVINL u16 f2bf(float f) { uint32_t u = __float_as_uint(f); u += 0x7FFFu + ((u >> 16) & 1u); return (u16)(u >> 16); }
; DEVINL float shx(float v, int m, int lane) { return __int_as_float(__builtin_amdgcn_ds_bpermute((lane ^ m) << 2, __float_as_int(v))); }
; DEVINL void attn_item(const Params& p, int item, char* smem, int wv) {
;     ...
; #pragma unroll
;   for (int hh = 0; hh < 2; ++hh) {
;     float lt = lsum[hh];
;     lt += shx(lt, 16, lane); lt += shx(lt, 32, lane);
;     float inv = 1.f / lt;
; #pragma unroll
;     for (int dt = 0; dt < 8; ++dt) {
;       bf16x4 ov;
; #pragma unroll
;       for (int j = 0; j < 4; ++j) ov[j] = (short)f2bf(o[hh][dt][j] * inv);
;       *(bf16x4*)(ycat + qtok * DM + 1024 + (kvh * 2 + hh) * 128 + dt * 16 + fq * 4) = ov;
;     }
.LBB0_1717:
	s_setprio 0
	v_lshlrev_b32_e32 v0, 2, v0
	v_xor_b32_e32 v10, 64, v0
	ds_bpermute_b32 v4, v10, v160
	v_xor_b32_e32 v11, 0x80, v0
	v_lshlrev_b64 v[2:3], 12, v[156:157]
	v_lshlrev_b32_e32 v0, 1, v174
	v_lshl_add_u64 v[2:3], s[94:95], 0, v[2:3]
	s_waitcnt lgkmcnt(0)
	v_add_f32_e32 v4, v160, v4
	ds_bpermute_b32 v5, v11, v4
	v_lshl_add_u64 v[2:3], v[2:3], 0, v[0:1]
	s_lshl_b32 s10, s18, 1
	s_mov_b64 s[2:3], 0
	s_waitcnt lgkmcnt(0)
	v_add_f32_e32 v0, v4, v5
	v_div_scale_f32 v6, s[0:1], v0, v0, 1.0
	v_rcp_f32_e32 v7, v6
	v_lshl_add_u64 v[4:5], v[2:3], 0, s[10:11]
	v_div_scale_f32 v2, vcc, 1.0, v0, 1.0
	v_fma_f32 v3, -v6, v7, 1.0
	v_fmac_f32_e32 v7, v3, v7
	v_mul_f32_e32 v3, v2, v7
	v_fma_f32 v8, -v6, v3, v2
	v_fmac_f32_e32 v3, v8, v7
	v_fma_f32 v2, -v6, v3, v2
	v_div_fmas_f32 v2, v2, v7, v3
	v_div_fixup_f32 v0, v2, v0, 1.0
	v_pk_mul_f32 v[6:7], v[88:89], v[0:1] op_sel_hi:[1,0]
	v_pk_mul_f32 v[8:9], v[90:91], v[0:1] op_sel_hi:[1,0]
	v_bfe_u32 v14, v7, 16, 1
	v_bfe_u32 v12, v9, 16, 1
	v_bfe_u32 v13, v8, 16, 1
	v_bfe_u32 v15, v6, 16, 1
	v_lshl_add_u64 v[2:3], v[4:5], 0, s[16:17]
	v_add3_u32 v6, v6, v15, s29
	v_add3_u32 v14, v7, v14, s29
	v_add3_u32 v7, v8, v13, s29
	v_add3_u32 v8, v9, v12, s29
	v_add_co_u32_e32 v4, vcc, s31, v4
	v_perm_b32 v7, v8, v7, s30
	v_perm_b32 v6, v14, v6, s30
	v_addc_co_u32_e32 v5, vcc, 0, v5, vcc
	global_store_dwordx2 v[4:5], v[6:7], off offset:2048
	v_pk_mul_f32 v[4:5], v[84:85], v[0:1] op_sel_hi:[1,0]
	v_pk_mul_f32 v[6:7], v[86:87], v[0:1] op_sel_hi:[1,0]
	v_bfe_u32 v12, v5, 16, 1
	v_bfe_u32 v8, v7, 16, 1
	v_bfe_u32 v9, v6, 16, 1
	v_bfe_u32 v13, v4, 16, 1
	v_add3_u32 v4, v4, v13, s29
	v_add3_u32 v12, v5, v12, s29
	v_add3_u32 v5, v6, v9, s29
	v_add3_u32 v6, v7, v8, s29
	v_perm_b32 v5, v6, v5, s30
	v_perm_b32 v4, v12, v4, s30
	global_store_dwordx2 v[2:3], v[4:5], off offset:32
	v_pk_mul_f32 v[4:5], v[92:93], v[0:1] op_sel_hi:[1,0]
	v_pk_mul_f32 v[6:7], v[94:95], v[0:1] op_sel_hi:[1,0]
	v_bfe_u32 v12, v5, 16, 1
	v_bfe_u32 v8, v7, 16, 1
	v_bfe_u32 v9, v6, 16, 1
	v_bfe_u32 v13, v4, 16, 1
	v_add3_u32 v4, v4, v13, s29
	v_add3_u32 v12, v5, v12, s29
	v_add3_u32 v5, v6, v9, s29
	v_add3_u32 v6, v7, v8, s29
	v_perm_b32 v5, v6, v5, s30
	v_perm_b32 v4, v12, v4, s30
	global_store_dwordx2 v[2:3], v[4:5], off offset:64
	v_pk_mul_f32 v[4:5], v[96:97], v[0:1] op_sel_hi:[1,0]
	v_pk_mul_f32 v[6:7], v[98:99], v[0:1] op_sel_hi:[1,0]
	v_bfe_u32 v12, v5, 16, 1
	v_bfe_u32 v8, v7, 16, 1
	v_bfe_u32 v9, v6, 16, 1
	v_bfe_u32 v13, v4, 16, 1
	v_add3_u32 v4, v4, v13, s29
	v_add3_u32 v12, v5, v12, s29
	v_add3_u32 v5, v6, v9, s29
	v_add3_u32 v6, v7, v8, s29
	v_perm_b32 v5, v6, v5, s30
	v_perm_b32 v4, v12, v4, s30
	global_store_dwordx2 v[2:3], v[4:5], off offset:96
	v_pk_mul_f32 v[4:5], v[104:105], v[0:1] op_sel_hi:[1,0]
	v_pk_mul_f32 v[6:7], v[106:107], v[0:1] op_sel_hi:[1,0]
	v_bfe_u32 v12, v5, 16, 1
	v_bfe_u32 v8, v7, 16, 1
	v_bfe_u32 v9, v6, 16, 1
	v_bfe_u32 v13, v4, 16, 1
	v_add3_u32 v4, v4, v13, s29
	v_add3_u32 v12, v5, v12, s29
	v_add3_u32 v5, v6, v9, s29
	v_add3_u32 v6, v7, v8, s29
	v_perm_b32 v5, v6, v5, s30
	v_perm_b32 v4, v12, v4, s30
	global_store_dwordx2 v[2:3], v[4:5], off offset:128
	v_pk_mul_f32 v[4:5], v[108:109], v[0:1] op_sel_hi:[1,0]
	v_pk_mul_f32 v[6:7], v[110:111], v[0:1] op_sel_hi:[1,0]
	v_bfe_u32 v12, v5, 16, 1
	v_bfe_u32 v8, v7, 16, 1
	v_bfe_u32 v9, v6, 16, 1
	v_bfe_u32 v13, v4, 16, 1
	v_add3_u32 v4, v4, v13, s29
	v_add3_u32 v12, v5, v12, s29
	v_add3_u32 v5, v6, v9, s29
	v_add3_u32 v6, v7, v8, s29
	v_perm_b32 v5, v6, v5, s30
	v_perm_b32 v4, v12, v4, s30
	global_store_dwordx2 v[2:3], v[4:5], off offset:160
	v_pk_mul_f32 v[4:5], v[112:113], v[0:1] op_sel_hi:[1,0]
	v_pk_mul_f32 v[6:7], v[114:115], v[0:1] op_sel_hi:[1,0]
	v_bfe_u32 v12, v5, 16, 1
	v_bfe_u32 v8, v7, 16, 1
	v_bfe_u32 v9, v6, 16, 1
	v_bfe_u32 v13, v4, 16, 1
	v_add3_u32 v4, v4, v13, s29
	v_add3_u32 v12, v5, v12, s29
	v_add3_u32 v5, v6, v9, s29
	v_add3_u32 v6, v7, v8, s29
	v_perm_b32 v5, v6, v5, s30
	v_perm_b32 v4, v12, v4, s30
	global_store_dwordx2 v[2:3], v[4:5], off offset:192
	v_pk_mul_f32 v[4:5], v[100:101], v[0:1] op_sel_hi:[1,0]
	v_pk_mul_f32 v[6:7], v[102:103], v[0:1] op_sel_hi:[1,0]
	ds_bpermute_b32 v0, v10, v161
	v_bfe_u32 v8, v7, 16, 1
	v_bfe_u32 v9, v6, 16, 1
	v_bfe_u32 v10, v5, 16, 1
	v_add3_u32 v10, v5, v10, s29
	s_waitcnt lgkmcnt(0)
; DEVINL u16 f2bf(float f) { uint32_t u = __float_as_uint(f); u += 0x7FFFu + ((u >> 16) & 1u); return (u16)(u >> 16); }
; DEVINL float shx(float v, int m, int lane) { return __int_as_float(__builtin_amdgcn_ds_bpermute((lane ^ m) << 2, __float_as_int(v))); }
; DEVINL void attn_item(const Params& p, int item, char* smem, int wv) {
;     ...
; #pragma unroll
;   for (int hh = 0; hh < 2; ++hh) {
;     float lt = lsum[hh];
;     lt += shx(lt, 16, lane); lt += shx(lt, 32, lane);
;     float inv = 1.f / lt;
; #pragma unroll
;     for (int dt = 0; dt < 8; ++dt) {
;       bf16x4 ov;
; #pragma unroll
;       for (int j = 0; j < 4; ++j) ov[j] = (short)f2bf(o[hh][dt][j] * inv);
;       *(bf16x4*)(ycat + qtok * DM + 1024 + (kvh * 2 + hh) * 128 + dt * 16 + fq * 4) = ov;
;     }
;   }
	v_add_f32_e32 v0, v161, v0
	ds_bpermute_b32 v11, v11, v0
	v_add3_u32 v5, v6, v9, s29
	v_add3_u32 v6, v7, v8, s29
	v_bfe_u32 v12, v4, 16, 1
	v_add3_u32 v4, v4, v12, s29
	s_waitcnt lgkmcnt(0)
	v_add_f32_e32 v0, v0, v11
	v_div_scale_f32 v7, s[0:1], v0, v0, 1.0
	v_rcp_f32_e32 v8, v7
	v_perm_b32 v5, v6, v5, s30
	v_perm_b32 v4, v10, v4, s30
	global_store_dwordx2 v[2:3], v[4:5], off offset:224
	v_fma_f32 v4, -v7, v8, 1.0
	v_fmac_f32_e32 v8, v4, v8
	v_div_scale_f32 v4, vcc, 1.0, v0, 1.0
	v_mul_f32_e32 v5, v4, v8
	v_fma_f32 v6, -v7, v5, v4
	v_fmac_f32_e32 v5, v6, v8
	v_fma_f32 v4, -v7, v5, v4
	v_div_fmas_f32 v4, v4, v8, v5
	v_div_fixup_f32 v0, v4, v0, 1.0
	v_pk_mul_f32 v[4:5], v[52:53], v[0:1] op_sel_hi:[1,0]
	v_pk_mul_f32 v[6:7], v[54:55], v[0:1] op_sel_hi:[1,0]
	v_bfe_u32 v10, v5, 16, 1
	v_bfe_u32 v8, v7, 16, 1
	v_bfe_u32 v9, v6, 16, 1
	v_bfe_u32 v11, v4, 16, 1
	v_add3_u32 v4, v4, v11, s29
	v_add3_u32 v10, v5, v10, s29
	v_add3_u32 v5, v6, v9, s29
	v_add3_u32 v6, v7, v8, s29
	v_perm_b32 v5, v6, v5, s30
	v_perm_b32 v4, v10, v4, s30
	global_store_dwordx2 v[2:3], v[4:5], off offset:256
	v_pk_mul_f32 v[4:5], v[56:57], v[0:1] op_sel_hi:[1,0]
	v_pk_mul_f32 v[6:7], v[58:59], v[0:1] op_sel_hi:[1,0]
	v_bfe_u32 v10, v5, 16, 1
	v_bfe_u32 v8, v7, 16, 1
	v_bfe_u32 v9, v6, 16, 1
	v_bfe_u32 v11, v4, 16, 1
	v_add3_u32 v4, v4, v11, s29
	v_add3_u32 v10, v5, v10, s29
	v_add3_u32 v5, v6, v9, s29
	v_add3_u32 v6, v7, v8, s29
	v_perm_b32 v5, v6, v5, s30
	v_perm_b32 v4, v10, v4, s30
	global_store_dwordx2 v[2:3], v[4:5], off offset:288
	v_pk_mul_f32 v[4:5], v[60:61], v[0:1] op_sel_hi:[1,0]
	v_pk_mul_f32 v[6:7], v[62:63], v[0:1] op_sel_hi:[1,0]
	v_bfe_u32 v10, v5, 16, 1
	v_bfe_u32 v8, v7, 16, 1
	v_bfe_u32 v9, v6, 16, 1
	v_bfe_u32 v11, v4, 16, 1
	v_add3_u32 v4, v4, v11, s29
	v_add3_u32 v10, v5, v10, s29
	v_add3_u32 v5, v6, v9, s29
	v_add3_u32 v6, v7, v8, s29
	v_perm_b32 v5, v6, v5, s30
	v_perm_b32 v4, v10, v4, s30
	global_store_dwordx2 v[2:3], v[4:5], off offset:320
	v_pk_mul_f32 v[4:5], v[64:65], v[0:1] op_sel_hi:[1,0]
	v_pk_mul_f32 v[6:7], v[66:67], v[0:1] op_sel_hi:[1,0]
	v_bfe_u32 v10, v5, 16, 1
	v_bfe_u32 v8, v7, 16, 1
	v_bfe_u32 v9, v6, 16, 1
	v_bfe_u32 v11, v4, 16, 1
	v_add3_u32 v4, v4, v11, s29
	v_add3_u32 v10, v5, v10, s29
	v_add3_u32 v5, v6, v9, s29
	v_add3_u32 v6, v7, v8, s29
	v_perm_b32 v5, v6, v5, s30
	v_perm_b32 v4, v10, v4, s30
	global_store_dwordx2 v[2:3], v[4:5], off offset:352
	v_pk_mul_f32 v[4:5], v[72:73], v[0:1] op_sel_hi:[1,0]
	v_pk_mul_f32 v[6:7], v[74:75], v[0:1] op_sel_hi:[1,0]
	v_bfe_u32 v10, v5, 16, 1
	v_bfe_u32 v8, v7, 16, 1
	v_bfe_u32 v9, v6, 16, 1
	v_bfe_u32 v11, v4, 16, 1
	v_add3_u32 v4, v4, v11, s29
	v_add3_u32 v10, v5, v10, s29
	v_add3_u32 v5, v6, v9, s29
	v_add3_u32 v6, v7, v8, s29
	v_perm_b32 v5, v6, v5, s30
	v_perm_b32 v4, v10, v4, s30
	global_store_dwordx2 v[2:3], v[4:5], off offset:384
	v_pk_mul_f32 v[4:5], v[76:77], v[0:1] op_sel_hi:[1,0]
	v_pk_mul_f32 v[6:7], v[78:79], v[0:1] op_sel_hi:[1,0]
	v_bfe_u32 v10, v5, 16, 1
	v_bfe_u32 v8, v7, 16, 1
	v_bfe_u32 v9, v6, 16, 1
	v_bfe_u32 v11, v4, 16, 1
	v_add3_u32 v4, v4, v11, s29
	v_add3_u32 v10, v5, v10, s29
	v_add3_u32 v5, v6, v9, s29
	v_add3_u32 v6, v7, v8, s29
	v_perm_b32 v5, v6, v5, s30
	v_perm_b32 v4, v10, v4, s30
	global_store_dwordx2 v[2:3], v[4:5], off offset:416
	v_pk_mul_f32 v[4:5], v[80:81], v[0:1] op_sel_hi:[1,0]
	v_pk_mul_f32 v[6:7], v[82:83], v[0:1] op_sel_hi:[1,0]
	v_bfe_u32 v10, v5, 16, 1
	v_bfe_u32 v8, v7, 16, 1
	v_bfe_u32 v9, v6, 16, 1
	v_bfe_u32 v11, v4, 16, 1
	v_add3_u32 v4, v4, v11, s29
	v_add3_u32 v10, v5, v10, s29
	v_add3_u32 v5, v6, v9, s29
	v_add3_u32 v6, v7, v8, s29
	v_perm_b32 v5, v6, v5, s30
	v_perm_b32 v4, v10, v4, s30
	global_store_dwordx2 v[2:3], v[4:5], off offset:448
	v_pk_mul_f32 v[4:5], v[68:69], v[0:1] op_sel_hi:[1,0]
	v_pk_mul_f32 v[6:7], v[70:71], v[0:1] op_sel_hi:[1,0]
	v_bfe_u32 v9, v5, 16, 1
	v_bfe_u32 v0, v7, 16, 1
	v_bfe_u32 v8, v6, 16, 1
	v_bfe_u32 v10, v4, 16, 1
	v_add3_u32 v4, v4, v10, s29
	v_add3_u32 v9, v5, v9, s29
	v_add3_u32 v5, v6, v8, s29
	v_add3_u32 v0, v7, v0, s29
	v_perm_b32 v5, v0, v5, s30
	v_perm_b32 v4, v9, v4, s30
	global_store_dwordx2 v[2:3], v[4:5], off offset:480

; DEVINL int opaque_tid(int wv) { int t = (wv << 6) | (int)__builtin_amdgcn_mbcnt_hi(~0u, __builtin_amdgcn_mbcnt_lo(~0u, 0u)); asm volatile("" : "+v"(t)); return t; }
; DEVINL int next_item(int* ctr, char* smem, int wv) {
;     ...
;   __syncthreads();
;   if (opaque_tid(wv) == 0) *slot = atomicAdd(ctr, 1);
;   __syncthreads();
;   return *slot;
; DEVINL void attn_item(const Params& p, int item, char* smem, int wv) {
;     ...
;   const int tid = opaque_tid(wv), lane = tid & 63, wid = __builtin_amdgcn_readfirstlane(tid >> 6), fr = lane & 15, fq = lane >> 4;
;   const int qblk = 31 - (item >> 4), b = (item >> 2) & 3, kvh = item & 3;
;   const int q0 = qblk * 128, ntile = 2 * qblk + 2;
;   const int qlast = q0 + wid * 16 + 15;
;   u16* Ks = (u16*)smem;
;   u16* Vs = Ks + 64 * 136;
;   const size_t qtok = (size_t)b * SEQ + q0 + wid * 16 + fr;
;   bf16x8 qf[2][4];
; #pragma unroll
;   for (int hh = 0; hh < 2; ++hh)
; #pragma unroll
;     for (int kc = 0; kc < 4; ++kc)
;       qf[hh][kc] = *(const bf16x8*)(hb + qtok * HS + 2560 + (kvh * 2 + hh) * 128 + kc * 32 + fq * 8);
;   f32x4 o[2][8];
; #pragma unroll
;   for (int hh = 0; hh < 2; ++hh)
; #pragma unroll
;     for (int dt = 0; dt < 8; ++dt) o[hh][dt] = f32x4{0.f, 0.f, 0.f, 0.f};
;   float mrun[2] = {0.f, 0.f}, lsum[2] = {0.f, 0.f};
;   unsigned long long mw_next = bits[qtok * 64];
;   u32x4 rk[2], rv[2];
;   const u16* kg = hb + ((size_t)b * SEQ + (tid >> 4)) * HS + 3584 + kvh * 128 + (tid & 15) * 8;
;   const u16* vg = vT + ((size_t)(b * 4 + kvh) * 128 + (tid >> 3)) * SEQ + (tid & 7) * 8;
; #pragma unroll
;   for (int i = 0; i < 2; ++i) {
;     rk[i] = *(const u32x4*)(kg + (size_t)(32 * i) * HS);
;     rv[i] = *(const u32x4*)(vg + (size_t)(64 * i) * SEQ);
;   }
;   for (int kt = 0; kt < ntile; ++kt) {
; #pragma unroll
;     for (int i = 0; i < 2; ++i) {
;       *(u32x4*)(Ks + ((tid >> 4) + 32 * i) * 136 + (tid & 15) * 8) = rk[i];
;       *(u32x4*)(Vs + ((tid >> 3) + 64 * i) * 72 + (tid & 7) * 8) = rv[i];
;     }
;     __syncthreads();
.LBB0_1723:
	s_or_b64 exec, exec, s[2:3]
	s_waitcnt lgkmcnt(0)
	s_barrier
	ds_read_b32 v0, v170
	s_mov_b64 s[2:3], -1
	s_waitcnt lgkmcnt(0)
	v_cmp_lt_i32_e32 vcc, s21, v0
	v_readfirstlane_b32 s1, v0
	s_cbranch_vccnz .LBB0_1718
	s_waitcnt vmcnt(1)
	v_mov_b32_e32 v120, v176
	s_ashr_i32 s33, s1, 4
	s_sub_i32 s0, 31, s33
	v_readfirstlane_b32 s2, v120
	s_lshl_b32 s3, s1, 10
	s_lshl_b32 s6, s0, 7
	s_ashr_i32 s7, s2, 2
	s_cmp_lt_i32 s7, 64
	s_cbranch_scc1 .Lprio_skip_a1
	s_setprio 2
.Lprio_skip_a1:
	s_and_b32 s34, s3, 0x3000
	v_and_b32_e32 v60, 15, v120
	s_and_b32 s2, s7, -16
	s_add_i32 s10, s6, s34
	s_ashr_i32 s3, s2, 31
	v_or_b32_e32 v0, s10, v60
	v_lshl_add_u64 v[156:157], v[0:1], 0, s[2:3]
	v_mov_b64_e32 v[2:3], s[62:63]
	v_mad_u64_u32 v[4:5], s[2:3], v156, s22, v[2:3]
	s_and_b32 s5, s1, 3
	v_mad_i32_i24 v5, v157, s22, v5
	v_and_b32_e32 v0, 48, v120
	v_lshl_add_u64 v[4:5], v[4:5], 0, v[0:1]
	s_lshl_b32 s10, s5, 9
	v_ashrrev_i32_e32 v14, 4, v120
	v_lshl_add_u64 v[8:9], v[4:5], 0, s[10:11]
	v_add_u32_e32 v4, s34, v14
	s_lshl_b32 s18, s5, 8
	s_mov_b32 s19, s11
	v_mad_i64_i32 v[2:3], s[2:3], v4, s22, v[2:3]
	v_lshlrev_b32_e32 v6, 4, v120
	v_lshl_add_u64 v[2:3], v[2:3], 0, s[18:19]
	v_and_b32_e32 v10, 0xf0, v6
	v_mov_b32_e32 v11, v1
	v_lshl_add_u64 v[116:117], v[2:3], 0, v[10:11]
	s_lshl_b32 s1, s1, 7
	v_ashrrev_i32_e32 v2, 3, v120
	s_and_b32 s10, s1, 0x780
	v_ashrrev_i32_e32 v3, 31, v2
	v_lshl_add_u64 v[4:5], v[2:3], 0, s[10:11]
	v_lshlrev_b64 v[4:5], 13, v[4:5]
	v_lshl_add_u64 v[4:5], s[40:41], 0, v[4:5]
	v_and_b32_e32 v12, 0x70, v6
	v_mov_b32_e32 v13, v1
	v_lshl_add_u64 v[158:159], v[4:5], 0, v[12:13]
	v_add_co_u32_e32 v4, vcc, s23, v116
	global_load_dwordx4 v[36:39], v[158:159], off
	s_nop 0
	v_addc_co_u32_e32 v5, vcc, 0, v117, vcc
	v_add_co_u32_e32 v6, vcc, s24, v116
	v_mul_lo_u32 v2, v2, s27
	s_nop 0
	v_addc_co_u32_e32 v7, vcc, 0, v117, vcc
	global_load_dwordx4 v[40:43], v[4:5], off offset:3072
	global_load_dwordx4 v[44:47], v[6:7], off offset:3072
	v_add_co_u32_e32 v52, vcc, s25, v158
	v_add_u32_e32 v11, 0, v12
	s_nop 0
	v_addc_co_u32_e32 v53, vcc, 0, v159, vcc
	global_load_dwordx4 v[48:51], v[52:53], off
	v_mul_lo_u32 v3, v14, s26
	v_add_u32_e32 v10, 0, v10
	v_and_b32_e32 v173, 64, v12
	v_bfe_u32 v11, v12, 4, 1
	v_lshl_or_b32 v173, v11, 5, v173
	v_bfe_u32 v11, v12, 5, 1
	v_lshl_or_b32 v173, v11, 3, v173
	v_add_u32_e32 v173, v173, v2
	v_add_co_u32_e64 v2, s[2:3], s23, v8
	v_lshl_add_u64 v[28:29], v[8:9], 0, s[12:13]
	v_add_u32_e32 v172, v10, v3
	v_lshlrev_b64 v[118:119], 9, v[156:157]
	v_add_co_u32_e32 v54, vcc, 0xa1000, v116
	v_addc_co_u32_e64 v3, s[2:3], 0, v9, s[2:3]
	global_load_dwordx4 v[4:7], v[28:29], off offset:64
	v_lshl_add_u64 v[56:57], s[38:39], 0, v[118:119]
	v_addc_co_u32_e32 v55, vcc, 0, v117, vcc
	global_load_dwordx4 v[8:11], v[28:29], off offset:128
	global_load_dwordx4 v[12:15], v[28:29], off offset:192
	global_load_dwordx4 v[16:19], v[28:29], off offset:256
	global_load_dwordx4 v[20:23], v[28:29], off offset:320
	global_load_dwordx4 v[24:27], v[28:29], off offset:384
	s_nop 0
	global_load_dwordx4 v[28:31], v[28:29], off offset:448
	s_nop 0
	global_load_dwordx4 v[32:35], v[2:3], off offset:1024
	s_nop 0
	global_load_dwordx2 v[2:3], v[56:57], off
	v_add_co_u32_e32 v58, vcc, 0xf1000, v116
	s_add_i32 s1, s7, s6
	s_nop 0
	v_addc_co_u32_e32 v59, vcc, 0, v117, vcc
	s_cmp_gt_i32 s1, -1
	s_mov_b64 s[2:3], -1
	s_waitcnt vmcnt(11)
	ds_write_b128 v172, v[40:43]
	ds_write_b64 v173, v[36:37] offset:17408
	ds_write_b64 v173, v[38:39] offset:17424
	s_waitcnt vmcnt(10)
	ds_write_b128 v172, v[44:47] offset:8704
	s_waitcnt vmcnt(9)
	ds_write_b64 v173, v[48:49] offset:26624
	ds_write_b64 v173, v[50:51] offset:26640
	s_waitcnt lgkmcnt(0)
	s_barrier
	global_load_dwordx4 v[44:47], v[58:59], off offset:3072
	global_load_dwordx4 v[36:39], v[54:55], off offset:3072
	global_load_dwordx4 v[48:51], v[52:53], off offset:128
	global_load_dwordx4 v[40:43], v[158:159], off offset:128
	global_load_dwordx2 v[162:163], v[56:57], off offset:8
	v_mad_u32_u24 v52, v60, s26, 0
	v_lshlrev_b32_e32 v53, 7, v60
	v_lshrrev_b32_e32 v54, 2, v120
	v_sub_u32_e32 v53, v52, v53
	v_and_b32_e32 v174, 12, v54
	v_add_u32_e32 v175, v52, v0
	v_lshl_add_u32 v177, v174, 2, v53
	s_cbranch_scc0 .LBB0_1726
; DEVINL float fexp2(float x) { return __builtin_amdgcn_exp2f(x); }
; #define LDK(DST, KQ) _Pragma("unroll") for (int kc = 0; kc < 4; ++kc) DST[kc] = *(const bf16x8*)(Ks + ((KQ) * 16 + fr) * 136 + kc * 32 + fq * 8)
; DEVINL void attn_item(const Params& p, int item, char* smem, int wv) {
;     ...
;     LDK(kfa, 0);
;     LDK(kfb, 1); MMS(kfa, 0);
;     LDK(kfa, 2); MMS(kfb, 1);
;     LDK(kfb, 3); MMS(kfa, 2);
;     LDV(vfa, 0); MMS(kfb, 3);
;     bf16x8 pf[2][2];
;     {
;       const unsigned long long msh = mw >> (fq * 4);
;       const int mlo = (int)(unsigned)msh, mhi = (int)(unsigned)(msh >> 32);
;       int mk[4][4];
; #pragma unroll
;       for (int j = 0; j < 4; ++j) {
;         mk[0][j] = __builtin_amdgcn_sbfe(mlo, j, 1); mk[1][j] = __builtin_amdgcn_sbfe(mlo, 16 + j, 1);
;         mk[2][j] = __builtin_amdgcn_sbfe(mhi, j, 1); mk[3][j] = __builtin_amdgcn_sbfe(mhi, 16 + j, 1);
;       }
; #pragma unroll
;       for (int hh = 0; hh < 2; ++hh) {
;         float mx = s[hh][0][0];
; #pragma unroll
;         for (int kq = 0; kq < 4; ++kq)
; #pragma unroll
;           for (int j = 0; j < 4; ++j) mx = fmaxf(mx, s[hh][kq][j]);
;         {
;           auto r1 = __builtin_amdgcn_permlane16_swap(__float_as_uint(mx), __float_as_uint(mx), false, false);
;           mx = fmaxf(__uint_as_float(r1[0]), __uint_as_float(r1[1]));
;           auto r2 = __builtin_amdgcn_permlane32_swap(__float_as_uint(mx), __float_as_uint(mx), false, false);
;           mx = fmaxf(__uint_as_float(r2[0]), __uint_as_float(r2[1]));
;         }
;         if (kt == 0 || __ballot(mx > 8.f)) {
;           const float delta = (kt == 0) ? mx : fmaxf(mx, 0.f);
;           const float alpha = fexp2(-delta);
;           mrun[hh] += delta;
;           lsum[hh] *= alpha;
; #pragma unroll
;           for (int dt = 0; dt < 8; ++dt) o[hh][dt] *= alpha;
; #pragma unroll
;           for (int kq = 0; kq < 4; ++kq)
; #pragma unroll
;             for (int j = 0; j < 4; ++j) s[hh][kq][j] -= delta;
;         }
;         float ps = 0.f;
;         float pv[4][4];
; #pragma unroll
;         for (int kq = 0; kq < 4; ++kq)
; #pragma unroll
;           for (int j = 0; j < 4; ++j) {
;             pv[kq][j] = __uint_as_float(__float_as_uint(fexp2(s[hh][kq][j])) & (unsigned)mk[kq][j]);
;             ps += pv[kq][j];
;           }
	ds_read_b128 v[52:55], v175
	ds_read_b128 v[56:59], v175 offset:64
	ds_read_b128 v[60:63], v175 offset:128
	ds_read_b128 v[64:67], v175 offset:192
	ds_read_b128 v[68:71], v175 offset:4352
	ds_read_b128 v[72:75], v175 offset:4416
	ds_read_b128 v[76:79], v175 offset:4480
	ds_read_b128 v[80:83], v175 offset:4544
	s_mov_b32 s6, s4
	s_mov_b32 s7, s4
	s_mov_b32 s5, s4
	v_mov_b64_e32 v[86:87], s[6:7]
	v_mov_b64_e32 v[84:85], s[4:5]
	s_waitcnt vmcnt(6) lgkmcnt(7)
	s_nop 0
	v_mfma_f32_16x16x32_bf16 v[88:91], v[52:55], v[32:35], v[84:87]
	v_mfma_f32_16x16x32_bf16 v[52:55], v[52:55], v[16:19], v[84:87]
	s_waitcnt lgkmcnt(6)
	v_mfma_f32_16x16x32_bf16 v[88:91], v[56:59], v[4:7], v[88:91]
	v_mfma_f32_16x16x32_bf16 v[52:55], v[56:59], v[20:23], v[52:55]
	s_waitcnt lgkmcnt(5)
	v_mfma_f32_16x16x32_bf16 v[56:59], v[60:63], v[8:11], v[88:91]
	v_mfma_f32_16x16x32_bf16 v[52:55], v[60:63], v[24:27], v[52:55]
	s_waitcnt lgkmcnt(4)
	v_mfma_f32_16x16x32_bf16 v[60:63], v[64:67], v[12:15], v[56:59]
	v_mfma_f32_16x16x32_bf16 v[64:67], v[64:67], v[28:31], v[52:55]
	s_nop 3
	ds_read_b128 v[52:55], v175 offset:8704
	ds_read_b128 v[56:59], v175 offset:8768
	ds_read_b128 v[88:91], v175 offset:8832
	ds_read_b128 v[92:95], v175 offset:8896
	s_waitcnt lgkmcnt(7)
	v_mfma_f32_16x16x32_bf16 v[96:99], v[68:71], v[32:35], v[84:87]
	v_mfma_f32_16x16x32_bf16 v[68:71], v[68:71], v[16:19], v[84:87]
	s_waitcnt lgkmcnt(6)
	v_mfma_f32_16x16x32_bf16 v[96:99], v[72:75], v[4:7], v[96:99]
	v_mfma_f32_16x16x32_bf16 v[68:71], v[72:75], v[20:23], v[68:71]
	s_waitcnt lgkmcnt(5)
	v_mfma_f32_16x16x32_bf16 v[72:75], v[76:79], v[8:11], v[96:99]
	v_mfma_f32_16x16x32_bf16 v[68:71], v[76:79], v[24:27], v[68:71]
	s_waitcnt lgkmcnt(4)
	v_mfma_f32_16x16x32_bf16 v[72:75], v[80:83], v[12:15], v[72:75]
	v_mfma_f32_16x16x32_bf16 v[68:71], v[80:83], v[28:31], v[68:71]
	ds_read_b128 v[76:79], v175 offset:13056
	ds_read_b128 v[80:83], v175 offset:13120
	ds_read_b128 v[96:99], v175 offset:13184
	ds_read_b128 v[100:103], v175 offset:13248
	s_waitcnt lgkmcnt(7)
	v_mfma_f32_16x16x32_bf16 v[104:107], v[52:55], v[32:35], v[84:87]
	v_mfma_f32_16x16x32_bf16 v[52:55], v[52:55], v[16:19], v[84:87]
	s_waitcnt lgkmcnt(6)
	v_mfma_f32_16x16x32_bf16 v[104:107], v[56:59], v[4:7], v[104:107]
	v_mfma_f32_16x16x32_bf16 v[52:55], v[56:59], v[20:23], v[52:55]
	s_waitcnt lgkmcnt(5)
	v_mfma_f32_16x16x32_bf16 v[56:59], v[88:91], v[8:11], v[104:107]
	v_mfma_f32_16x16x32_bf16 v[52:55], v[88:91], v[24:27], v[52:55]
	s_waitcnt lgkmcnt(4)
	v_mfma_f32_16x16x32_bf16 v[88:91], v[92:95], v[12:15], v[56:59]
	v_mfma_f32_16x16x32_bf16 v[92:95], v[92:95], v[28:31], v[52:55]
	s_nop 0
	s_nop 2
	ds_read_b128 v[52:55], v177 offset:17408
	ds_read_b128 v[56:59], v177 offset:17472
	s_waitcnt lgkmcnt(5)
	v_mfma_f32_16x16x32_bf16 v[104:107], v[76:79], v[32:35], v[84:87]
	v_mfma_f32_16x16x32_bf16 v[76:79], v[76:79], v[16:19], v[84:87]
	s_waitcnt lgkmcnt(4)
	v_mfma_f32_16x16x32_bf16 v[84:87], v[80:83], v[4:7], v[104:107]
	v_mfma_f32_16x16x32_bf16 v[76:79], v[80:83], v[20:23], v[76:79]
	s_waitcnt lgkmcnt(3)
	v_mfma_f32_16x16x32_bf16 v[80:83], v[96:99], v[8:11], v[84:87]
	v_mfma_f32_16x16x32_bf16 v[76:79], v[96:99], v[24:27], v[76:79]
	s_waitcnt lgkmcnt(2)
	v_mfma_f32_16x16x32_bf16 v[80:83], v[100:103], v[12:15], v[80:83]
	v_mfma_f32_16x16x32_bf16 v[76:79], v[100:103], v[28:31], v[76:79]
	s_waitcnt vmcnt(5)
	v_lshrrev_b64 v[2:3], v174, v[2:3]
	v_bfe_i32 v0, v2, 0, 1
	v_bfe_i32 v86, v2, 16, 1
	v_bfe_i32 v87, v3, 0, 1
	v_bfe_i32 v96, v3, 16, 1
	v_bfe_i32 v97, v2, 1, 1
	v_bfe_i32 v98, v2, 17, 1
	v_bfe_i32 v99, v3, 1, 1
	v_bfe_i32 v104, v3, 17, 1
	v_bfe_i32 v100, v2, 2, 1
	v_bfe_i32 v101, v2, 18, 1
	v_bfe_i32 v105, v3, 2, 1
	v_bfe_i32 v106, v3, 18, 1
	v_bfe_i32 v102, v2, 3, 1
	v_bfe_i32 v103, v2, 19, 1
	v_bfe_i32 v107, v3, 3, 1
	v_bfe_i32 v108, v3, 19, 1
	v_max_f32_e32 v2, v61, v61
	v_max_f32_e32 v3, v60, v60
	v_max_f32_e32 v2, v3, v2
	v_max3_f32 v2, v2, v62, v63
	v_max3_f32 v2, v2, v72, v73
	v_max3_f32 v2, v2, v74, v75
	v_max3_f32 v2, v2, v88, v89
	v_max3_f32 v2, v2, v90, v91
	v_max3_f32 v2, v2, v80, v81
	v_max3_f32 v2, v2, v82, v83
	v_mov_b32_e32 v3, v2
	s_nop 1
	v_permlane16_swap_b32_e32 v2, v3
	v_max_f32_e32 v3, v3, v3
	v_max_f32_e32 v2, v2, v2
	v_max_f32_e32 v2, v2, v3
	v_mov_b32_e32 v3, v2
	s_nop 1
	v_permlane32_swap_b32_e32 v2, v3
	v_max_f32_e32 v3, v3, v3
	v_max_f32_e32 v2, v2, v2
	v_max_f32_e32 v3, v2, v3
	v_sub_f32_e32 v2, v80, v3
	v_sub_f32_e32 v61, v61, v3
	v_sub_f32_e32 v80, v81, v3
	v_sub_f32_e32 v81, v82, v3
	v_sub_f32_e32 v82, v83, v3
	v_sub_f32_e32 v83, v88, v3
	v_sub_f32_e32 v88, v90, v3
	v_exp_f32_e32 v90, v61
	v_exp_f32_e32 v115, v2
	v_max_f32_e32 v2, v65, v65
	v_max_f32_e32 v61, v64, v64
	v_max_f32_e32 v2, v61, v2
	v_max3_f32 v2, v2, v66, v67
	v_max3_f32 v2, v2, v68, v69
	v_max3_f32 v2, v2, v70, v71
	v_max3_f32 v2, v2, v92, v93
	v_max3_f32 v2, v2, v94, v95
	v_max3_f32 v2, v2, v76, v77
	v_max3_f32 v2, v2, v78, v79
	v_mov_b32_e32 v61, v2
	s_nop 1
	v_permlane16_swap_b32_e32 v2, v61
	v_max_f32_e32 v61, v61, v61
	v_max_f32_e32 v2, v2, v2
	v_max_f32_e32 v2, v2, v61
	v_mov_b32_e32 v61, v2
	s_nop 1
	v_permlane32_swap_b32_e32 v2, v61
	v_max_f32_e32 v61, v61, v61
	v_max_f32_e32 v2, v2, v2
	v_max_f32_e32 v2, v2, v61
	v_sub_f32_e32 v60, v60, v3
	v_sub_f32_e32 v64, v64, v2
	v_exp_f32_e32 v60, v60
	v_sub_f32_e32 v65, v65, v2
	v_exp_f32_e32 v64, v64
	v_sub_f32_e32 v62, v62, v3
	v_sub_f32_e32 v66, v66, v2
	v_exp_f32_e32 v65, v65
	v_sub_f32_e32 v85, v89, v3
	v_sub_f32_e32 v89, v91, v3
	v_sub_f32_e32 v63, v63, v3
	v_exp_f32_e32 v91, v62
	v_sub_f32_e32 v67, v67, v2
	v_exp_f32_e32 v66, v66
	v_sub_f32_e32 v72, v72, v3
	v_exp_f32_e32 v109, v63
	v_sub_f32_e32 v61, v68, v2
; DEVINL float fexp2(float x) { return __builtin_amdgcn_exp2f(x); }
; DEVINL uint32_t pk2(float a, float b) { hwf2 v = {a, b}; hwbf2 r = __builtin_convertvector(v, hwbf2); return *(uint32_t*)&r; }
; #define MMV(SRC, DT) do { __builtin_amdgcn_s_setprio(1); _Pragma("unroll") for (int c2 = 0; c2 < 2; ++c2) { o[0][DT] = mfma16(SRC[c2], pf[0][c2], o[0][DT]); o[1][DT] = mfma16(SRC[c2], pf[1][c2], o[1][DT]); } __builtin_amdgcn_s_setprio(0); } while (0)
; DEVINL void attn_item(const Params& p, int item, char* smem, int wv) {
;     ...
;         if (kt == 0 || __ballot(mx > 8.f)) {
;           const float delta = (kt == 0) ? mx : fmaxf(mx, 0.f);
;           const float alpha = fexp2(-delta);
;           mrun[hh] += delta;
;           lsum[hh] *= alpha;
; #pragma unroll
;           for (int dt = 0; dt < 8; ++dt) o[hh][dt] *= alpha;
; #pragma unroll
;           for (int kq = 0; kq < 4; ++kq)
; #pragma unroll
;             for (int j = 0; j < 4; ++j) s[hh][kq][j] -= delta;
;         }
;         float ps = 0.f;
;         float pv[4][4];
; #pragma unroll
;         for (int kq = 0; kq < 4; ++kq)
; #pragma unroll
;           for (int j = 0; j < 4; ++j) {
;             pv[kq][j] = __uint_as_float(__float_as_uint(fexp2(s[hh][kq][j])) & (unsigned)mk[kq][j]);
;             ps += pv[kq][j];
;           }
; #pragma unroll
;         for (int c2 = 0; c2 < 2; ++c2) {
;           u32x4 pw;
;           pw[0] = pk2(pv[2 * c2][0], pv[2 * c2][1]); pw[1] = pk2(pv[2 * c2][2], pv[2 * c2][3]);
;           pw[2] = pk2(pv[2 * c2 + 1][0], pv[2 * c2 + 1][1]); pw[3] = pk2(pv[2 * c2 + 1][2], pv[2 * c2 + 1][3]);
;           pf[hh][c2] = *(bf16x8*)&pw;
;         }
;         lsum[hh] += ps;
;       }
;     }
;     LDV(vfb, 1); MMV(vfa, 0);
;     LDV(vfa, 2); MMV(vfb, 1);
;     LDV(vfb, 3); MMV(vfa, 2);
;     LDV(vfa, 4); MMV(vfb, 3);
;     LDV(vfb, 5); MMV(vfa, 4);
;     LDV(vfa, 6); MMV(vfb, 5);
;     LDV(vfb, 7); MMV(vfa, 6);
;     MMV(vfb, 7);
	v_sub_f32_e32 v62, v69, v2
	v_exp_f32_e32 v67, v67
	v_sub_f32_e32 v73, v73, v3
	v_exp_f32_e32 v72, v72
	v_exp_f32_e32 v113, v83
	v_exp_f32_e32 v125, v82
	v_sub_f32_e32 v82, v92, v2
	v_sub_f32_e32 v83, v93, v2
	v_sub_f32_e32 v63, v70, v2
	v_sub_f32_e32 v68, v71, v2
	v_exp_f32_e32 v70, v61
	v_exp_f32_e32 v71, v62
	v_and_b32_e32 v61, v0, v64
	v_and_b32_e32 v60, v0, v60
	v_and_b32_e32 v62, v97, v90
	v_sub_f32_e32 v74, v74, v3
	v_exp_f32_e32 v110, v73
	v_exp_f32_e32 v121, v80
	v_exp_f32_e32 v124, v81
	v_sub_f32_e32 v122, v76, v2
	v_sub_f32_e32 v126, v78, v2
	v_exp_f32_e32 v76, v63
	v_exp_f32_e32 v78, v68
	v_and_b32_e32 v63, v97, v65
	v_cvt_pk_bf16_f32 v68, v60, v62
	v_pk_add_f32 v[80:81], v[60:61], 0 op_sel_hi:[1,0]
	v_exp_f32_e32 v0, v82
	v_exp_f32_e32 v60, v83
	v_sub_f32_e32 v75, v75, v3
	v_exp_f32_e32 v111, v74
	v_and_b32_e32 v65, v100, v66
	v_and_b32_e32 v64, v100, v91
	v_pk_add_f32 v[80:81], v[80:81], v[62:63]
	v_exp_f32_e32 v112, v75
	v_and_b32_e32 v67, v102, v67
	v_and_b32_e32 v66, v102, v109
	v_pk_add_f32 v[80:81], v[80:81], v[64:65]
	v_sub_f32_e32 v93, v95, v2
	v_and_b32_e32 v73, v86, v70
	v_and_b32_e32 v72, v86, v72
	v_pk_add_f32 v[80:81], v[80:81], v[66:67]
	v_exp_f32_e32 v114, v85
	v_sub_f32_e32 v92, v94, v2
	v_and_b32_e32 v75, v98, v71
	v_and_b32_e32 v74, v98, v110
	v_pk_add_f32 v[80:81], v[80:81], v[72:73]
	v_and_b32_e32 v83, v87, v0
	v_and_b32_e32 v82, v87, v113
	v_and_b32_e32 v87, v99, v60
	v_exp_f32_e32 v60, v93
	v_exp_f32_e32 v88, v88
	v_sub_f32_e32 v123, v77, v2
	v_and_b32_e32 v77, v101, v76
	v_and_b32_e32 v76, v101, v111
	v_pk_add_f32 v[80:81], v[80:81], v[74:75]
	v_exp_f32_e32 v0, v92
	v_exp_f32_e32 v89, v89
	v_sub_f32_e32 v127, v79, v2
	v_and_b32_e32 v79, v103, v78
	v_and_b32_e32 v78, v103, v112
	v_pk_add_f32 v[80:81], v[80:81], v[76:77]
	v_exp_f32_e32 v62, v122
	v_pk_add_f32 v[80:81], v[80:81], v[78:79]
	v_cvt_pk_bf16_f32 v69, v64, v66
	v_and_b32_e32 v86, v99, v114
	v_exp_f32_e32 v64, v123
	v_cvt_pk_bf16_f32 v100, v61, v63
	v_cvt_pk_bf16_f32 v102, v73, v75
	v_and_b32_e32 v75, v107, v60
	v_pk_add_f32 v[60:61], v[80:81], v[82:83]
	v_cvt_pk_bf16_f32 v70, v72, v74
	v_exp_f32_e32 v66, v126
	v_and_b32_e32 v73, v105, v0
	v_and_b32_e32 v72, v105, v88
	v_pk_add_f32 v[60:61], v[60:61], v[86:87]
	v_exp_f32_e32 v90, v127
	v_and_b32_e32 v74, v107, v89
	v_pk_add_f32 v[60:61], v[60:61], v[72:73]
	v_cvt_pk_bf16_f32 v71, v76, v78
	v_cvt_pk_bf16_f32 v103, v77, v79
	v_and_b32_e32 v77, v96, v62
	v_and_b32_e32 v76, v96, v115
	v_pk_add_f32 v[60:61], v[60:61], v[74:75]
	v_and_b32_e32 v79, v104, v64
	v_and_b32_e32 v78, v104, v121
	v_pk_add_f32 v[60:61], v[60:61], v[76:77]
	v_and_b32_e32 v89, v106, v66
	v_and_b32_e32 v88, v106, v124
	v_pk_add_f32 v[60:61], v[60:61], v[78:79]
	v_and_b32_e32 v91, v108, v90
	v_and_b32_e32 v90, v108, v125
	v_pk_add_f32 v[60:61], v[60:61], v[88:89]
	s_nop 0
	v_exp_f32_e64 v84, -v3
	v_exp_f32_e64 v85, -v2
	v_cvt_pk_bf16_f32 v101, v65, v67
	v_pk_add_f32 v[80:81], v[60:61], v[90:91]
	ds_read_b128 v[60:63], v177 offset:19712
	ds_read_b128 v[64:67], v177 offset:19776
	v_pk_add_f32 v[2:3], v[2:3], 0 op_sel_hi:[1,0]
	v_pk_mul_f32 v[122:123], v[84:85], 0 op_sel_hi:[1,0]
	v_pk_fma_f32 v[160:161], v[84:85], 0, v[80:81] op_sel_hi:[1,0,1]
	v_mov_b32_e32 v126, v122
	v_mov_b32_e32 v127, v122
	v_mov_b32_e32 v128, v122
	v_mov_b32_e32 v129, v122
	v_cvt_pk_bf16_f32 v130, v82, v86
	v_cvt_pk_bf16_f32 v131, v72, v74
	v_cvt_pk_bf16_f32 v132, v76, v78
	v_cvt_pk_bf16_f32 v133, v88, v90
	v_mov_b32_e32 v122, v123
	v_mov_b32_e32 v124, v123
	v_mov_b32_e32 v125, v123
	v_cvt_pk_bf16_f32 v134, v83, v87
	v_cvt_pk_bf16_f32 v135, v73, v75
	v_cvt_pk_bf16_f32 v136, v77, v79
	v_cvt_pk_bf16_f32 v137, v89, v91
	s_waitcnt lgkmcnt(3)
	v_mfma_f32_16x16x32_bf16 v[72:75], v[52:55], v[68:71], v[126:129]
	v_mfma_f32_16x16x32_bf16 v[52:55], v[52:55], v[100:103], v[122:125]
	s_waitcnt lgkmcnt(2)
	v_mfma_f32_16x16x32_bf16 v[88:91], v[56:59], v[130:133], v[72:75]
	v_mfma_f32_16x16x32_bf16 v[52:55], v[56:59], v[134:137], v[52:55]
	s_nop 0
	s_nop 1
	ds_read_b128 v[72:75], v177 offset:22016
	ds_read_b128 v[76:79], v177 offset:22080
	s_waitcnt lgkmcnt(3)
	v_mfma_f32_16x16x32_bf16 v[56:59], v[60:63], v[68:71], v[126:129]
	v_mfma_f32_16x16x32_bf16 v[60:63], v[60:63], v[100:103], v[122:125]
	s_waitcnt lgkmcnt(2)
	v_mfma_f32_16x16x32_bf16 v[84:87], v[64:67], v[130:133], v[56:59]
	v_mfma_f32_16x16x32_bf16 v[56:59], v[64:67], v[134:137], v[60:63]
	s_nop 0
	ds_read_b128 v[64:67], v177 offset:24320
	ds_read_b128 v[80:83], v177 offset:24384
	s_waitcnt lgkmcnt(3)
	v_mfma_f32_16x16x32_bf16 v[60:63], v[72:75], v[68:71], v[126:129]
	v_mfma_f32_16x16x32_bf16 v[72:75], v[72:75], v[100:103], v[122:125]
	s_waitcnt lgkmcnt(2)
	v_mfma_f32_16x16x32_bf16 v[92:95], v[76:79], v[130:133], v[60:63]
	v_mfma_f32_16x16x32_bf16 v[60:63], v[76:79], v[134:137], v[72:75]
	s_nop 0
	s_nop 2
	ds_read_b128 v[72:75], v177 offset:26624
	ds_read_b128 v[76:79], v177 offset:26688
	s_waitcnt lgkmcnt(3)
	v_mfma_f32_16x16x32_bf16 v[96:99], v[64:67], v[68:71], v[126:129]
	v_mfma_f32_16x16x32_bf16 v[64:67], v[64:67], v[100:103], v[122:125]
	s_waitcnt lgkmcnt(2)
	v_mfma_f32_16x16x32_bf16 v[96:99], v[80:83], v[130:133], v[96:99]
	v_mfma_f32_16x16x32_bf16 v[64:67], v[80:83], v[134:137], v[64:67]
	s_nop 0
	ds_read_b128 v[80:83], v177 offset:28928
	ds_read_b128 v[112:115], v177 offset:28992
	s_waitcnt lgkmcnt(3)
	v_mfma_f32_16x16x32_bf16 v[104:107], v[72:75], v[68:71], v[126:129]
	v_mfma_f32_16x16x32_bf16 v[72:75], v[72:75], v[100:103], v[122:125]
	s_waitcnt lgkmcnt(2)
	v_mfma_f32_16x16x32_bf16 v[104:107], v[76:79], v[130:133], v[104:107]
	v_mfma_f32_16x16x32_bf16 v[72:75], v[76:79], v[134:137], v[72:75]
	s_nop 0
	ds_read_b128 v[138:141], v177 offset:31232
	ds_read_b128 v[142:145], v177 offset:31296
	s_waitcnt lgkmcnt(3)
	v_mfma_f32_16x16x32_bf16 v[76:79], v[80:83], v[68:71], v[126:129]
	v_mfma_f32_16x16x32_bf16 v[80:83], v[80:83], v[100:103], v[122:125]
	s_waitcnt lgkmcnt(2)
	v_mfma_f32_16x16x32_bf16 v[108:111], v[112:115], v[130:133], v[76:79]
	v_mfma_f32_16x16x32_bf16 v[76:79], v[112:115], v[134:137], v[80:83]
	s_nop 0
	ds_read_b128 v[146:149], v177 offset:33536
	ds_read_b128 v[150:153], v177 offset:33600
	s_waitcnt lgkmcnt(3)
	v_mfma_f32_16x16x32_bf16 v[80:83], v[138:141], v[68:71], v[126:129]
	v_mfma_f32_16x16x32_bf16 v[138:141], v[138:141], v[100:103], v[122:125]
	s_waitcnt lgkmcnt(2)
	v_mfma_f32_16x16x32_bf16 v[112:115], v[142:145], v[130:133], v[80:83]
	v_mfma_f32_16x16x32_bf16 v[80:83], v[142:145], v[134:137], v[138:141]
	s_waitcnt lgkmcnt(1)
	v_mfma_f32_16x16x32_bf16 v[68:71], v[146:149], v[68:71], v[126:129]
	v_mfma_f32_16x16x32_bf16 v[122:125], v[146:149], v[100:103], v[122:125]
	s_waitcnt lgkmcnt(0)
	v_mfma_f32_16x16x32_bf16 v[100:103], v[150:153], v[130:133], v[68:71]
	v_mfma_f32_16x16x32_bf16 v[68:71], v[150:153], v[134:137], v[122:125]
	s_cbranch_execz .LBB0_1727
	s_branch .LBB0_1728

; DEVINL void attn_item(const Params& p, int item, char* smem, int wv) {
;     ...
;   for (int kt = 0; kt < ntile; ++kt) {
; #pragma unroll
;     for (int i = 0; i < 2; ++i) {
;       *(u32x4*)(Ks + ((tid >> 4) + 32 * i) * 136 + (tid & 15) * 8) = rk[i];
;       *(u32x4*)(Vs + ((tid >> 3) + 64 * i) * 72 + (tid & 7) * 8) = rv[i];
;     }
;     __syncthreads();
;     if (kt + 1 < ntile) {
; #pragma unroll
;       for (int i = 0; i < 2; ++i) {
;         rk[i] = *(const u32x4*)(kg + (size_t)((kt + 1) * 64 + 32 * i) * HS);
;         rv[i] = *(const u32x4*)(vg + (size_t)(64 * i) * SEQ + (kt + 1) * 64);
;       }
;     }
;     const unsigned long long mw = mw_next;
;     if (kt + 1 < ntile) mw_next = bits[qtok * 64 + kt + 1];
.LBB0_1729:
	s_add_i32 s6, s5, 0x41
	s_cmp_ge_u32 s6, s0
	ds_write_b128 v172, v[36:39]
	ds_write_b64 v173, v[40:41] offset:17408
	ds_write_b64 v173, v[42:43] offset:17424
	ds_write_b128 v172, v[44:47] offset:8704
	ds_write_b64 v173, v[48:49] offset:26624
	ds_write_b64 v173, v[50:51] offset:26640
	s_waitcnt lgkmcnt(0)
	s_barrier
	s_cbranch_scc1 .LBB0_1731
	s_sub_i32 s10, s3, 32
	v_lshl_add_u64 v[44:45], s[10:11], 1, v[158:159]
	v_add_co_u32_e32 v48, vcc, 0x80000, v44
	v_mad_u64_u32 v[36:37], s[6:7], s10, v171, v[164:165]
	v_mad_u64_u32 v[46:47], s[6:7], s3, v171, v[164:165]
	v_addc_co_u32_e32 v49, vcc, 0, v45, vcc
	global_load_dwordx4 v[36:39], v[36:37], off
	s_nop 0
	global_load_dwordx4 v[40:43], v[44:45], off
	s_nop 0
	global_load_dwordx4 v[44:47], v[46:47], off
	s_nop 0
	global_load_dwordx4 v[48:51], v[48:49], off
	s_nop 0
	global_load_dwordx2 v[168:169], v[166:167], off
; DEVINL float fexp2(float x) { return __builtin_amdgcn_exp2f(x); }
; #define LDK(DST, KQ) _Pragma("unroll") for (int kc = 0; kc < 4; ++kc) DST[kc] = *(const bf16x8*)(Ks + ((KQ) * 16 + fr) * 136 + kc * 32 + fq * 8)
; DEVINL void attn_item(const Params& p, int item, char* smem, int wv) {
;     ...
;     if (kt * 64 <= qlast) {
;     f32x4 s[2][4];
;     bf16x8 kfa[4], kfb[4];
;     bf16x8 vfa[2], vfb[2];
;     ...
;     LDK(kfa, 0);
;     LDK(kfb, 1); MMS(kfa, 0);
;     LDK(kfa, 2); MMS(kfb, 1);
;     LDK(kfb, 3); MMS(kfa, 2);
;     LDV(vfa, 0); MMS(kfb, 3);
;     bf16x8 pf[2][2];
;     {
;       const unsigned long long msh = mw >> (fq * 4);
;       const int mlo = (int)(unsigned)msh, mhi = (int)(unsigned)(msh >> 32);
;       int mk[4][4];
; #pragma unroll
;       for (int j = 0; j < 4; ++j) {
;         mk[0][j] = __builtin_amdgcn_sbfe(mlo, j, 1); mk[1][j] = __builtin_amdgcn_sbfe(mlo, 16 + j, 1);
;         mk[2][j] = __builtin_amdgcn_sbfe(mhi, j, 1); mk[3][j] = __builtin_amdgcn_sbfe(mhi, 16 + j, 1);
;       }
; #pragma unroll
;       for (int hh = 0; hh < 2; ++hh) {
;         float mx = s[hh][0][0];
; #pragma unroll
;         for (int kq = 0; kq < 4; ++kq)
; #pragma unroll
;           for (int j = 0; j < 4; ++j) mx = fmaxf(mx, s[hh][kq][j]);
;         {
;           auto r1 = __builtin_amdgcn_permlane16_swap(__float_as_uint(mx), __float_as_uint(mx), false, false);
;           mx = fmaxf(__uint_as_float(r1[0]), __uint_as_float(r1[1]));
;           auto r2 = __builtin_amdgcn_permlane32_swap(__float_as_uint(mx), __float_as_uint(mx), false, false);
;           mx = fmaxf(__uint_as_float(r2[0]), __uint_as_float(r2[1]));
;         }
;         if (kt == 0 || __ballot(mx > 8.f)) {
;           const float delta = (kt == 0) ? mx : fmaxf(mx, 0.f);
;           const float alpha = fexp2(-delta);
;           mrun[hh] += delta;
;           lsum[hh] *= alpha;
; #pragma unroll
;           for (int dt = 0; dt < 8; ++dt) o[hh][dt] *= alpha;
; #pragma unroll
;           for (int kq = 0; kq < 4; ++kq)
; #pragma unroll
;             for (int j = 0; j < 4; ++j) s[hh][kq][j] -= delta;
.LBB0_1731:
	s_add_i32 s6, s3, 0xffffffa0
	s_cmp_gt_i32 s6, s1
	s_cbranch_scc1 .LBB0_1737
	ds_read_b128 v[116:119], v175
	ds_read_b128 v[120:123], v175 offset:64
	ds_read_b128 v[124:127], v175 offset:128
	ds_read_b128 v[128:131], v175 offset:192
	ds_read_b128 v[132:135], v175 offset:4352
	ds_read_b128 v[140:143], v175 offset:4416
	ds_read_b128 v[144:147], v175 offset:4480
	ds_read_b128 v[178:181], v175 offset:4544
	v_xor_b32_e32 v182, 0x80000000, v3
	v_xor_b32_e32 v186, 0x80000000, v2
	v_mov_b32_e32 v183, v182
	v_mov_b32_e32 v184, v182
	v_mov_b32_e32 v185, v182
	v_mov_b32_e32 v187, v186
	v_mov_b32_e32 v188, v186
	v_mov_b32_e32 v189, v186
	s_waitcnt lgkmcnt(7)
	v_mfma_f32_16x16x32_bf16 v[136:139], v[116:119], v[32:35], v[182:185]
	v_mfma_f32_16x16x32_bf16 v[116:119], v[116:119], v[16:19], v[186:189]
	s_waitcnt lgkmcnt(6)
	v_mfma_f32_16x16x32_bf16 v[136:139], v[120:123], v[4:7], v[136:139]
	v_mfma_f32_16x16x32_bf16 v[116:119], v[120:123], v[20:23], v[116:119]
	s_waitcnt lgkmcnt(5)
	v_mfma_f32_16x16x32_bf16 v[120:123], v[124:127], v[8:11], v[136:139]
	v_mfma_f32_16x16x32_bf16 v[116:119], v[124:127], v[24:27], v[116:119]
	s_waitcnt lgkmcnt(4)
	v_mfma_f32_16x16x32_bf16 v[152:155], v[128:131], v[12:15], v[120:123]
	v_mfma_f32_16x16x32_bf16 v[136:139], v[128:131], v[28:31], v[116:119]
	s_nop 3
	ds_read_b128 v[116:119], v175 offset:8704
	ds_read_b128 v[120:123], v175 offset:8768
	ds_read_b128 v[124:127], v175 offset:8832
	ds_read_b128 v[128:131], v175 offset:8896
	s_waitcnt lgkmcnt(7)
	v_mfma_f32_16x16x32_bf16 v[148:151], v[132:135], v[32:35], v[182:185]
	v_mfma_f32_16x16x32_bf16 v[132:135], v[132:135], v[16:19], v[186:189]
	s_waitcnt lgkmcnt(6)
	v_mfma_f32_16x16x32_bf16 v[148:151], v[140:143], v[4:7], v[148:151]
	v_mfma_f32_16x16x32_bf16 v[132:135], v[140:143], v[20:23], v[132:135]
	s_waitcnt lgkmcnt(5)
	v_mfma_f32_16x16x32_bf16 v[140:143], v[144:147], v[8:11], v[148:151]
	v_mfma_f32_16x16x32_bf16 v[132:135], v[144:147], v[24:27], v[132:135]
	s_waitcnt lgkmcnt(4)
	v_mfma_f32_16x16x32_bf16 v[148:151], v[178:181], v[12:15], v[140:143]
	v_mfma_f32_16x16x32_bf16 v[132:135], v[178:181], v[28:31], v[132:135]
	ds_read_b128 v[144:147], v175 offset:13056
	ds_read_b128 v[178:181], v175 offset:13120
	ds_read_b128 v[190:193], v175 offset:13184
	ds_read_b128 v[194:197], v175 offset:13248
	s_waitcnt lgkmcnt(7)
	v_mfma_f32_16x16x32_bf16 v[140:143], v[116:119], v[32:35], v[182:185]
	v_mfma_f32_16x16x32_bf16 v[116:119], v[116:119], v[16:19], v[186:189]
	s_waitcnt lgkmcnt(6)
	v_mfma_f32_16x16x32_bf16 v[140:143], v[120:123], v[4:7], v[140:143]
	v_mfma_f32_16x16x32_bf16 v[116:119], v[120:123], v[20:23], v[116:119]
	s_waitcnt lgkmcnt(5)
	v_mfma_f32_16x16x32_bf16 v[120:123], v[124:127], v[8:11], v[140:143]
	v_mfma_f32_16x16x32_bf16 v[116:119], v[124:127], v[24:27], v[116:119]
	s_waitcnt lgkmcnt(4)
	v_mfma_f32_16x16x32_bf16 v[140:143], v[128:131], v[12:15], v[120:123]
	v_mfma_f32_16x16x32_bf16 v[124:127], v[128:131], v[28:31], v[116:119]
	s_nop 2
	s_nop 0
	ds_read_b128 v[116:119], v177 offset:17408
	ds_read_b128 v[120:123], v177 offset:17472
	s_waitcnt lgkmcnt(5)
	v_mfma_f32_16x16x32_bf16 v[128:131], v[144:147], v[32:35], v[182:185]
	v_mfma_f32_16x16x32_bf16 v[144:147], v[144:147], v[16:19], v[186:189]
	s_waitcnt lgkmcnt(4)
	v_mfma_f32_16x16x32_bf16 v[128:131], v[178:181], v[4:7], v[128:131]
	v_mfma_f32_16x16x32_bf16 v[144:147], v[178:181], v[20:23], v[144:147]
	s_waitcnt lgkmcnt(3)
	v_mfma_f32_16x16x32_bf16 v[128:131], v[190:193], v[8:11], v[128:131]
	v_mfma_f32_16x16x32_bf16 v[178:181], v[190:193], v[24:27], v[144:147]
	s_waitcnt lgkmcnt(2)
	v_mfma_f32_16x16x32_bf16 v[144:147], v[194:197], v[12:15], v[128:131]
	v_mfma_f32_16x16x32_bf16 v[128:131], v[194:197], v[28:31], v[178:181]
	s_nop 3
	v_max_f32_e32 v178, v153, v153
	v_max_f32_e32 v179, v152, v152
	v_max_f32_e32 v178, v179, v178
	v_max3_f32 v178, v178, v154, v155
	v_max3_f32 v178, v178, v148, v149
	v_max3_f32 v178, v178, v150, v151
	v_max3_f32 v178, v178, v140, v141
	v_max3_f32 v178, v178, v142, v143
	v_max3_f32 v178, v178, v144, v145
	v_max3_f32 v178, v178, v146, v147
	v_mov_b32_e32 v179, v178
	s_nop 1
	v_permlane16_swap_b32_e32 v178, v179
	v_max_f32_e32 v179, v179, v179
	v_max_f32_e32 v178, v178, v178
	v_max_f32_e32 v178, v178, v179
	v_mov_b32_e32 v179, v178
	s_nop 1
	v_permlane32_swap_b32_e32 v178, v179
	v_max_f32_e32 v179, v179, v179
	v_max_f32_e32 v178, v178, v178
	v_max_f32_e32 v178, v178, v179
	v_cmp_lt_f32_e32 vcc, s28, v178
	s_cbranch_vccz .LBB0_1734
	v_max_f32_e32 v178, v178, v178
	v_max_f32_e32 v178, 0, v178
	v_exp_f32_e64 v180, -v178
	v_add_f32_e32 v3, v3, v178
	v_pk_add_f32 v[152:153], v[152:153], v[178:179] op_sel_hi:[1,0] neg_lo:[0,1] neg_hi:[0,1]
	v_pk_add_f32 v[154:155], v[154:155], v[178:179] op_sel_hi:[1,0] neg_lo:[0,1] neg_hi:[0,1]
	v_mul_f32_e32 v160, v160, v180
	v_pk_mul_f32 v[90:91], v[90:91], v[180:181] op_sel_hi:[1,0]
	v_pk_mul_f32 v[88:89], v[88:89], v[180:181] op_sel_hi:[1,0]
	v_pk_mul_f32 v[86:87], v[86:87], v[180:181] op_sel_hi:[1,0]
	v_pk_mul_f32 v[84:85], v[84:85], v[180:181] op_sel_hi:[1,0]
	v_pk_mul_f32 v[94:95], v[94:95], v[180:181] op_sel_hi:[1,0]
	v_pk_mul_f32 v[92:93], v[92:93], v[180:181] op_sel_hi:[1,0]
	v_pk_mul_f32 v[98:99], v[98:99], v[180:181] op_sel_hi:[1,0]
	v_pk_mul_f32 v[96:97], v[96:97], v[180:181] op_sel_hi:[1,0]
	v_pk_mul_f32 v[106:107], v[106:107], v[180:181] op_sel_hi:[1,0]
	v_pk_mul_f32 v[104:105], v[104:105], v[180:181] op_sel_hi:[1,0]
	v_pk_mul_f32 v[110:111], v[110:111], v[180:181] op_sel_hi:[1,0]
	v_pk_mul_f32 v[108:109], v[108:109], v[180:181] op_sel_hi:[1,0]
	v_pk_mul_f32 v[114:115], v[114:115], v[180:181] op_sel_hi:[1,0]
	v_pk_mul_f32 v[112:113], v[112:113], v[180:181] op_sel_hi:[1,0]
	v_pk_mul_f32 v[102:103], v[102:103], v[180:181] op_sel_hi:[1,0]
	v_pk_mul_f32 v[100:101], v[100:101], v[180:181] op_sel_hi:[1,0]
	v_pk_add_f32 v[148:149], v[148:149], v[178:179] op_sel_hi:[1,0] neg_lo:[0,1] neg_hi:[0,1]
	v_pk_add_f32 v[150:151], v[150:151], v[178:179] op_sel_hi:[1,0] neg_lo:[0,1] neg_hi:[0,1]
	v_pk_add_f32 v[140:141], v[140:141], v[178:179] op_sel_hi:[1,0] neg_lo:[0,1] neg_hi:[0,1]
	v_pk_add_f32 v[142:143], v[142:143], v[178:179] op_sel_hi:[1,0] neg_lo:[0,1] neg_hi:[0,1]
	v_pk_add_f32 v[144:145], v[144:145], v[178:179] op_sel_hi:[1,0] neg_lo:[0,1] neg_hi:[0,1]
	v_pk_add_f32 v[146:147], v[146:147], v[178:179] op_sel_hi:[1,0] neg_lo:[0,1] neg_hi:[0,1]
